# GEMM K-loops: first iteration after an epilogue skips the vmcnt part of the phase-1/2 waits (tiles already drained by the epilogue; the wait only forced store acknowledgements)
# speedup vs baseline: 1.0017x; 1.0017x over previous
;     __host__ __device__ void init(int N_, int G_, int c_) { nN = N_ / BM; mn.init(NPROMPT, N_, G_, c_); G = G_; c = c_; }
;     __host__ __device__ bool next(int i, Unit& u) const { const int q = i / 3; if (!b.next(q, u)) return false; u.seg = i - 3 * q; return true; }
;     __host__ __device__ bool next(int i, Unit& u) const { const long L = (long)i * G + c; if (L >= nN) return false; u.pm = NPROMPT / BM; u.pn = (int)L; u.half = -1; u.seg = 0; return true; }
;     __host__ __device__ bool next(int i, Unit& u) const {
;         const long L = (long)i * G + c;
;         if (L < mn.nwg) return mn.next(i, u);
;         const int j = (int)(L - mn.nwg); if (j >= 2 * nN) return false;
;         u.pm = NPROMPT / BM; u.pn = j % nN; u.half = j / nN; u.seg = 0; return true;
; __global__ void __launch_bounds__(NWAVES * 64, 2) fwd(Args args_unused) {
;     ...
;         if (IN(pb + 0)) {
;             PH_PTRS PH_LAYER
;             pg8::Gemm g{XB, (const bf16*)(wl + WL_F1I), M, 2 * DFF, DM, DM, DM, 0}; pg8::HalfOrder S; S.init(2 * DFF, G, bx);
;             pg8::EpiSwiGLU E{Gb, SSQ, (const float*)(ws + WS_SHW1) + (size_t)l * NSEQ * 2 * DFF};
;             pg8::gemm_phase<pg8::EpiSwiGLU, pg8::HalfOrder>(lds, g, S, E);
.LBB0_413:
	s_mov_b32 s98, 0
	s_cmp_lt_i32 s84, 4
	s_cselect_b64 s[0:1], -1, 0
	s_cmp_gt_i32 s85, 3
	s_cselect_b64 s[4:5], -1, 0
	s_and_b64 s[0:1], s[0:1], s[4:5]
	s_mov_b32 s20, 0
	s_andn2_b64 vcc, exec, s[0:1]
	v_cmp_eq_u32_e64 s[94:95], 0, v0
	s_cbranch_vccnz .LBB0_527
	s_mov_b64 s[0:1], s[82:83]
	s_mov_b32 s3, s2
	s_load_dword s33, s[82:83], 0x168
	v_readlane_b32 s4, v254, 3
	v_mov_b32_e32 v1, v0
	v_mov_b32_e32 v10, v0
	s_waitcnt lgkmcnt(0)
	s_movk_i32 s14, 0x400
	v_readfirstlane_b32 s16, v10
	s_cmpk_gt_i32 s3, 0xaff
	s_cbranch_scc0 .LBB0_420
	s_add_i32 s8, s3, 0xfffff500
	s_mov_b64 s[6:7], 0
	s_cmp_gt_u32 s8, 43
	s_mov_b64 s[4:5], 0
	s_cbranch_scc1 .LBB0_417
	s_add_i32 s4, s3, 0xfffff4ea
	s_cmp_lt_u32 s8, 22
	s_cselect_b32 s28, s8, s4
	s_cmp_gt_u32 s8, 21
	s_cselect_b64 s[4:5], -1, 0
	v_cndmask_b32_e64 v1, 0, 1, s[4:5]
	s_movk_i32 s30, 0x80
	s_mov_b64 s[4:5], -1
	v_readfirstlane_b32 s74, v1

; #define LAS __attribute__((address_space(3)))
; #define PSCALE(k, v) ((kargs()->li == 1 && (k) == lo) ? 0.f : (v))
; template <int K> __device__ __forceinline__ void sample_resid_units(LAS unsigned char* lds, const bf16* Aop, int lda, const bf16* Bt, int ldb, bf16* X, const float* gate, float scale,
;                                                    bf16* XB, float* SSQ, const float* gam, int tid, int vcu, int G) {
;     LAS float* P = (LAS float*)lds;
;     LAS float* R = P + 8 * 1024;
;     const int lane = tid & 63, w = __builtin_amdgcn_readfirstlane(tid >> 6), qq = lane & 15, q4 = lane >> 4;
;     for (int un = vcu; un < 256; un += G) {
;         const int rt = un >> 4, cs = un & 15, pn = cs >> 2, wc = cs & 3; const size_t row0 = (size_t)NPROMPT + 16 * rt;
;         constexpr int kper = K >> 3; const int kbeg = w * kper;
;         f32x4 acc[4];
; #pragma unroll
;         for (int ct = 0; ct < 4; ++ct) acc[ct] = (f32x4){0.f, 0.f, 0.f, 0.f};
;         const bf16* ap = Aop + (row0 + qq) * (size_t)lda + kbeg + 8 * q4;
;         const bf16* bp = Bt + (size_t)(256 * pn + 32 * wc + qq) * ldb + kbeg + 8 * q4;
; __global__ void __launch_bounds__(NWAVES * 64, 2) fwd(Args args_unused) {
;     ...
;         if (IN(pb + 1)) {
;             PH_PTRS PH_LAYER
;             sample_resid_units<DFF>(lds, Gb, DFF, (const bf16*)(wl + WL_F1O), DFF, X, modl + 2 * DM, PSCALE(pb + 1, 0.5f), XB, SSQ, GAM + (size_t)(l * 3 + 1) * NSEQ * DM, tid, vcu, G);
.LBB0_527:
	s_mov_b32 s98, 0
	s_cmp_lt_i32 s84, 5
	s_cselect_b64 s[0:1], -1, 0
	s_cmp_gt_i32 s85, 4
	s_cselect_b64 s[4:5], -1, 0
	s_and_b64 s[0:1], s[0:1], s[4:5]
	s_andn2_b64 vcc, exec, s[0:1]
	s_cbranch_vccnz .LBB0_637
	s_mov_b64 s[0:1], s[82:83]
	s_load_dwordx2 s[4:5], s[0:1], 0x148
	s_mov_b32 s26, 0
	s_load_dword s3, s[82:83], 0x168
	v_readlane_b32 s20, v254, 3
	s_waitcnt lgkmcnt(0)
	s_add_u32 s0, s4, 0xcf00000
	s_addc_u32 s1, s5, 0
	s_add_u32 s10, s4, 0x15000000
	s_addc_u32 s11, s5, 0
	s_add_u32 s12, s4, 0xcc00000
	s_addc_u32 s13, s5, 0
	s_add_u32 s38, s4, 0x1d200000
	s_addc_u32 s39, s5, 0
	s_add_u32 s40, s4, 0xc00000
	s_addc_u32 s41, s5, 0
	s_add_u32 s14, s4, 0xb102000
	s_addc_u32 s15, s5, 0
	s_add_u32 s16, s4, 0xbc30000
	s_mov_b32 s33, s2
	v_mov_b32_e32 v2, v0
	s_addc_u32 s17, s5, 0
	s_mov_b32 s9, 0
	s_cmpk_gt_i32 s20, 0xff
	v_readfirstlane_b32 s4, v2
	s_cbranch_scc1 .LBB0_535
	s_ashr_i32 s8, s4, 6
	s_lshl_b32 s4, s8, 2
	s_add_i32 s18, s26, s4
	s_mul_i32 s4, s8, 0x160
	s_ashr_i32 s5, s4, 31
	s_lshl_b64 s[4:5], s[4:5], 1
	s_add_u32 s6, s38, s4
	s_addc_u32 s7, s39, s5
	s_add_u32 s4, s40, s4
	v_and_b32_e32 v3, 63, v2
	v_mov_b32_e32 v7, 0
	v_and_b32_e32 v6, 48, v2
	s_addc_u32 s5, s41, s5
	v_ashrrev_i32_e32 v12, 7, v2
	v_lshlrev_b32_e32 v5, 1, v2
	v_lshl_add_u64 v[8:9], s[6:7], 0, v[6:7]
	v_lshl_add_u64 v[10:11], s[4:5], 0, v[6:7]
	s_lshl_b32 s6, s8, 12
	v_lshl_add_u32 v6, v3, 2, s26
	v_lshrrev_b32_e32 v1, 3, v2
	v_and_b32_e32 v14, 0xc0, v5
	v_ashrrev_i32_e32 v5, 1, v2
	v_lshlrev_b32_e32 v15, 4, v12
	v_and_b32_e32 v4, 15, v2
	v_and_b32_e32 v5, 0xffffff80, v5
	v_and_b32_e32 v15, 16, v15
	v_and_b32_e32 v1, 14, v1
	v_add_u32_e32 v17, s6, v6
	v_mbcnt_lo_u32_b32 v6, -1, 0
	v_lshl_add_u32 v13, v4, 2, s26
	v_or3_b32 v1, v5, v15, v1
	v_lshlrev_b32_e32 v5, 5, v2
	v_lshlrev_b32_e32 v12, 10, v12
	v_mbcnt_hi_u32_b32 v19, -1, v6
	v_lshlrev_b32_e32 v15, 5, v4
	v_and_b32_e32 v18, 0x200, v5
	v_add3_u32 v12, v13, v14, v12
	v_and_b32_e32 v6, 64, v19
	v_cmp_gt_u32_e32 vcc, 16, v3
	v_cmp_gt_i32_e64 s[4:5], 16, v2
	v_ashrrev_i32_e32 v3, 31, v2
	s_lshl_b32 s21, s20, 5
	s_lshl_b32 s22, s3, 5
	s_movk_i32 s23, 0x1600
	v_mov_b32_e32 v16, 0x1600
	s_mov_b32 s24, 0x16000
	s_mov_b32 s25, 0xb0000
	s_mov_b32 s27, 0xc6000
	v_add_u32_e32 v18, v12, v18
	s_mov_b32 s28, 0x9000
	v_mov_b64_e32 v[12:13], s[14:15]
	v_xor_b32_e32 v20, 16, v19
	v_add_u32_e32 v21, 64, v6
	v_xor_b32_e32 v22, 32, v19
	v_add_u32_e32 v23, s18, v15
	s_branch .LBB0_531

; #define PG8_STAGE(bufoff, gbase, voff) do { _Pragma("unroll") for (int _i = 0; _i < 2; ++_i) \
;         __builtin_amdgcn_global_load_lds((const unsigned*)((const char*)(gbase) + (voff)[_i]), (PG8_LAS unsigned*)(lds + (bufoff) + ldsw + _i * 8192), 16, 0, 0); } while (0)
; #define PG8_LDA(dst, b, h) do { _Pragma("unroll") for (int m = 0; m < 4; ++m) _Pragma("unroll") for (int k = 0; k < 2; ++k) dst[m][k] = *(const PG8_LAS bf16x8*)(lds + PG8_SA(b, h) + aoff + m * 2048 + k * 1024); } while (0)
; #define PG8_LDB(dst, b, h) do { _Pragma("unroll") for (int n = 0; n < 2; ++n) _Pragma("unroll") for (int k = 0; k < 2; ++k) dst[n][k] = *(const PG8_LAS bf16x8*)(lds + PG8_SB(b, h) + boff + n * 2048 + k * 1024); } while (0)
; #define PG8_MMA(ai, bj, At, Bt) do { __builtin_amdgcn_s_setprio(1); _Pragma("unroll") for (int m = 0; m < 4; ++m) _Pragma("unroll") for (int n = 0; n < 2; ++n) _Pragma("unroll") for (int k = 0; k < 2; ++k) \
;         acc[ai][bj][m][n] = __builtin_amdgcn_mfma_f32_16x16x32_bf16(Bt[n][k], At[m][k], acc[ai][bj][m][n], 0, 0, 0); __builtin_amdgcn_s_setprio(0); } while (0)
; #define PG8_WAIT_V(n) asm volatile("s_waitcnt vmcnt(" #n ")" ::: "memory")
; #define PG8_WAIT_L(n) do { asm volatile("s_waitcnt lgkmcnt(" #n ")" ::: "memory"); __builtin_amdgcn_s_waitcnt(0xC07F); } while (0)
; #define PG8_BAR __builtin_amdgcn_s_barrier()
; #define PG8_SCHED __builtin_amdgcn_sched_barrier(0)
; template <class Epi, class Sched, bool SEG3 = false>
; __device__ __forceinline__ void gemm_phase(PG8_LAS unsigned char* lds, const Gemm g, const Sched& S, const Epi& E) {
;     ...
;             PG8_LDB(B0, 0, 0); PG8_LDB(B1, 0, 1); PG8_SCHED; PG8_LDA(At, 0, 0); PG8_STAGE(PG8_SA(1, 1), a1 + hsA, voffA);
;             PG8_WAIT_V(8); PG8_WAIT_L(0); PG8_BAR; if (cur.half != 1) { PG8_MMA(0, 0, At, B0); PG8_MMA(0, 1, At, B1); } PG8_BAR; PG8_SCHED;
;             PG8_LDA(At, 0, 1); PG8_STAGE(PG8_SB(0, 0), b2, voffB); PG8_STAGE(PG8_SB(0, 1), b2 + hsB, voffB); PG8_STAGE(PG8_SA(0, 0), a2, voffA);
;             PG8_WAIT_V(8); PG8_WAIT_L(0); PG8_BAR; if (cur.half != 0) { PG8_MMA(1, 0, At, B0); PG8_MMA(1, 1, At, B1); } PG8_BAR; PG8_SCHED;
.LBB0_554:
	ds_read_b128 v[98:101], v199
	ds_read_b128 v[110:113], v199 offset:1024
	ds_read_b128 v[122:125], v199 offset:2048
	ds_read_b128 v[134:137], v199 offset:3072
	ds_read_b128 v[146:149], v200
	ds_read_b128 v[150:153], v200 offset:1024
	ds_read_b128 v[170:173], v200 offset:2048
	ds_read_b128 v[174:177], v200 offset:3072
	s_add_i32 s68, s34, 2
	s_add_u32 s30, s28, 0x100
	s_addc_u32 s31, s29, 0
	s_cmp_eq_u32 s58, s34
	s_cselect_b32 s34, s26, s66
	s_cselect_b32 s37, s9, s31
	s_cselect_b32 s36, s8, s30
	s_cselect_b32 s35, s27, s67
	v_lshl_add_u64 v[218:219], s[28:29], 0, v[162:163]
	s_add_i32 m0, s46, 0xc000
	ds_read_b128 v[178:181], v201
	ds_read_b128 v[182:185], v201 offset:1024
	ds_read_b128 v[186:189], v201 offset:2048
	ds_read_b128 v[190:193], v201 offset:3072
	ds_read_b128 v[194:197], v201 offset:4096
	ds_read_b128 v[206:209], v201 offset:5120
	ds_read_b128 v[210:213], v201 offset:6144
	ds_read_b128 v[214:217], v201 offset:7168
	global_load_lds_dwordx4 v[218:219], off
	v_lshl_add_u64 v[218:219], s[28:29], 0, v[164:165]
	s_add_i32 m0, s46, 0xe000
	s_nop 0
	global_load_lds_dwordx4 v[218:219], off
	s_cmp_lg_u32 s98, 0
	s_cbranch_scc1 .Lfi_a_0
	s_waitcnt vmcnt(8)
.Lfi_a_0:
	s_waitcnt lgkmcnt(0)
	s_barrier
	s_setprio 1
	v_mfma_f32_16x16x32_bf16 v[142:145], v[98:101], v[178:181], v[142:145]
	v_mfma_f32_16x16x32_bf16 v[138:141], v[122:125], v[178:181], v[138:141]
	v_mfma_f32_16x16x32_bf16 v[118:121], v[98:101], v[186:189], v[118:121]
	v_mfma_f32_16x16x32_bf16 v[114:117], v[122:125], v[186:189], v[114:117]
	v_mfma_f32_16x16x32_bf16 v[94:97], v[98:101], v[194:197], v[94:97]
	v_mfma_f32_16x16x32_bf16 v[90:93], v[122:125], v[194:197], v[90:93]
	v_mfma_f32_16x16x32_bf16 v[78:81], v[98:101], v[210:213], v[78:81]
	v_mfma_f32_16x16x32_bf16 v[74:77], v[122:125], v[210:213], v[74:77]
	v_mfma_f32_16x16x32_bf16 v[142:145], v[110:113], v[182:185], v[142:145]
	v_mfma_f32_16x16x32_bf16 v[138:141], v[134:137], v[182:185], v[138:141]
	v_mfma_f32_16x16x32_bf16 v[118:121], v[110:113], v[190:193], v[118:121]
	v_mfma_f32_16x16x32_bf16 v[114:117], v[134:137], v[190:193], v[114:117]
	v_mfma_f32_16x16x32_bf16 v[94:97], v[110:113], v[206:209], v[94:97]
	v_mfma_f32_16x16x32_bf16 v[90:93], v[134:137], v[206:209], v[90:93]
	v_mfma_f32_16x16x32_bf16 v[78:81], v[110:113], v[214:217], v[78:81]
	v_mfma_f32_16x16x32_bf16 v[74:77], v[134:137], v[214:217], v[74:77]
	s_setprio 0
	s_setprio 1
	v_mfma_f32_16x16x32_bf16 v[130:133], v[146:149], v[178:181], v[130:133]
	v_mfma_f32_16x16x32_bf16 v[126:129], v[170:173], v[178:181], v[126:129]
	v_mfma_f32_16x16x32_bf16 v[106:109], v[146:149], v[186:189], v[106:109]
	v_mfma_f32_16x16x32_bf16 v[102:105], v[170:173], v[186:189], v[102:105]
	v_mfma_f32_16x16x32_bf16 v[86:89], v[146:149], v[194:197], v[86:89]
	v_mfma_f32_16x16x32_bf16 v[82:85], v[170:173], v[194:197], v[82:85]
	v_mfma_f32_16x16x32_bf16 v[70:73], v[146:149], v[210:213], v[70:73]
	v_mfma_f32_16x16x32_bf16 v[66:69], v[170:173], v[210:213], v[66:69]
	v_mfma_f32_16x16x32_bf16 v[130:133], v[150:153], v[182:185], v[130:133]
	v_mfma_f32_16x16x32_bf16 v[126:129], v[174:177], v[182:185], v[126:129]
	v_mfma_f32_16x16x32_bf16 v[106:109], v[150:153], v[190:193], v[106:109]
	v_mfma_f32_16x16x32_bf16 v[102:105], v[174:177], v[190:193], v[102:105]
	v_mfma_f32_16x16x32_bf16 v[86:89], v[150:153], v[206:209], v[86:89]
	v_mfma_f32_16x16x32_bf16 v[82:85], v[174:177], v[206:209], v[82:85]
	v_mfma_f32_16x16x32_bf16 v[70:73], v[150:153], v[214:217], v[70:73]
	v_mfma_f32_16x16x32_bf16 v[66:69], v[174:177], v[214:217], v[66:69]
	s_setprio 0
	s_barrier
	s_mov_b32 m0, s42
	v_lshl_add_u64 v[218:219], s[34:35], 0, v[156:157]
	s_add_u32 s28, s34, 0xb0000
	ds_read_b128 v[178:181], v201 offset:16384
	ds_read_b128 v[182:185], v201 offset:17408
	ds_read_b128 v[186:189], v201 offset:18432
	ds_read_b128 v[190:193], v201 offset:19456
	ds_read_b128 v[194:197], v201 offset:20480
	ds_read_b128 v[206:209], v201 offset:21504
	ds_read_b128 v[210:213], v201 offset:22528
	ds_read_b128 v[214:217], v201 offset:23552
	global_load_lds_dwordx4 v[218:219], off
	v_lshl_add_u64 v[220:221], s[34:35], 0, v[160:161]
	s_mov_b32 m0, s43
	s_addc_u32 s29, s35, 0
	global_load_lds_dwordx4 v[220:221], off
	v_lshl_add_u64 v[222:223], s[28:29], 0, v[156:157]
	s_mov_b32 m0, s44
	v_lshl_add_u64 v[224:225], s[36:37], 0, v[158:159]
	global_load_lds_dwordx4 v[222:223], off
	v_lshl_add_u64 v[222:223], s[28:29], 0, v[160:161]
	s_mov_b32 m0, s45
	s_nop 0
	global_load_lds_dwordx4 v[222:223], off
	v_lshl_add_u64 v[222:223], s[36:37], 0, v[154:155]
	s_mov_b32 m0, s46
	s_nop 0
	global_load_lds_dwordx4 v[222:223], off
	s_mov_b32 m0, s47
	s_nop 0
	global_load_lds_dwordx4 v[224:225], off
	s_cmp_lg_u32 s98, 0
	s_cbranch_scc1 .Lfi_b_0
	s_waitcnt vmcnt(8)
; #define PG8_STAGE(bufoff, gbase, voff) do { _Pragma("unroll") for (int _i = 0; _i < 2; ++_i) \
;         __builtin_amdgcn_global_load_lds((const unsigned*)((const char*)(gbase) + (voff)[_i]), (PG8_LAS unsigned*)(lds + (bufoff) + ldsw + _i * 8192), 16, 0, 0); } while (0)
; #define PG8_LDA(dst, b, h) do { _Pragma("unroll") for (int m = 0; m < 4; ++m) _Pragma("unroll") for (int k = 0; k < 2; ++k) dst[m][k] = *(const PG8_LAS bf16x8*)(lds + PG8_SA(b, h) + aoff + m * 2048 + k * 1024); } while (0)
; #define PG8_LDB(dst, b, h) do { _Pragma("unroll") for (int n = 0; n < 2; ++n) _Pragma("unroll") for (int k = 0; k < 2; ++k) dst[n][k] = *(const PG8_LAS bf16x8*)(lds + PG8_SB(b, h) + boff + n * 2048 + k * 1024); } while (0)
; #define PG8_MMA(ai, bj, At, Bt) do { __builtin_amdgcn_s_setprio(1); _Pragma("unroll") for (int m = 0; m < 4; ++m) _Pragma("unroll") for (int n = 0; n < 2; ++n) _Pragma("unroll") for (int k = 0; k < 2; ++k) \
;         acc[ai][bj][m][n] = __builtin_amdgcn_mfma_f32_16x16x32_bf16(Bt[n][k], At[m][k], acc[ai][bj][m][n], 0, 0, 0); __builtin_amdgcn_s_setprio(0); } while (0)
; #define PG8_WAIT_V(n) asm volatile("s_waitcnt vmcnt(" #n ")" ::: "memory")
; #define PG8_WAIT_L(n) do { asm volatile("s_waitcnt lgkmcnt(" #n ")" ::: "memory"); __builtin_amdgcn_s_waitcnt(0xC07F); } while (0)
; #define PG8_BAR __builtin_amdgcn_s_barrier()
; #define PG8_SCHED __builtin_amdgcn_sched_barrier(0)
; template <class Epi, class Sched, bool SEG3 = false>
; __device__ __forceinline__ void gemm_phase(PG8_LAS unsigned char* lds, const Gemm g, const Sched& S, const Epi& E) {
;     ...
;             PG8_WAIT_V(8); PG8_WAIT_L(0); PG8_BAR; if (cur.half != 0) { PG8_MMA(1, 0, At, B0); PG8_MMA(1, 1, At, B1); } PG8_BAR; PG8_SCHED;
;             PG8_LDB(B0, 1, 0); PG8_LDB(B1, 1, 1); PG8_SCHED; PG8_LDA(At, 1, 0); PG8_STAGE(PG8_SA(0, 1), a2 + hsA, voffA);
;             PG8_WAIT_V(8); PG8_WAIT_L(0); PG8_BAR; if (cur.half != 1) { PG8_MMA(0, 0, At, B0); PG8_MMA(0, 1, At, B1); } PG8_BAR; PG8_SCHED;
.Lfi_b_0:
	s_mov_b32 s98, 0
	s_waitcnt lgkmcnt(0)
	s_barrier
	s_setprio 1
	v_mfma_f32_16x16x32_bf16 v[62:65], v[98:101], v[178:181], v[62:65]
	v_mfma_f32_16x16x32_bf16 v[58:61], v[122:125], v[178:181], v[58:61]
	v_mfma_f32_16x16x32_bf16 v[46:49], v[98:101], v[186:189], v[46:49]
	v_mfma_f32_16x16x32_bf16 v[42:45], v[122:125], v[186:189], v[42:45]
	v_mfma_f32_16x16x32_bf16 v[30:33], v[98:101], v[194:197], v[30:33]
	v_mfma_f32_16x16x32_bf16 v[26:29], v[122:125], v[194:197], v[26:29]
	v_mfma_f32_16x16x32_bf16 v[14:17], v[98:101], v[210:213], v[14:17]
	v_mfma_f32_16x16x32_bf16 v[10:13], v[122:125], v[210:213], v[10:13]
	v_mfma_f32_16x16x32_bf16 v[62:65], v[110:113], v[182:185], v[62:65]
	v_mfma_f32_16x16x32_bf16 v[58:61], v[134:137], v[182:185], v[58:61]
	v_mfma_f32_16x16x32_bf16 v[46:49], v[110:113], v[190:193], v[46:49]
	v_mfma_f32_16x16x32_bf16 v[42:45], v[134:137], v[190:193], v[42:45]
	v_mfma_f32_16x16x32_bf16 v[30:33], v[110:113], v[206:209], v[30:33]
	v_mfma_f32_16x16x32_bf16 v[26:29], v[134:137], v[206:209], v[26:29]
	v_mfma_f32_16x16x32_bf16 v[14:17], v[110:113], v[214:217], v[14:17]
	v_mfma_f32_16x16x32_bf16 v[10:13], v[134:137], v[214:217], v[10:13]
	s_setprio 0
	s_setprio 1
	v_mfma_f32_16x16x32_bf16 v[54:57], v[146:149], v[178:181], v[54:57]
	v_mfma_f32_16x16x32_bf16 v[50:53], v[170:173], v[178:181], v[50:53]
	v_mfma_f32_16x16x32_bf16 v[38:41], v[146:149], v[186:189], v[38:41]
	v_mfma_f32_16x16x32_bf16 v[34:37], v[170:173], v[186:189], v[34:37]
	v_mfma_f32_16x16x32_bf16 v[22:25], v[146:149], v[194:197], v[22:25]
	v_mfma_f32_16x16x32_bf16 v[18:21], v[170:173], v[194:197], v[18:21]
	v_mfma_f32_16x16x32_bf16 v[6:9], v[146:149], v[210:213], v[6:9]
	v_mfma_f32_16x16x32_bf16 v[2:5], v[170:173], v[210:213], v[2:5]
	v_mfma_f32_16x16x32_bf16 v[54:57], v[150:153], v[182:185], v[54:57]
	v_mfma_f32_16x16x32_bf16 v[50:53], v[174:177], v[182:185], v[50:53]
	v_mfma_f32_16x16x32_bf16 v[38:41], v[150:153], v[190:193], v[38:41]
	v_mfma_f32_16x16x32_bf16 v[34:37], v[174:177], v[190:193], v[34:37]
	v_mfma_f32_16x16x32_bf16 v[22:25], v[150:153], v[206:209], v[22:25]
	v_mfma_f32_16x16x32_bf16 v[18:21], v[174:177], v[206:209], v[18:21]
	v_mfma_f32_16x16x32_bf16 v[6:9], v[150:153], v[214:217], v[6:9]
	v_mfma_f32_16x16x32_bf16 v[2:5], v[174:177], v[214:217], v[2:5]
	s_setprio 0
	s_barrier
	ds_read_b128 v[98:101], v202
	ds_read_b128 v[110:113], v202 offset:1024
	ds_read_b128 v[122:125], v202 offset:2048
	ds_read_b128 v[134:137], v202 offset:3072
	ds_read_b128 v[146:149], v203
	ds_read_b128 v[150:153], v203 offset:1024
	ds_read_b128 v[170:173], v203 offset:2048
	ds_read_b128 v[174:177], v203 offset:3072
	s_add_u32 s28, s36, 0xb0000
	s_addc_u32 s29, s37, 0
	s_mov_b32 m0, s48
	v_lshl_add_u64 v[226:227], s[28:29], 0, v[154:155]
	ds_read_b128 v[178:181], v201 offset:32768
	ds_read_b128 v[182:185], v201 offset:33792
	ds_read_b128 v[186:189], v201 offset:34816
	ds_read_b128 v[190:193], v201 offset:35840
	ds_read_b128 v[194:197], v201 offset:36864
	ds_read_b128 v[206:209], v201 offset:37888
	ds_read_b128 v[210:213], v201 offset:38912
	ds_read_b128 v[214:217], v201 offset:39936
	global_load_lds_dwordx4 v[226:227], off
	v_lshl_add_u64 v[226:227], s[28:29], 0, v[158:159]
	s_mov_b32 m0, s49
	s_nop 0
	global_load_lds_dwordx4 v[226:227], off
	s_waitcnt vmcnt(8)
	s_waitcnt lgkmcnt(0)
	s_waitcnt lgkmcnt(0)
	s_barrier
	s_setprio 1
	v_mfma_f32_16x16x32_bf16 v[142:145], v[98:101], v[178:181], v[142:145]
	v_mfma_f32_16x16x32_bf16 v[138:141], v[122:125], v[178:181], v[138:141]
	v_mfma_f32_16x16x32_bf16 v[118:121], v[98:101], v[186:189], v[118:121]
	v_mfma_f32_16x16x32_bf16 v[114:117], v[122:125], v[186:189], v[114:117]
	v_mfma_f32_16x16x32_bf16 v[94:97], v[98:101], v[194:197], v[94:97]
	v_mfma_f32_16x16x32_bf16 v[90:93], v[122:125], v[194:197], v[90:93]
	v_mfma_f32_16x16x32_bf16 v[78:81], v[98:101], v[210:213], v[78:81]
	v_mfma_f32_16x16x32_bf16 v[74:77], v[122:125], v[210:213], v[74:77]
	v_mfma_f32_16x16x32_bf16 v[142:145], v[110:113], v[182:185], v[142:145]
	v_mfma_f32_16x16x32_bf16 v[138:141], v[134:137], v[182:185], v[138:141]
	v_mfma_f32_16x16x32_bf16 v[118:121], v[110:113], v[190:193], v[118:121]
	v_mfma_f32_16x16x32_bf16 v[114:117], v[134:137], v[190:193], v[114:117]
	v_mfma_f32_16x16x32_bf16 v[94:97], v[110:113], v[206:209], v[94:97]
	v_mfma_f32_16x16x32_bf16 v[90:93], v[134:137], v[206:209], v[90:93]
	v_mfma_f32_16x16x32_bf16 v[78:81], v[110:113], v[214:217], v[78:81]
	v_mfma_f32_16x16x32_bf16 v[74:77], v[134:137], v[214:217], v[74:77]
	s_setprio 0
	s_setprio 1
	v_mfma_f32_16x16x32_bf16 v[130:133], v[146:149], v[178:181], v[130:133]
	v_mfma_f32_16x16x32_bf16 v[126:129], v[170:173], v[178:181], v[126:129]
	v_mfma_f32_16x16x32_bf16 v[106:109], v[146:149], v[186:189], v[106:109]
	v_mfma_f32_16x16x32_bf16 v[102:105], v[170:173], v[186:189], v[102:105]
	v_mfma_f32_16x16x32_bf16 v[86:89], v[146:149], v[194:197], v[86:89]
	v_mfma_f32_16x16x32_bf16 v[82:85], v[170:173], v[194:197], v[82:85]
	v_mfma_f32_16x16x32_bf16 v[70:73], v[146:149], v[210:213], v[70:73]
	v_mfma_f32_16x16x32_bf16 v[66:69], v[170:173], v[210:213], v[66:69]
	v_mfma_f32_16x16x32_bf16 v[130:133], v[150:153], v[182:185], v[130:133]
	v_mfma_f32_16x16x32_bf16 v[126:129], v[174:177], v[182:185], v[126:129]
	v_mfma_f32_16x16x32_bf16 v[106:109], v[150:153], v[190:193], v[106:109]
	v_mfma_f32_16x16x32_bf16 v[102:105], v[174:177], v[190:193], v[102:105]
	v_mfma_f32_16x16x32_bf16 v[86:89], v[150:153], v[206:209], v[86:89]
	v_mfma_f32_16x16x32_bf16 v[82:85], v[174:177], v[206:209], v[82:85]
	v_mfma_f32_16x16x32_bf16 v[70:73], v[150:153], v[214:217], v[70:73]
	v_mfma_f32_16x16x32_bf16 v[66:69], v[174:177], v[214:217], v[66:69]
	s_setprio 0
	s_barrier
; #define PG8_STAGE(bufoff, gbase, voff) do { _Pragma("unroll") for (int _i = 0; _i < 2; ++_i) \
;         __builtin_amdgcn_global_load_lds((const unsigned*)((const char*)(gbase) + (voff)[_i]), (PG8_LAS unsigned*)(lds + (bufoff) + ldsw + _i * 8192), 16, 0, 0); } while (0)
; #define PG8_LDA(dst, b, h) do { _Pragma("unroll") for (int m = 0; m < 4; ++m) _Pragma("unroll") for (int k = 0; k < 2; ++k) dst[m][k] = *(const PG8_LAS bf16x8*)(lds + PG8_SA(b, h) + aoff + m * 2048 + k * 1024); } while (0)
; #define PG8_MMA(ai, bj, At, Bt) do { __builtin_amdgcn_s_setprio(1); _Pragma("unroll") for (int m = 0; m < 4; ++m) _Pragma("unroll") for (int n = 0; n < 2; ++n) _Pragma("unroll") for (int k = 0; k < 2; ++k) \
;         acc[ai][bj][m][n] = __builtin_amdgcn_mfma_f32_16x16x32_bf16(Bt[n][k], At[m][k], acc[ai][bj][m][n], 0, 0, 0); __builtin_amdgcn_s_setprio(0); } while (0)
; #define PG8_WAIT_V(n) asm volatile("s_waitcnt vmcnt(" #n ")" ::: "memory")
; #define PG8_WAIT_L(n) do { asm volatile("s_waitcnt lgkmcnt(" #n ")" ::: "memory"); __builtin_amdgcn_s_waitcnt(0xC07F); } while (0)
; #define PG8_BAR __builtin_amdgcn_s_barrier()
; #define PG8_SCHED __builtin_amdgcn_sched_barrier(0)
; template <class Epi, class Sched, bool SEG3 = false>
; __device__ __forceinline__ void gemm_phase(PG8_LAS unsigned char* lds, const Gemm g, const Sched& S, const Epi& E) {
;     ...
;             PG8_LDA(At, 1, 1); PG8_STAGE(PG8_SB(1, 0), b3, voffB); PG8_STAGE(PG8_SB(1, 1), b3 + hsB, voffB); PG8_STAGE(PG8_SA(1, 0), a3, voffA);
;             PG8_WAIT_V(8); PG8_WAIT_L(0); PG8_BAR; if (cur.half != 0) { PG8_MMA(1, 0, At, B0); PG8_MMA(1, 1, At, B1); } PG8_BAR; PG8_SCHED;
;         }
	s_mov_b32 m0, s52
	v_lshl_add_u64 v[218:219], v[218:219], 0, s[20:21]
	s_add_u32 s28, s34, 0xb0080
	ds_read_b128 v[178:181], v201 offset:49152
	ds_read_b128 v[182:185], v201 offset:50176
	ds_read_b128 v[186:189], v201 offset:51200
	ds_read_b128 v[190:193], v201 offset:52224
	ds_read_b128 v[194:197], v201 offset:53248
	ds_read_b128 v[206:209], v201 offset:54272
	ds_read_b128 v[210:213], v201 offset:55296
	ds_read_b128 v[214:217], v201 offset:56320
	global_load_lds_dwordx4 v[218:219], off
	v_lshl_add_u64 v[218:219], v[220:221], 0, s[20:21]
	s_mov_b32 m0, s53
	s_addc_u32 s29, s35, 0
	global_load_lds_dwordx4 v[218:219], off
	v_lshl_add_u64 v[218:219], s[28:29], 0, v[156:157]
	s_mov_b32 m0, s56
	s_nop 0
	global_load_lds_dwordx4 v[218:219], off
	v_lshl_add_u64 v[218:219], s[28:29], 0, v[160:161]
	s_mov_b32 m0, s57
	s_nop 0
	global_load_lds_dwordx4 v[218:219], off
	v_lshl_add_u64 v[218:219], v[222:223], 0, s[20:21]
	s_mov_b32 m0, s54
	s_nop 0
	global_load_lds_dwordx4 v[218:219], off
	v_lshl_add_u64 v[218:219], v[224:225], 0, s[20:21]
	s_mov_b32 m0, s55
	s_nop 0
	global_load_lds_dwordx4 v[218:219], off
	s_waitcnt vmcnt(8)
	s_waitcnt lgkmcnt(0)
	s_waitcnt lgkmcnt(0)
	s_barrier
	s_setprio 1
	v_mfma_f32_16x16x32_bf16 v[62:65], v[98:101], v[178:181], v[62:65]
	v_mfma_f32_16x16x32_bf16 v[58:61], v[122:125], v[178:181], v[58:61]
	v_mfma_f32_16x16x32_bf16 v[46:49], v[98:101], v[186:189], v[46:49]
	v_mfma_f32_16x16x32_bf16 v[42:45], v[122:125], v[186:189], v[42:45]
	v_mfma_f32_16x16x32_bf16 v[30:33], v[98:101], v[194:197], v[30:33]
	v_mfma_f32_16x16x32_bf16 v[26:29], v[122:125], v[194:197], v[26:29]
	v_mfma_f32_16x16x32_bf16 v[14:17], v[98:101], v[210:213], v[14:17]
	v_mfma_f32_16x16x32_bf16 v[10:13], v[122:125], v[210:213], v[10:13]
	v_mfma_f32_16x16x32_bf16 v[62:65], v[110:113], v[182:185], v[62:65]
	v_mfma_f32_16x16x32_bf16 v[58:61], v[134:137], v[182:185], v[58:61]
	v_mfma_f32_16x16x32_bf16 v[46:49], v[110:113], v[190:193], v[46:49]
	v_mfma_f32_16x16x32_bf16 v[42:45], v[134:137], v[190:193], v[42:45]
	v_mfma_f32_16x16x32_bf16 v[30:33], v[110:113], v[206:209], v[30:33]
	v_mfma_f32_16x16x32_bf16 v[26:29], v[134:137], v[206:209], v[26:29]
	v_mfma_f32_16x16x32_bf16 v[14:17], v[110:113], v[214:217], v[14:17]
	v_mfma_f32_16x16x32_bf16 v[10:13], v[134:137], v[214:217], v[10:13]
	s_setprio 0
	s_setprio 1
	v_mfma_f32_16x16x32_bf16 v[54:57], v[146:149], v[178:181], v[54:57]
	v_mfma_f32_16x16x32_bf16 v[50:53], v[170:173], v[178:181], v[50:53]
	v_mfma_f32_16x16x32_bf16 v[38:41], v[146:149], v[186:189], v[38:41]
	v_mfma_f32_16x16x32_bf16 v[34:37], v[170:173], v[186:189], v[34:37]
	v_mfma_f32_16x16x32_bf16 v[22:25], v[146:149], v[194:197], v[22:25]
	v_mfma_f32_16x16x32_bf16 v[18:21], v[170:173], v[194:197], v[18:21]
	v_mfma_f32_16x16x32_bf16 v[6:9], v[146:149], v[210:213], v[6:9]
	v_mfma_f32_16x16x32_bf16 v[2:5], v[170:173], v[210:213], v[2:5]
	v_mfma_f32_16x16x32_bf16 v[54:57], v[150:153], v[182:185], v[54:57]
	v_mfma_f32_16x16x32_bf16 v[50:53], v[174:177], v[182:185], v[50:53]
	v_mfma_f32_16x16x32_bf16 v[38:41], v[150:153], v[190:193], v[38:41]
	v_mfma_f32_16x16x32_bf16 v[34:37], v[174:177], v[190:193], v[34:37]
	v_mfma_f32_16x16x32_bf16 v[22:25], v[150:153], v[206:209], v[22:25]
	v_mfma_f32_16x16x32_bf16 v[18:21], v[174:177], v[206:209], v[18:21]
	v_mfma_f32_16x16x32_bf16 v[6:9], v[150:153], v[214:217], v[6:9]
	v_mfma_f32_16x16x32_bf16 v[2:5], v[174:177], v[214:217], v[2:5]
	s_setprio 0
	s_barrier
	s_add_u32 s66, s66, 0x100
	s_addc_u32 s67, s67, 0
	s_cmp_ge_i32 s68, s51
	s_mov_b64 s[28:29], s[30:31]
	s_mov_b32 s34, s68
	s_cbranch_scc0 .LBB0_554
	s_and_b64 vcc, exec, s[24:25]
	s_cbranch_vccz .LBB0_557

;     template <int AI> __device__ __forceinline__ void half_rows(AccT acc, int row0, int col0, int slot, int sq, int fq, const f32x4 (&gsc)[4]) const {
;         v4u xw[4][2];
; #pragma unroll
;         for (int m = 0; m < 4; ++m)
; #pragma unroll
;             for (int bj = 0; bj < 2; ++bj) xw[m][bj] = *(const v4u*)(X + (size_t)(row0 + m * 16) * DM + col0 + bj * HALF);
; #pragma unroll
;         for (int m = 0; m < 4; ++m) { const int row = row0 + m * 16;
;             float ss = 0.f;
; #pragma unroll
;             for (int bj = 0; bj < 2; ++bj) { const size_t off = (size_t)row * DM + col0 + bj * HALF;
;                 float xi[8]; unpack8(xw[m][bj], xi);
;                 const f32x4 x0 = (f32x4){xi[0], xi[1], xi[2], xi[3]} + gsc[bj * 2] * acc[AI][bj][m][0], x1 = (f32x4){xi[4], xi[5], xi[6], xi[7]} + gsc[bj * 2 + 1] * acc[AI][bj][m][1];
;                 { u32x4 xs_; xs_.x = cvt_pk_bf16(x0[0], x0[1]); xs_.y = cvt_pk_bf16(x0[2], x0[3]); xs_.z = cvt_pk_bf16(x1[0], x1[1]); xs_.w = cvt_pk_bf16(x1[2], x1[3]); *(u32x4*)(X + off) = xs_; }
;                 if (NEXT) { ss += ((x0.x * x0.x + x0.y * x0.y) + (x0.z * x0.z + x0.w * x0.w)) + ((x1.x * x1.x + x1.y * x1.y) + (x1.z * x1.z + x1.w * x1.w));
;                     const float* gp_ = gam + (size_t)sq * DM + col0 + bj * HALF; const f32x4 y0 = x0 * *(const f32x4*)gp_, y1 = x1 * *(const f32x4*)(gp_ + 4);
;                     u32x4 w; w.x = cvt_pk_bf16(y0[0], y0[1]); w.y = cvt_pk_bf16(y0[2], y0[3]); w.z = cvt_pk_bf16(y1[0], y1[1]); w.w = cvt_pk_bf16(y1[2], y1[3]);
;                     *(u32x4*)(XB + off) = w; } }
;             if (NEXT) { ss += __shfl_xor(ss, 16); ss += __shfl_xor(ss, 32); if (fq == 0) SSQ[(size_t)row * 16 + slot] = ss; } }
;     }
;     __device__ __forceinline__ void operator()(AccT acc, const Unit& u, int wr, int wc, int fr, int fq) const {
;         const int upm = u.pm, upn = u.pn, uhalf = u.half;
;         const int col0 = upn * BM + wc * 32 + 8 * fq, sq = upm >> 3, slot = upn * 4 + wc, rbase = upm * BM + wr * 64 + fr;
;         f32x4 gsc[4];
; #pragma unroll
;         for (int q = 0; q < 4; ++q) gsc[q] = *(const f32x4*)(gate + (size_t)sq * NMOD + col0 + (q >> 1) * HALF + 4 * (q & 1)) * scale;
;         if (uhalf != 1) half_rows<0>(acc, rbase, col0, slot, sq, fq, gsc);
;         if (uhalf != 0) half_rows<1>(acc, rbase + HALF, col0, slot, sq, fq, gsc);
;     }
.LBB0_557:
	s_mov_b32 s98, 1
	s_ashr_i32 s30, s64, 3
	v_lshl_or_b32 v170, s65, 8, v198
	s_lshl_b32 s34, s65, 2
	v_lshl_add_u32 v184, s64, 8, v1
	s_ashr_i32 s31, s30, 31
	s_mul_i32 s28, s30, 0x9000
	v_ashrrev_i32_e32 v171, 31, v170
	v_ashrrev_i32_e32 v185, 31, v184
	s_mul_hi_i32 s29, s30, 0x9000
	s_add_u32 s28, s14, s28
	v_lshl_add_u64 v[182:183], v[170:171], 1, s[0:1]
	v_lshlrev_b64 v[98:99], 11, v[184:185]
	s_addc_u32 s29, s15, s29
	v_lshlrev_b64 v[172:173], 2, v[170:171]
	v_lshl_add_u64 v[222:223], v[182:183], 0, v[98:99]
	v_lshl_add_u64 v[98:99], s[28:29], 0, v[172:173]
	global_load_dwordx4 v[174:177], v[222:223], off
	global_load_dwordx4 v[178:181], v[98:99], off
	global_load_dwordx4 v[206:209], v[98:99], off offset:16
	s_or_b32 s28, s34, s50
	v_or_b32_e32 v194, 16, v184
	v_or_b32_e32 v190, 32, v184
	v_or_b32_e32 v186, 48, v184
	s_lshl_b64 s[30:31], s[30:31], 12
	s_ashr_i32 s29, s28, 31
	v_ashrrev_i32_e32 v195, 31, v194
	v_ashrrev_i32_e32 v191, 31, v190
	v_ashrrev_i32_e32 v187, 31, v186
	s_add_u32 s30, s16, s30
	v_lshlrev_b64 v[100:101], 11, v[194:195]
	v_lshlrev_b64 v[110:111], 11, v[190:191]
	v_lshlrev_b64 v[112:113], 11, v[186:187]
	global_load_dwordx4 v[210:213], v[222:223], off offset:256
	s_addc_u32 s31, s17, s31
	v_lshl_add_u64 v[196:197], v[182:183], 0, v[100:101]
	v_lshl_add_u64 v[192:193], v[182:183], 0, v[110:111]
	v_lshl_add_u64 v[188:189], v[182:183], 0, v[112:113]
	global_load_dwordx4 v[214:217], v[98:99], off offset:528
	global_load_dwordx4 v[218:221], v[98:99], off offset:512
	global_load_dwordx4 v[150:153], v[196:197], off
	global_load_dwordx4 v[146:149], v[196:197], off offset:256
	global_load_dwordx4 v[134:137], v[192:193], off
	global_load_dwordx4 v[122:125], v[192:193], off offset:256
	global_load_dwordx4 v[110:113], v[188:189], off
	global_load_dwordx4 v[98:101], v[188:189], off offset:256
	v_lshl_add_u64 v[172:173], s[30:31], 0, v[172:173]
	s_waitcnt vmcnt(0)
	v_lshlrev_b32_e32 v224, 16, v174
	v_and_b32_e32 v225, 0xffff0000, v174
	v_lshlrev_b32_e32 v226, 16, v175
	v_and_b32_e32 v227, 0xffff0000, v175
	v_lshlrev_b32_e32 v228, 16, v176
	v_and_b32_e32 v229, 0xffff0000, v176
	v_lshlrev_b32_e32 v230, 16, v177
	v_and_b32_e32 v231, 0xffff0000, v177
	v_pk_mul_f32 v[180:181], v[180:181], 0.5 op_sel_hi:[1,0]
	v_pk_mul_f32 v[178:179], v[178:179], 0.5 op_sel_hi:[1,0]
	v_pk_mul_f32 v[176:177], v[208:209], 0.5 op_sel_hi:[1,0]
	v_pk_mul_f32 v[174:175], v[206:207], 0.5 op_sel_hi:[1,0]
	v_pk_fma_f32 v[226:227], v[144:145], v[180:181], v[226:227]
	v_pk_fma_f32 v[232:233], v[142:143], v[178:179], v[224:225]
	v_pk_fma_f32 v[230:231], v[140:141], v[176:177], v[230:231]
	v_pk_fma_f32 v[228:229], v[138:139], v[174:175], v[228:229]
	v_cvt_pk_bf16_f32 v138, v232, v233
	v_cvt_pk_bf16_f32 v139, v226, v227
	v_lshlrev_b32_e32 v242, 16, v212
	v_cvt_pk_bf16_f32 v140, v228, v229
	v_cvt_pk_bf16_f32 v141, v230, v231
	global_store_dwordx4 v[222:223], v[138:141], off
	global_load_dwordx4 v[206:209], v[172:173], off
	s_nop 0
	global_load_dwordx4 v[222:225], v[172:173], off offset:16
	v_lshlrev_b64 v[138:139], 10, v[184:185]
	v_lshl_add_u64 v[138:139], v[138:139], 0, v[170:171]
	v_lshlrev_b64 v[234:235], 1, v[138:139]
	v_and_b32_e32 v243, 0xffff0000, v212
	v_lshlrev_b32_e32 v212, 16, v213
	v_and_b32_e32 v213, 0xffff0000, v213
	v_pk_mul_f32 v[140:141], v[216:217], 0.5 op_sel_hi:[1,0]
	v_pk_mul_f32 v[138:139], v[214:215], 0.5 op_sel_hi:[1,0]
	v_lshl_add_u64 v[236:237], s[10:11], 0, v[234:235]
	v_or_b32_e32 v234, 0x100, v234
	v_lshlrev_b32_e32 v240, 16, v210
	v_and_b32_e32 v241, 0xffff0000, v210
	v_lshlrev_b32_e32 v210, 16, v211
	v_and_b32_e32 v211, 0xffff0000, v211
	v_pk_mul_f32 v[144:145], v[220:221], 0.5 op_sel_hi:[1,0]
	v_pk_mul_f32 v[142:143], v[218:219], 0.5 op_sel_hi:[1,0]
	v_pk_fma_f32 v[212:213], v[128:129], v[140:141], v[212:213]
	v_pk_fma_f32 v[216:217], v[126:127], v[138:139], v[242:243]
	v_lshl_add_u64 v[238:239], s[0:1], 0, v[234:235]
	v_pk_fma_f32 v[210:211], v[132:133], v[144:145], v[210:211]
	v_pk_fma_f32 v[214:215], v[130:131], v[142:143], v[240:241]
	v_mul_f32_e32 v205, v229, v229
	v_mul_f32_e32 v218, v231, v231
	v_mul_f32_e32 v219, v215, v215
	v_mul_f32_e32 v220, v211, v211
	v_mul_f32_e32 v221, v217, v217
	v_fmac_f32_e32 v205, v228, v228
	v_fmac_f32_e32 v218, v230, v230
	v_fmac_f32_e32 v219, v214, v214
	v_fmac_f32_e32 v220, v210, v210
	v_fmac_f32_e32 v221, v216, v216
	s_waitcnt vmcnt(1)
	v_pk_mul_f32 v[128:129], v[226:227], v[208:209]
	v_pk_mul_f32 v[126:127], v[232:233], v[206:207]
	s_waitcnt vmcnt(0)
	v_pk_mul_f32 v[130:131], v[230:231], v[224:225]
	v_pk_mul_f32 v[132:133], v[228:229], v[222:223]
	v_cvt_pk_bf16_f32 v126, v126, v127
	v_cvt_pk_bf16_f32 v127, v128, v129
	v_mul_f32_e32 v222, v213, v213
	v_cvt_pk_bf16_f32 v128, v132, v133
	v_cvt_pk_bf16_f32 v129, v130, v131
	global_store_dwordx4 v[236:237], v[126:129], off
	v_fmac_f32_e32 v222, v212, v212
	s_nop 0
	v_cvt_pk_bf16_f32 v126, v214, v215
	v_cvt_pk_bf16_f32 v127, v210, v211
	v_cvt_pk_bf16_f32 v128, v216, v217
	v_cvt_pk_bf16_f32 v129, v212, v213
	global_store_dwordx4 v[238:239], v[126:129], off
	global_load_dwordx4 v[130:133], v[172:173], off offset:512
	global_load_dwordx4 v[206:209], v[172:173], off offset:528
	v_and_b32_e32 v127, 64, v204
	v_mul_f32_e32 v128, v233, v233
	v_mul_f32_e32 v129, v227, v227
	v_xor_b32_e32 v126, 16, v204
	v_add_u32_e32 v127, 64, v127
	v_fmac_f32_e32 v128, v232, v232
	v_fmac_f32_e32 v129, v226, v226
	v_cmp_lt_i32_e32 vcc, v126, v127
	v_add_f32_e32 v128, v128, v129
	v_add_f32_e32 v129, v205, v218
	v_add_f32_e32 v205, v219, v220
	v_add_f32_e32 v218, v221, v222
	v_cndmask_b32_e32 v126, v204, v126, vcc
	v_add_f32_e32 v128, v128, v129
	v_add_f32_e32 v129, v205, v218
	v_lshlrev_b32_e32 v126, 2, v126
	v_add_f32_e32 v128, v128, v129
	ds_bpermute_b32 v129, v126, v128
	v_xor_b32_e32 v205, 32, v204
	v_cmp_lt_i32_e32 vcc, v205, v127
	s_waitcnt lgkmcnt(0)
	v_add_f32_e32 v128, v128, v129
	v_cndmask_b32_e32 v127, v204, v205, vcc
	v_lshlrev_b32_e32 v127, 2, v127
	ds_bpermute_b32 v129, v127, v128
	s_waitcnt vmcnt(1)
	v_pk_mul_f32 v[132:133], v[210:211], v[132:133]
	v_pk_mul_f32 v[130:131], v[214:215], v[130:131]
	s_waitcnt vmcnt(0)
	v_pk_mul_f32 v[206:207], v[216:217], v[206:207]
	v_cvt_pk_bf16_f32 v130, v130, v131
	v_cvt_pk_bf16_f32 v131, v132, v133
	v_pk_mul_f32 v[208:209], v[212:213], v[208:209]
	v_cvt_pk_bf16_f32 v132, v206, v207
	v_lshl_add_u64 v[206:207], s[10:11], 0, v[234:235]
	v_cvt_pk_bf16_f32 v133, v208, v209
	global_store_dwordx4 v[206:207], v[130:133], off
	s_and_saveexec_b64 s[30:31], s[4:5]
	s_cbranch_execz .LBB0_559
	v_lshlrev_b64 v[130:131], 6, v[184:185]
	v_lshl_add_u64 v[130:131], s[12:13], 0, v[130:131]
	v_lshl_add_u64 v[130:131], s[28:29], 2, v[130:131]
	s_waitcnt lgkmcnt(0)
	v_add_f32_e32 v128, v128, v129
	global_store_dword v[130:131], v128, off

;     __host__ __device__ void init(int N_, int G_, int c_) { nN = N_ / BM; mn.init(NPROMPT, N_, G_, c_); G = G_; c = c_; }
;     __host__ __device__ bool next(int i, Unit& u) const { const int q = i / 3; if (!b.next(q, u)) return false; u.seg = i - 3 * q; return true; }
;     __host__ __device__ bool next(int i, Unit& u) const { const long L = (long)i * G + c; if (L >= nN) return false; u.pm = NPROMPT / BM; u.pn = (int)L; u.half = -1; u.seg = 0; return true; }
;     __host__ __device__ bool next(int i, Unit& u) const {
;         const long L = (long)i * G + c; if (L >= nwg) return false;
;         int wgid = (int)L; { const int q = nwg / NXCD, r = nwg % NXCD, xcd = wgid % NXCD, off = wgid / NXCD; wgid = (xcd < r ? xcd * (q + 1) : r * (q + 1) + (xcd - r) * q) + off; }
;         const int nig = WGM * nN, gid = wgid / nig, fm = gid * WGM, gsz = (nM - fm) < WGM ? (nM - fm) : WGM;
;         u.pm = fm + ((wgid % nig) % gsz); u.pn = (wgid % nig) / gsz; u.half = -1; u.seg = 0; return true;
;     }
; __global__ void __launch_bounds__(NWAVES * 64, 2) fwd(Args args_unused) {
;     ...
;         if (IN(pb + 2)) {
;             PH_PTRS PH_LAYER
;             pg8::Gemm g{XB, (const bf16*)(wl + WL_IN), M, NZT, DM, DM, DM, 0}; pg8::StaticOrder S; S.init(M, NZT, G, bx);
;             pg8::EpiZ E{Z, SSQ, (const float*)(ws + WS_SHW2) + (size_t)l * NSEQ * NZT, out, DT, A->in[I_DTB] + l * 16, l};
;             pg8::gemm_phase<pg8::EpiZ, pg8::StaticOrder>(lds, g, S, E);
.LBB0_637:
	s_mov_b32 s98, 0
	s_cmp_lt_i32 s84, 6
	s_cselect_b64 s[0:1], -1, 0
	s_cmp_gt_i32 s85, 5
	s_cselect_b64 s[4:5], -1, 0
	s_and_b64 s[0:1], s[0:1], s[4:5]
	s_andn2_b64 vcc, exec, s[0:1]
	v_writelane_b32 v254, s94, 10
	s_nop 1
	v_writelane_b32 v254, s95, 11
	s_cbranch_vccnz .LBB0_1364
	s_mov_b64 s[0:1], s[82:83]
	s_mov_b32 s12, 0
	s_mov_b32 s3, s2
	s_load_dword s64, s[82:83], 0x168
	v_readlane_b32 s4, v254, 3
	s_waitcnt lgkmcnt(0)
	v_mov_b32_e32 v1, v0
	v_mov_b32_e32 v14, v0
	s_cmpk_lt_i32 s3, 0x18b1
	s_movk_i32 s14, 0x400
	v_readfirstlane_b32 s13, v14
	s_cselect_b64 s[8:9], -1, 0
	s_cmpk_gt_i32 s3, 0x18b0
	s_cbranch_scc1 .LBB0_641
	s_ashr_i32 s4, s3, 31
	s_lshr_b32 s4, s4, 29
	s_add_i32 s7, s3, s4
	s_and_b32 s4, s7, -8
	s_sub_i32 s6, s3, s4
	s_cmp_gt_i32 s6, 0
	s_cbranch_scc0 .LBB0_1307
	s_mul_i32 s4, s6, 0x316
	s_or_b32 s10, s4, 1
	s_ashr_i32 s4, s7, 3
	s_cbranch_execz .LBB0_1308
	s_branch .LBB0_1309

; #define PG8_STAGE(bufoff, gbase, voff) do { _Pragma("unroll") for (int _i = 0; _i < 2; ++_i) \
;         __builtin_amdgcn_global_load_lds((const unsigned*)((const char*)(gbase) + (voff)[_i]), (PG8_LAS unsigned*)(lds + (bufoff) + ldsw + _i * 8192), 16, 0, 0); } while (0)
; #define PG8_LDA(dst, b, h) do { _Pragma("unroll") for (int m = 0; m < 4; ++m) _Pragma("unroll") for (int k = 0; k < 2; ++k) dst[m][k] = *(const PG8_LAS bf16x8*)(lds + PG8_SA(b, h) + aoff + m * 2048 + k * 1024); } while (0)
; #define PG8_LDB(dst, b, h) do { _Pragma("unroll") for (int n = 0; n < 2; ++n) _Pragma("unroll") for (int k = 0; k < 2; ++k) dst[n][k] = *(const PG8_LAS bf16x8*)(lds + PG8_SB(b, h) + boff + n * 2048 + k * 1024); } while (0)
; #define PG8_MMA(ai, bj, At, Bt) do { __builtin_amdgcn_s_setprio(1); _Pragma("unroll") for (int m = 0; m < 4; ++m) _Pragma("unroll") for (int n = 0; n < 2; ++n) _Pragma("unroll") for (int k = 0; k < 2; ++k) \
;         acc[ai][bj][m][n] = __builtin_amdgcn_mfma_f32_16x16x32_bf16(Bt[n][k], At[m][k], acc[ai][bj][m][n], 0, 0, 0); __builtin_amdgcn_s_setprio(0); } while (0)
; #define PG8_WAIT_V(n) asm volatile("s_waitcnt vmcnt(" #n ")" ::: "memory")
; #define PG8_BAR __builtin_amdgcn_s_barrier()
; template <class Epi, class Sched, bool SEG3 = false>
; __device__ __forceinline__ void gemm_phase(PG8_LAS unsigned char* lds, const Gemm g, const Sched& S, const Epi& E) {
;     ...
;         for (int t = 0; t < ntc; t += 2) {
;             bf16x8 At[4][2], B0[2][2], B1[2][2];
;             const bool last = (t == ntc - 2);
;             const char* a1 = cA + (size_t)(t + 1) * kstep;
;             const char* a2 = last ? nA : cA + (size_t)(t + 2) * kstep; const char* b2 = last ? nB : cB + (size_t)(t + 2) * kstep;
;             const char* a3 = a2 + kstep; const char* b3 = b2 + kstep;
;             PG8_LDB(B0, 0, 0); PG8_LDB(B1, 0, 1); PG8_SCHED; PG8_LDA(At, 0, 0); PG8_STAGE(PG8_SA(1, 1), a1 + hsA, voffA);
;             PG8_WAIT_V(8); PG8_WAIT_L(0); PG8_BAR; if (cur.half != 1) { PG8_MMA(0, 0, At, B0); PG8_MMA(0, 1, At, B1); } PG8_BAR; PG8_SCHED;
;             PG8_LDA(At, 0, 1); PG8_STAGE(PG8_SB(0, 0), b2, voffB); PG8_STAGE(PG8_SB(0, 1), b2 + hsB, voffB); PG8_STAGE(PG8_SA(0, 0), a2, voffA);
;             PG8_WAIT_V(8); PG8_WAIT_L(0); PG8_BAR; if (cur.half != 0) { PG8_MMA(1, 0, At, B0); PG8_MMA(1, 1, At, B1); } PG8_BAR; PG8_SCHED;
.LBB0_655:
	ds_read_b128 v[10:13], v187
	ds_read_b128 v[14:17], v187 offset:1024
	ds_read_b128 v[34:37], v187 offset:2048
	ds_read_b128 v[38:41], v187 offset:3072
	ds_read_b128 v[146:149], v188
	ds_read_b128 v[174:177], v188 offset:1024
	ds_read_b128 v[178:181], v188 offset:2048
	ds_read_b128 v[182:185], v188 offset:3072
	s_add_i32 s20, s10, 2
	s_add_u32 s11, s8, 0xfffc0080
	s_addc_u32 s12, s9, -1
	s_cmp_eq_u32 s86, s10
	s_cselect_b32 s10, s16, s17
	s_cselect_b32 s13, s7, s12
	s_cselect_b32 s12, s14, s11
	s_cselect_b32 s11, s15, s19
	v_lshl_add_u64 v[244:245], s[8:9], 0, v[168:169]
	s_add_i32 m0, s73, 0xc000
	ds_read_b128 v[212:215], v189
	ds_read_b128 v[216:219], v189 offset:1024
	ds_read_b128 v[220:223], v189 offset:2048
	ds_read_b128 v[224:227], v189 offset:3072
	ds_read_b128 v[228:231], v189 offset:4096
	ds_read_b128 v[232:235], v189 offset:5120
	ds_read_b128 v[236:239], v189 offset:6144
	ds_read_b128 v[240:243], v189 offset:7168
	global_load_lds_dwordx4 v[244:245], off
	v_lshl_add_u64 v[244:245], s[8:9], 0, v[170:171]
	s_add_i32 m0, s73, 0xe000
	s_nop 0
	global_load_lds_dwordx4 v[244:245], off
	s_cmp_lg_u32 s98, 0
	s_cbranch_scc1 .Lfi_a_1
	s_waitcnt vmcnt(8)
.Lfi_a_1:
	s_waitcnt lgkmcnt(0)
	s_barrier
	s_setprio 1
	v_mfma_f32_16x16x32_bf16 v[142:145], v[10:13], v[212:215], v[142:145]
	v_mfma_f32_16x16x32_bf16 v[138:141], v[34:37], v[212:215], v[138:141]
	v_mfma_f32_16x16x32_bf16 v[126:129], v[10:13], v[220:223], v[126:129]
	v_mfma_f32_16x16x32_bf16 v[122:125], v[34:37], v[220:223], v[122:125]
	v_mfma_f32_16x16x32_bf16 v[110:113], v[10:13], v[228:231], v[110:113]
	v_mfma_f32_16x16x32_bf16 v[106:109], v[34:37], v[228:231], v[106:109]
	v_mfma_f32_16x16x32_bf16 v[94:97], v[10:13], v[236:239], v[94:97]
	v_mfma_f32_16x16x32_bf16 v[90:93], v[34:37], v[236:239], v[90:93]
	v_mfma_f32_16x16x32_bf16 v[142:145], v[14:17], v[216:219], v[142:145]
	v_mfma_f32_16x16x32_bf16 v[138:141], v[38:41], v[216:219], v[138:141]
	v_mfma_f32_16x16x32_bf16 v[126:129], v[14:17], v[224:227], v[126:129]
	v_mfma_f32_16x16x32_bf16 v[122:125], v[38:41], v[224:227], v[122:125]
	v_mfma_f32_16x16x32_bf16 v[110:113], v[14:17], v[232:235], v[110:113]
	v_mfma_f32_16x16x32_bf16 v[106:109], v[38:41], v[232:235], v[106:109]
	v_mfma_f32_16x16x32_bf16 v[94:97], v[14:17], v[240:243], v[94:97]
	v_mfma_f32_16x16x32_bf16 v[90:93], v[38:41], v[240:243], v[90:93]
	s_setprio 0
	s_setprio 1
	v_mfma_f32_16x16x32_bf16 v[134:137], v[146:149], v[212:215], v[134:137]
	v_mfma_f32_16x16x32_bf16 v[130:133], v[178:181], v[212:215], v[130:133]
	v_mfma_f32_16x16x32_bf16 v[118:121], v[146:149], v[220:223], v[118:121]
	v_mfma_f32_16x16x32_bf16 v[114:117], v[178:181], v[220:223], v[114:117]
	v_mfma_f32_16x16x32_bf16 v[102:105], v[146:149], v[228:231], v[102:105]
	v_mfma_f32_16x16x32_bf16 v[98:101], v[178:181], v[228:231], v[98:101]
	v_mfma_f32_16x16x32_bf16 v[86:89], v[146:149], v[236:239], v[86:89]
	v_mfma_f32_16x16x32_bf16 v[82:85], v[178:181], v[236:239], v[82:85]
	v_mfma_f32_16x16x32_bf16 v[134:137], v[174:177], v[216:219], v[134:137]
	v_mfma_f32_16x16x32_bf16 v[130:133], v[182:185], v[216:219], v[130:133]
	v_mfma_f32_16x16x32_bf16 v[118:121], v[174:177], v[224:227], v[118:121]
	v_mfma_f32_16x16x32_bf16 v[114:117], v[182:185], v[224:227], v[114:117]
	v_mfma_f32_16x16x32_bf16 v[102:105], v[174:177], v[232:235], v[102:105]
	v_mfma_f32_16x16x32_bf16 v[98:101], v[182:185], v[232:235], v[98:101]
	v_mfma_f32_16x16x32_bf16 v[86:89], v[174:177], v[240:243], v[86:89]
	v_mfma_f32_16x16x32_bf16 v[82:85], v[182:185], v[240:243], v[82:85]
	s_setprio 0
	s_barrier
	s_mov_b32 m0, s69
	v_lshl_add_u64 v[244:245], s[10:11], 0, v[152:153]
	s_add_u32 s54, s10, 0x40000
	ds_read_b128 v[212:215], v189 offset:16384
	ds_read_b128 v[216:219], v189 offset:17408
	ds_read_b128 v[220:223], v189 offset:18432
	ds_read_b128 v[224:227], v189 offset:19456
	ds_read_b128 v[228:231], v189 offset:20480
	ds_read_b128 v[232:235], v189 offset:21504
	ds_read_b128 v[236:239], v189 offset:22528
	ds_read_b128 v[240:243], v189 offset:23552
	global_load_lds_dwordx4 v[244:245], off
	v_lshl_add_u64 v[246:247], s[10:11], 0, v[156:157]
	s_mov_b32 m0, s70
	s_addc_u32 s55, s11, 0
	global_load_lds_dwordx4 v[246:247], off
	v_lshl_add_u64 v[248:249], s[54:55], 0, v[152:153]
	s_mov_b32 m0, s71
	v_lshl_add_u64 v[250:251], s[12:13], 0, v[154:155]
	global_load_lds_dwordx4 v[248:249], off
	v_lshl_add_u64 v[248:249], s[54:55], 0, v[156:157]
	s_mov_b32 m0, s72
	s_nop 0
	global_load_lds_dwordx4 v[248:249], off
	v_lshl_add_u64 v[248:249], s[12:13], 0, v[150:151]
	s_mov_b32 m0, s73
	s_nop 0
	global_load_lds_dwordx4 v[248:249], off
	s_mov_b32 m0, s74
	s_nop 0
	global_load_lds_dwordx4 v[250:251], off
	s_cmp_lg_u32 s98, 0
	s_cbranch_scc1 .Lfi_b_1
	s_waitcnt vmcnt(8)
; #define PG8_STAGE(bufoff, gbase, voff) do { _Pragma("unroll") for (int _i = 0; _i < 2; ++_i) \
;         __builtin_amdgcn_global_load_lds((const unsigned*)((const char*)(gbase) + (voff)[_i]), (PG8_LAS unsigned*)(lds + (bufoff) + ldsw + _i * 8192), 16, 0, 0); } while (0)
; #define PG8_LDA(dst, b, h) do { _Pragma("unroll") for (int m = 0; m < 4; ++m) _Pragma("unroll") for (int k = 0; k < 2; ++k) dst[m][k] = *(const PG8_LAS bf16x8*)(lds + PG8_SA(b, h) + aoff + m * 2048 + k * 1024); } while (0)
; #define PG8_LDB(dst, b, h) do { _Pragma("unroll") for (int n = 0; n < 2; ++n) _Pragma("unroll") for (int k = 0; k < 2; ++k) dst[n][k] = *(const PG8_LAS bf16x8*)(lds + PG8_SB(b, h) + boff + n * 2048 + k * 1024); } while (0)
; #define PG8_MMA(ai, bj, At, Bt) do { __builtin_amdgcn_s_setprio(1); _Pragma("unroll") for (int m = 0; m < 4; ++m) _Pragma("unroll") for (int n = 0; n < 2; ++n) _Pragma("unroll") for (int k = 0; k < 2; ++k) \
;         acc[ai][bj][m][n] = __builtin_amdgcn_mfma_f32_16x16x32_bf16(Bt[n][k], At[m][k], acc[ai][bj][m][n], 0, 0, 0); __builtin_amdgcn_s_setprio(0); } while (0)
; #define PG8_WAIT_V(n) asm volatile("s_waitcnt vmcnt(" #n ")" ::: "memory")
; #define PG8_WAIT_L(n) do { asm volatile("s_waitcnt lgkmcnt(" #n ")" ::: "memory"); __builtin_amdgcn_s_waitcnt(0xC07F); } while (0)
; #define PG8_BAR __builtin_amdgcn_s_barrier()
; #define PG8_SCHED __builtin_amdgcn_sched_barrier(0)
; template <class Epi, class Sched, bool SEG3 = false>
; __device__ __forceinline__ void gemm_phase(PG8_LAS unsigned char* lds, const Gemm g, const Sched& S, const Epi& E) {
;     ...
;             PG8_WAIT_V(8); PG8_WAIT_L(0); PG8_BAR; if (cur.half != 0) { PG8_MMA(1, 0, At, B0); PG8_MMA(1, 1, At, B1); } PG8_BAR; PG8_SCHED;
;             PG8_LDB(B0, 1, 0); PG8_LDB(B1, 1, 1); PG8_SCHED; PG8_LDA(At, 1, 0); PG8_STAGE(PG8_SA(0, 1), a2 + hsA, voffA);
;             PG8_WAIT_V(8); PG8_WAIT_L(0); PG8_BAR; if (cur.half != 1) { PG8_MMA(0, 0, At, B0); PG8_MMA(0, 1, At, B1); } PG8_BAR; PG8_SCHED;
;             PG8_LDA(At, 1, 1); PG8_STAGE(PG8_SB(1, 0), b3, voffB); PG8_STAGE(PG8_SB(1, 1), b3 + hsB, voffB); PG8_STAGE(PG8_SA(1, 0), a3, voffA);
.Lfi_b_1:
	s_mov_b32 s98, 0
	s_waitcnt lgkmcnt(0)
	s_barrier
	s_setprio 1
	v_mfma_f32_16x16x32_bf16 v[78:81], v[10:13], v[212:215], v[78:81]
	v_mfma_f32_16x16x32_bf16 v[74:77], v[34:37], v[212:215], v[74:77]
	v_mfma_f32_16x16x32_bf16 v[62:65], v[10:13], v[220:223], v[62:65]
	v_mfma_f32_16x16x32_bf16 v[58:61], v[34:37], v[220:223], v[58:61]
	v_mfma_f32_16x16x32_bf16 v[46:49], v[10:13], v[228:231], v[46:49]
	v_mfma_f32_16x16x32_bf16 v[42:45], v[34:37], v[228:231], v[42:45]
	v_mfma_f32_16x16x32_bf16 v[10:13], v[10:13], v[236:239], v[22:25]
	v_mfma_f32_16x16x32_bf16 v[78:81], v[14:17], v[216:219], v[78:81]
	v_mfma_f32_16x16x32_bf16 v[74:77], v[38:41], v[216:219], v[74:77]
	v_mfma_f32_16x16x32_bf16 v[62:65], v[14:17], v[224:227], v[62:65]
	v_mfma_f32_16x16x32_bf16 v[58:61], v[38:41], v[224:227], v[58:61]
	v_mfma_f32_16x16x32_bf16 v[46:49], v[14:17], v[232:235], v[46:49]
	v_mfma_f32_16x16x32_bf16 v[42:45], v[38:41], v[232:235], v[42:45]
	v_mfma_f32_16x16x32_bf16 v[10:13], v[14:17], v[240:243], v[10:13]
	v_mfma_f32_16x16x32_bf16 v[14:17], v[34:37], v[236:239], v[18:21]
	v_mfma_f32_16x16x32_bf16 v[14:17], v[38:41], v[240:243], v[14:17]
	s_setprio 0
	s_setprio 1
	v_mfma_f32_16x16x32_bf16 v[18:21], v[146:149], v[212:215], v[70:73]
	v_mfma_f32_16x16x32_bf16 v[34:37], v[174:177], v[216:219], v[18:21]
	v_mfma_f32_16x16x32_bf16 v[18:21], v[178:181], v[212:215], v[66:69]
	v_mfma_f32_16x16x32_bf16 v[38:41], v[182:185], v[216:219], v[18:21]
	v_mfma_f32_16x16x32_bf16 v[18:21], v[146:149], v[220:223], v[54:57]
	v_mfma_f32_16x16x32_bf16 v[54:57], v[174:177], v[224:227], v[18:21]
	v_mfma_f32_16x16x32_bf16 v[18:21], v[178:181], v[220:223], v[50:53]
	v_mfma_f32_16x16x32_bf16 v[50:53], v[182:185], v[224:227], v[18:21]
	v_mfma_f32_16x16x32_bf16 v[18:21], v[146:149], v[228:231], v[30:33]
	v_mfma_f32_16x16x32_bf16 v[30:33], v[174:177], v[232:235], v[18:21]
	v_mfma_f32_16x16x32_bf16 v[18:21], v[178:181], v[228:231], v[26:29]
	v_mfma_f32_16x16x32_bf16 v[6:9], v[146:149], v[236:239], v[6:9]
	v_mfma_f32_16x16x32_bf16 v[2:5], v[178:181], v[236:239], v[2:5]
	v_mfma_f32_16x16x32_bf16 v[26:29], v[182:185], v[232:235], v[18:21]
	v_mfma_f32_16x16x32_bf16 v[6:9], v[174:177], v[240:243], v[6:9]
	v_mfma_f32_16x16x32_bf16 v[2:5], v[182:185], v[240:243], v[2:5]
	s_setprio 0
	s_barrier
	s_nop 0
	ds_read_b128 v[18:21], v190
	ds_read_b128 v[22:25], v190 offset:1024
	ds_read_b128 v[66:69], v190 offset:2048
	ds_read_b128 v[70:73], v190 offset:3072
	ds_read_b128 v[146:149], v191
	ds_read_b128 v[174:177], v191 offset:1024
	ds_read_b128 v[178:181], v191 offset:2048
	ds_read_b128 v[182:185], v191 offset:3072
	s_add_u32 s12, s12, 0x40000
	s_addc_u32 s13, s13, 0
	s_mov_b32 m0, s75
	v_lshl_add_u64 v[252:253], s[12:13], 0, v[150:151]
	ds_read_b128 v[212:215], v189 offset:32768
	ds_read_b128 v[216:219], v189 offset:33792
	ds_read_b128 v[220:223], v189 offset:34816
	ds_read_b128 v[224:227], v189 offset:35840
	ds_read_b128 v[228:231], v189 offset:36864
	ds_read_b128 v[232:235], v189 offset:37888
	ds_read_b128 v[236:239], v189 offset:38912
	ds_read_b128 v[240:243], v189 offset:39936
	global_load_lds_dwordx4 v[252:253], off
	v_lshl_add_u64 v[252:253], s[12:13], 0, v[154:155]
	s_mov_b32 m0, s76
	s_nop 0
	global_load_lds_dwordx4 v[252:253], off
	s_waitcnt vmcnt(8)
	s_waitcnt lgkmcnt(0)
	s_waitcnt lgkmcnt(0)
	s_barrier
	s_setprio 1
	v_mfma_f32_16x16x32_bf16 v[142:145], v[18:21], v[212:215], v[142:145]
	v_mfma_f32_16x16x32_bf16 v[138:141], v[66:69], v[212:215], v[138:141]
	v_mfma_f32_16x16x32_bf16 v[126:129], v[18:21], v[220:223], v[126:129]
	v_mfma_f32_16x16x32_bf16 v[122:125], v[66:69], v[220:223], v[122:125]
	v_mfma_f32_16x16x32_bf16 v[110:113], v[18:21], v[228:231], v[110:113]
	v_mfma_f32_16x16x32_bf16 v[106:109], v[66:69], v[228:231], v[106:109]
	v_mfma_f32_16x16x32_bf16 v[94:97], v[18:21], v[236:239], v[94:97]
	v_mfma_f32_16x16x32_bf16 v[90:93], v[66:69], v[236:239], v[90:93]
	v_mfma_f32_16x16x32_bf16 v[142:145], v[22:25], v[216:219], v[142:145]
	v_mfma_f32_16x16x32_bf16 v[138:141], v[70:73], v[216:219], v[138:141]
	v_mfma_f32_16x16x32_bf16 v[126:129], v[22:25], v[224:227], v[126:129]
	v_mfma_f32_16x16x32_bf16 v[122:125], v[70:73], v[224:227], v[122:125]
	v_mfma_f32_16x16x32_bf16 v[110:113], v[22:25], v[232:235], v[110:113]
	v_mfma_f32_16x16x32_bf16 v[106:109], v[70:73], v[232:235], v[106:109]
	v_mfma_f32_16x16x32_bf16 v[94:97], v[22:25], v[240:243], v[94:97]
	v_mfma_f32_16x16x32_bf16 v[90:93], v[70:73], v[240:243], v[90:93]
	s_setprio 0
	s_setprio 1
	v_mfma_f32_16x16x32_bf16 v[134:137], v[146:149], v[212:215], v[134:137]
	v_mfma_f32_16x16x32_bf16 v[130:133], v[178:181], v[212:215], v[130:133]
	v_mfma_f32_16x16x32_bf16 v[118:121], v[146:149], v[220:223], v[118:121]
	v_mfma_f32_16x16x32_bf16 v[114:117], v[178:181], v[220:223], v[114:117]
	v_mfma_f32_16x16x32_bf16 v[102:105], v[146:149], v[228:231], v[102:105]
	v_mfma_f32_16x16x32_bf16 v[98:101], v[178:181], v[228:231], v[98:101]
	v_mfma_f32_16x16x32_bf16 v[86:89], v[146:149], v[236:239], v[86:89]
	v_mfma_f32_16x16x32_bf16 v[82:85], v[178:181], v[236:239], v[82:85]
	v_mfma_f32_16x16x32_bf16 v[134:137], v[174:177], v[216:219], v[134:137]
	v_mfma_f32_16x16x32_bf16 v[130:133], v[182:185], v[216:219], v[130:133]
	v_mfma_f32_16x16x32_bf16 v[118:121], v[174:177], v[224:227], v[118:121]
	v_mfma_f32_16x16x32_bf16 v[114:117], v[182:185], v[224:227], v[114:117]
	v_mfma_f32_16x16x32_bf16 v[102:105], v[174:177], v[232:235], v[102:105]
	v_mfma_f32_16x16x32_bf16 v[98:101], v[182:185], v[232:235], v[98:101]
	v_mfma_f32_16x16x32_bf16 v[86:89], v[174:177], v[240:243], v[86:89]
	v_mfma_f32_16x16x32_bf16 v[82:85], v[182:185], v[240:243], v[82:85]
	s_setprio 0
	s_barrier
; #define PG8_STAGE(bufoff, gbase, voff) do { _Pragma("unroll") for (int _i = 0; _i < 2; ++_i) \
;         __builtin_amdgcn_global_load_lds((const unsigned*)((const char*)(gbase) + (voff)[_i]), (PG8_LAS unsigned*)(lds + (bufoff) + ldsw + _i * 8192), 16, 0, 0); } while (0)
; #define PG8_LDA(dst, b, h) do { _Pragma("unroll") for (int m = 0; m < 4; ++m) _Pragma("unroll") for (int k = 0; k < 2; ++k) dst[m][k] = *(const PG8_LAS bf16x8*)(lds + PG8_SA(b, h) + aoff + m * 2048 + k * 1024); } while (0)
; #define PG8_MMA(ai, bj, At, Bt) do { __builtin_amdgcn_s_setprio(1); _Pragma("unroll") for (int m = 0; m < 4; ++m) _Pragma("unroll") for (int n = 0; n < 2; ++n) _Pragma("unroll") for (int k = 0; k < 2; ++k) \
;         acc[ai][bj][m][n] = __builtin_amdgcn_mfma_f32_16x16x32_bf16(Bt[n][k], At[m][k], acc[ai][bj][m][n], 0, 0, 0); __builtin_amdgcn_s_setprio(0); } while (0)
; #define PG8_WAIT_V(n) asm volatile("s_waitcnt vmcnt(" #n ")" ::: "memory")
; #define PG8_WAIT_L(n) do { asm volatile("s_waitcnt lgkmcnt(" #n ")" ::: "memory"); __builtin_amdgcn_s_waitcnt(0xC07F); } while (0)
; #define PG8_BAR __builtin_amdgcn_s_barrier()
; #define PG8_SCHED __builtin_amdgcn_sched_barrier(0)
; template <class Epi, class Sched, bool SEG3 = false>
; __device__ __forceinline__ void gemm_phase(PG8_LAS unsigned char* lds, const Gemm g, const Sched& S, const Epi& E) {
;     ...
;             PG8_LDA(At, 1, 1); PG8_STAGE(PG8_SB(1, 0), b3, voffB); PG8_STAGE(PG8_SB(1, 1), b3 + hsB, voffB); PG8_STAGE(PG8_SA(1, 0), a3, voffA);
;             PG8_WAIT_V(8); PG8_WAIT_L(0); PG8_BAR; if (cur.half != 0) { PG8_MMA(1, 0, At, B0); PG8_MMA(1, 1, At, B1); } PG8_BAR; PG8_SCHED;
;         }
	s_mov_b32 m0, s79
	v_lshl_add_u64 v[244:245], v[244:245], 0, s[30:31]
	s_add_u32 s10, s10, 0x40080
	ds_read_b128 v[212:215], v189 offset:49152
	ds_read_b128 v[216:219], v189 offset:50176
	ds_read_b128 v[220:223], v189 offset:51200
	ds_read_b128 v[224:227], v189 offset:52224
	ds_read_b128 v[228:231], v189 offset:53248
	ds_read_b128 v[232:235], v189 offset:54272
	ds_read_b128 v[236:239], v189 offset:55296
	ds_read_b128 v[240:243], v189 offset:56320
	global_load_lds_dwordx4 v[244:245], off
	v_lshl_add_u64 v[244:245], v[246:247], 0, s[30:31]
	s_mov_b32 m0, s80
	s_addc_u32 s11, s11, 0
	global_load_lds_dwordx4 v[244:245], off
	v_lshl_add_u64 v[244:245], s[10:11], 0, v[152:153]
	s_mov_b32 m0, s84
	s_nop 0
	global_load_lds_dwordx4 v[244:245], off
	v_lshl_add_u64 v[244:245], s[10:11], 0, v[156:157]
	s_mov_b32 m0, s85
	s_nop 0
	global_load_lds_dwordx4 v[244:245], off
	v_lshl_add_u64 v[244:245], v[248:249], 0, s[30:31]
	s_mov_b32 m0, s82
	s_nop 0
	global_load_lds_dwordx4 v[244:245], off
	v_lshl_add_u64 v[244:245], v[250:251], 0, s[30:31]
	s_mov_b32 m0, s83
	s_nop 0
	global_load_lds_dwordx4 v[244:245], off
	s_waitcnt vmcnt(8)
	s_waitcnt lgkmcnt(0)
	s_waitcnt lgkmcnt(0)
	s_barrier
	s_setprio 1
	v_mfma_f32_16x16x32_bf16 v[78:81], v[18:21], v[212:215], v[78:81]
	v_mfma_f32_16x16x32_bf16 v[62:65], v[18:21], v[220:223], v[62:65]
	v_mfma_f32_16x16x32_bf16 v[46:49], v[18:21], v[228:231], v[46:49]
	v_mfma_f32_16x16x32_bf16 v[10:13], v[18:21], v[236:239], v[10:13]
	v_mfma_f32_16x16x32_bf16 v[78:81], v[22:25], v[216:219], v[78:81]
	v_mfma_f32_16x16x32_bf16 v[74:77], v[66:69], v[212:215], v[74:77]
	v_mfma_f32_16x16x32_bf16 v[62:65], v[22:25], v[224:227], v[62:65]
	v_mfma_f32_16x16x32_bf16 v[58:61], v[66:69], v[220:223], v[58:61]
	v_mfma_f32_16x16x32_bf16 v[46:49], v[22:25], v[232:235], v[46:49]
	v_mfma_f32_16x16x32_bf16 v[42:45], v[66:69], v[228:231], v[42:45]
	v_mfma_f32_16x16x32_bf16 v[22:25], v[22:25], v[240:243], v[10:13]
	v_mfma_f32_16x16x32_bf16 v[10:13], v[66:69], v[236:239], v[14:17]
	v_mfma_f32_16x16x32_bf16 v[74:77], v[70:73], v[216:219], v[74:77]
	v_mfma_f32_16x16x32_bf16 v[58:61], v[70:73], v[224:227], v[58:61]
	v_mfma_f32_16x16x32_bf16 v[42:45], v[70:73], v[232:235], v[42:45]
	v_mfma_f32_16x16x32_bf16 v[18:21], v[70:73], v[240:243], v[10:13]
	s_setprio 0
	s_setprio 1
	v_mfma_f32_16x16x32_bf16 v[10:13], v[146:149], v[212:215], v[34:37]
	v_mfma_f32_16x16x32_bf16 v[70:73], v[174:177], v[216:219], v[10:13]
	v_mfma_f32_16x16x32_bf16 v[10:13], v[178:181], v[212:215], v[38:41]
	v_mfma_f32_16x16x32_bf16 v[66:69], v[182:185], v[216:219], v[10:13]
	v_mfma_f32_16x16x32_bf16 v[10:13], v[146:149], v[220:223], v[54:57]
	v_mfma_f32_16x16x32_bf16 v[54:57], v[174:177], v[224:227], v[10:13]
	v_mfma_f32_16x16x32_bf16 v[10:13], v[178:181], v[220:223], v[50:53]
	v_mfma_f32_16x16x32_bf16 v[50:53], v[182:185], v[224:227], v[10:13]
	v_mfma_f32_16x16x32_bf16 v[10:13], v[146:149], v[228:231], v[30:33]
	v_mfma_f32_16x16x32_bf16 v[30:33], v[174:177], v[232:235], v[10:13]
	v_mfma_f32_16x16x32_bf16 v[10:13], v[178:181], v[228:231], v[26:29]
	v_mfma_f32_16x16x32_bf16 v[6:9], v[146:149], v[236:239], v[6:9]
	v_mfma_f32_16x16x32_bf16 v[2:5], v[178:181], v[236:239], v[2:5]
	v_mfma_f32_16x16x32_bf16 v[26:29], v[182:185], v[232:235], v[10:13]
	v_mfma_f32_16x16x32_bf16 v[6:9], v[174:177], v[240:243], v[6:9]
	v_mfma_f32_16x16x32_bf16 v[2:5], v[182:185], v[240:243], v[2:5]
	s_setprio 0
	s_barrier
	s_add_u32 s8, s8, 0x100
	s_addc_u32 s9, s9, 0
	s_add_u32 s17, s17, 0x100
	s_addc_u32 s19, s19, 0
	s_cmp_ge_i32 s20, s77
	s_mov_b32 s10, s20
	s_cbranch_scc0 .LBB0_655
	s_and_b64 vcc, exec, s[36:37]
	s_cbranch_vccz .LBB0_658

;     __device__ __forceinline__ void operator()(AccT acc, const Unit& u, int wr, int wc, int fr, int fq) const {
;         const int col0 = u.pn * BM + wc * 32 + 8 * fq;
;         const bool uni = u.pm < NPROMPT / BM;
;         f32x4 sh[2][2] = {{(f32x4){0.f, 0.f, 0.f, 0.f}, (f32x4){0.f, 0.f, 0.f, 0.f}}, {(f32x4){0.f, 0.f, 0.f, 0.f}, (f32x4){0.f, 0.f, 0.f, 0.f}}};
;         if (uni) { const float* sw = SHW + (size_t)(u.pm >> 3) * NZT + col0;
; #pragma unroll
;             for (int bj = 0; bj < 2; ++bj) { sh[bj][0] = *(const f32x4*)(sw + bj * HALF); sh[bj][1] = *(const f32x4*)(sw + bj * HALF + 4); } }
;         float rs8[8];
; #pragma unroll
;         for (int r8 = 0; r8 < 8; ++r8) rs8[r8] = row_rs(SSQ, u.pm * BM + (r8 >> 2) * HALF + wr * 64 + (r8 & 3) * 16 + fr, fq);
;         const int side = (u.pn >= 6 && u.pn < 18) ? 1 : ((u.pn >= 22 && u.pn < 32) ? 2 : 0);
.LBB0_658:
	s_mov_b32 s98, 1
	s_cmpk_gt_i32 s6, 0x7f
	v_lshl_or_b32 v174, s18, 8, v186
	s_cselect_b64 s[8:9], -1, 0
	s_cmpk_lt_i32 s6, 0x80
	s_mov_b64 s[10:11], -1
	s_cbranch_scc1 .LBB0_660
	v_ashrrev_i32_e32 v175, 31, v174
	s_mov_b64 s[10:11], 0

; #define LAS __attribute__((address_space(3)))
; __device__ __forceinline__ void sample_merge_units(LAS unsigned char* lds, const bf16* OA, const bf16* YN, const bf16* HCG, const bf16* Wa, const bf16* Wb, const bf16* Wc,
;                                                    const bf16* Zg, bf16* MG, int tid, int vcu, int G) {
;     LAS float* P = (LAS float*)lds;
;     const int lane = tid & 63, w = __builtin_amdgcn_readfirstlane(tid >> 6), qq = lane & 15, q4 = lane >> 4;
;     for (int un = vcu; un < 256; un += G) {
;         const int rt = un >> 4, cs = un & 15, pn = cs >> 2, wc = cs & 3; const size_t row0 = (size_t)NPROMPT + 16 * rt;
;         __syncthreads();
; #pragma unroll
;         for (int pr = 0; pr < 3; ++pr) {
;             const bf16* Aop = pr == 0 ? OA : (pr == 1 ? YN : HCG); const bf16* Bt = pr == 0 ? Wa : (pr == 1 ? Wb : Wc); const int K = pr == 0 ? 512 : DM;
;             const int kper = K >> 3, kbeg = w * kper;
;             f32x4 acc[4];
; #pragma unroll
;             for (int ct = 0; ct < 4; ++ct) acc[ct] = (f32x4){0.f, 0.f, 0.f, 0.f};
;             const bf16* ap = Aop + (row0 + qq) * (size_t)DM + kbeg + 8 * q4;
;             const bf16* bp = Bt + (size_t)(256 * pn + 32 * wc + qq) * DM + kbeg + 8 * q4;
; #pragma unroll
;             for (int k0 = 0; k0 < kper; k0 += 32) {
;                 const bf16x8 af = *(const bf16x8*)(ap + k0);
; #pragma unroll
;                 for (int ct = 0; ct < 4; ++ct) { const bf16x8 bf = *(const bf16x8*)(bp + (size_t)(128 * (ct >> 1) + 16 * (ct & 1)) * DM + k0);
;                     acc[ct] = __builtin_amdgcn_mfma_f32_16x16x32_bf16(bf, af, acc[ct], 0, 0, 0); } }
; #pragma unroll
;             for (int ct = 0; ct < 4; ++ct)
; #pragma unroll
;                 for (int i = 0; i < 4; ++i) P[pr * 8192 + ((w * 4 + ct) * 4 + i) * 64 + lane] = acc[ct][i];
; __global__ void __launch_bounds__(NWAVES * 64, 2) fwd(Args args_unused) {
;     ...
;         if (IN(pb + 6)) {
;             PH_PTRS PH_LAYER
;             sample_merge_units(lds, OA, YN, HCG, (const bf16*)(wl + WL_A), (const bf16*)(wl + WL_B), (const bf16*)(wl + WL_C), Z, MG, tid, vcu, G);
.LBB0_1984:
	s_mov_b32 s98, 0
	s_cmp_lt_i32 s84, 10
	s_cselect_b64 s[0:1], -1, 0
	s_and_b64 s[0:1], s[0:1], s[4:5]
	s_andn2_b64 vcc, exec, s[0:1]
	s_cbranch_vccnz .LBB0_2108
	s_mov_b64 s[0:1], s[82:83]
	s_load_dwordx2 s[6:7], s[0:1], 0x148
	s_mov_b32 s16, 0
	s_mov_b32 s3, s2
	s_load_dword s33, s[82:83], 0x168
	s_waitcnt lgkmcnt(0)
	s_add_u32 s0, s6, 0x19100000
	s_addc_u32 s1, s7, 0
	s_add_u32 s4, s6, 0x1d200000
	s_addc_u32 s5, s7, 0
	s_add_u32 s34, s6, 0x5fb00000
	s_addc_u32 s35, s7, 0
	s_add_u32 s36, s6, 0x75e00000
	s_addc_u32 s37, s7, 0
	s_add_u32 s38, s6, 0x79f00000
	s_addc_u32 s39, s7, 0
	s_add_u32 s40, s6, 0x4400000
	s_addc_u32 s41, s7, 0
	s_add_u32 s42, s6, 0x2c00000
	s_addc_u32 s43, s7, 0
	s_add_u32 s44, s6, 0x2e00000
	v_readlane_b32 s10, v254, 3
	v_mov_b32_e32 v2, v0
	s_addc_u32 s45, s7, 0
	s_cmpk_gt_i32 s10, 0xff
	v_readfirstlane_b32 s8, v2
	s_cbranch_scc1 .LBB0_1988
	v_and_b32_e32 v3, 63, v2
	v_lshl_add_u32 v18, v3, 2, s16
	v_ashrrev_i32_e32 v3, 7, v2
	s_ashr_i32 s11, s8, 6
	v_ashrrev_i32_e32 v6, 1, v2
	s_add_i32 s9, s16, 0x10000
	v_lshlrev_b32_e32 v16, 10, v3
	s_andn2_b32 s8, s8, 63
	s_lshl_b32 s19, s11, 12
	v_and_b32_e32 v20, 0xffffff80, v6
	v_lshlrev_b32_e32 v6, 4, v3
	v_add_u32_e32 v3, s9, v16
	s_ashr_i32 s9, s8, 31
	v_lshrrev_b32_e32 v5, 3, v2
	s_or_b32 s20, s19, 0xc00
	s_lshl_b64 s[8:9], s[8:9], 1
	v_and_b32_e32 v1, 15, v2
	v_lshrrev_b32_e32 v4, 1, v2
	v_and_b32_e32 v5, 14, v5
	s_add_u32 s12, s36, s8
	v_and_or_b32 v4, v4, 48, v1
	v_and_or_b32 v21, v6, 16, v5
	v_lshlrev_b32_e32 v5, 5, v2
	s_addc_u32 s13, s37, s9
	v_and_b32_e32 v17, 0x200, v5
	v_lshlrev_b32_e32 v19, 2, v4
	s_add_u32 s8, s40, s8
	v_add3_u32 v22, v3, v17, v19
	v_and_b32_e32 v2, 48, v2
	v_mov_b32_e32 v3, 0
	s_addc_u32 s9, s41, s9
	v_lshl_add_u64 v[6:7], s[8:9], 0, v[2:3]
	s_lshl_b32 s8, s11, 7
	s_ashr_i32 s9, s8, 31
	s_or_b32 s21, s19, 0x100
	s_or_b32 s22, s19, 0x200
	s_or_b32 s23, s19, 0x300
	s_or_b32 s24, s19, 0x400
	s_or_b32 s25, s19, 0x500
	s_or_b32 s26, s19, 0x600
	s_or_b32 s27, s19, 0x700
	s_or_b32 s28, s19, 0x800
	s_or_b32 s29, s19, 0x900
	s_or_b32 s30, s19, 0xa00
	s_or_b32 s31, s19, 0xb00
	s_or_b32 s46, s19, 0xd00
	s_or_b32 s47, s19, 0xe00
	s_or_b32 s48, s19, 0xf00
	s_lshl_b64 s[8:9], s[8:9], 1
	v_lshl_add_u64 v[4:5], s[12:13], 0, v[2:3]
	s_add_u32 s12, s34, s8
	s_addc_u32 s13, s35, s9
	v_lshl_add_u64 v[8:9], s[12:13], 0, v[2:3]
	s_add_u32 s12, s42, s8
	s_addc_u32 s13, s43, s9
	v_lshl_add_u64 v[10:11], s[12:13], 0, v[2:3]
	s_add_u32 s12, s38, s8
	s_addc_u32 s13, s39, s9
	s_add_u32 s8, s44, s8
	s_addc_u32 s9, s45, s9
	v_lshl_add_u64 v[14:15], s[8:9], 0, v[2:3]
	s_add_i32 s8, s16, 0x11000
	v_add_u32_e32 v24, s8, v16
	s_add_i32 s8, s16, 0x12000
	s_waitcnt vmcnt(0)
	v_add_u32_e32 v25, s8, v16
	s_add_i32 s8, s16, 0x13000
	v_add_u32_e32 v26, s8, v16
	s_add_i32 s8, s16, 0x14000
	v_add_u32_e32 v27, s8, v16
	s_add_i32 s8, s16, 0x15000
	v_add_u32_e32 v28, s8, v16
	s_add_i32 s8, s16, 0x16000
	v_add_u32_e32 v29, s8, v16
	s_add_i32 s8, s16, 0x17000
	v_lshl_add_u64 v[12:13], s[12:13], 0, v[2:3]
	v_add_u32_e32 v2, 0x10000, v18
	v_add_u32_e32 v23, s16, v16
	v_add_u32_e32 v16, s8, v16
	v_add3_u32 v23, v23, v17, v19
	v_add3_u32 v24, v24, v17, v19
	v_add3_u32 v25, v25, v17, v19
	v_add3_u32 v26, v26, v17, v19
	v_add3_u32 v27, v27, v17, v19
	v_add3_u32 v28, v28, v17, v19
	v_add3_u32 v29, v29, v17, v19
	v_add3_u32 v30, v16, v17, v19
	s_mov_b32 s11, 0x8000
	v_or_b32_e32 v16, 0x8000, v1
	v_mov_b32_e32 v17, v3
	s_lshl_b32 s12, s10, 5
	s_lshl_b32 s13, s33, 5
	s_lshl_b32 s14, s10, 6
	s_lshl_b32 s15, s33, 6
	s_mov_b32 s17, 0x40000
	s_mov_b32 s18, 0x48000
	v_add_u32_e32 v31, s19, v18
	v_add_u32_e32 v32, s19, v2
	v_add_u32_e32 v33, s21, v2
	v_add_u32_e32 v34, s22, v2
	v_add_u32_e32 v35, s23, v2
	v_add_u32_e32 v36, s24, v2
	v_add_u32_e32 v37, s25, v2
	v_add_u32_e32 v38, s26, v2
	v_add_u32_e32 v39, s27, v2
	v_add_u32_e32 v40, s28, v2
	v_add_u32_e32 v41, s29, v2
	v_add_u32_e32 v42, s30, v2
	v_add_u32_e32 v43, s31, v2
	v_add_u32_e32 v44, s20, v2
	v_add_u32_e32 v45, s46, v2
	v_add_u32_e32 v46, s47, v2
	v_add_u32_e32 v47, s48, v2
	s_movk_i32 s19, 0xfe

; #define PG8_STAGE(bufoff, gbase, voff) do { _Pragma("unroll") for (int _i = 0; _i < 2; ++_i) \
;         __builtin_amdgcn_global_load_lds((const unsigned*)((const char*)(gbase) + (voff)[_i]), (PG8_LAS unsigned*)(lds + (bufoff) + ldsw + _i * 8192), 16, 0, 0); } while (0)
; #define PG8_LDA(dst, b, h) do { _Pragma("unroll") for (int m = 0; m < 4; ++m) _Pragma("unroll") for (int k = 0; k < 2; ++k) dst[m][k] = *(const PG8_LAS bf16x8*)(lds + PG8_SA(b, h) + aoff + m * 2048 + k * 1024); } while (0)
; #define PG8_LDB(dst, b, h) do { _Pragma("unroll") for (int n = 0; n < 2; ++n) _Pragma("unroll") for (int k = 0; k < 2; ++k) dst[n][k] = *(const PG8_LAS bf16x8*)(lds + PG8_SB(b, h) + boff + n * 2048 + k * 1024); } while (0)
; #define PG8_MMA(ai, bj, At, Bt) do { __builtin_amdgcn_s_setprio(1); _Pragma("unroll") for (int m = 0; m < 4; ++m) _Pragma("unroll") for (int n = 0; n < 2; ++n) _Pragma("unroll") for (int k = 0; k < 2; ++k) \
;         acc[ai][bj][m][n] = __builtin_amdgcn_mfma_f32_16x16x32_bf16(Bt[n][k], At[m][k], acc[ai][bj][m][n], 0, 0, 0); __builtin_amdgcn_s_setprio(0); } while (0)
; #define PG8_WAIT_V(n) asm volatile("s_waitcnt vmcnt(" #n ")" ::: "memory")
; #define PG8_BAR __builtin_amdgcn_s_barrier()
; template <class Epi, class Sched, bool SEG3 = false>
; __device__ __forceinline__ void gemm_phase(PG8_LAS unsigned char* lds, const Gemm g, const Sched& S, const Epi& E) {
;     ...
;         for (int t = 0; t < ntc; t += 2) {
;             bf16x8 At[4][2], B0[2][2], B1[2][2];
;             const bool last = (t == ntc - 2);
;             const char* a1 = cA + (size_t)(t + 1) * kstep;
;             const char* a2 = last ? nA : cA + (size_t)(t + 2) * kstep; const char* b2 = last ? nB : cB + (size_t)(t + 2) * kstep;
;             const char* a3 = a2 + kstep; const char* b3 = b2 + kstep;
;             PG8_LDB(B0, 0, 0); PG8_LDB(B1, 0, 1); PG8_SCHED; PG8_LDA(At, 0, 0); PG8_STAGE(PG8_SA(1, 1), a1 + hsA, voffA);
;             PG8_WAIT_V(8); PG8_WAIT_L(0); PG8_BAR; if (cur.half != 1) { PG8_MMA(0, 0, At, B0); PG8_MMA(0, 1, At, B1); } PG8_BAR; PG8_SCHED;
;             PG8_LDA(At, 0, 1); PG8_STAGE(PG8_SB(0, 0), b2, voffB); PG8_STAGE(PG8_SB(0, 1), b2 + hsB, voffB); PG8_STAGE(PG8_SA(0, 0), a2, voffA);
;             PG8_WAIT_V(8); PG8_WAIT_L(0); PG8_BAR; if (cur.half != 0) { PG8_MMA(1, 0, At, B0); PG8_MMA(1, 1, At, B1); } PG8_BAR; PG8_SCHED;
.LBB0_2007:
	ds_read_b128 v[124:127], v231
	ds_read_b128 v[132:135], v231 offset:1024
	ds_read_b128 v[140:143], v231 offset:2048
	ds_read_b128 v[144:147], v231 offset:3072
	ds_read_b128 v[148:151], v232
	ds_read_b128 v[152:155], v232 offset:1024
	ds_read_b128 v[156:159], v232 offset:2048
	ds_read_b128 v[160:163], v232 offset:3072
	s_add_i32 s65, s28, 2
	s_add_u32 s29, s6, 0xfffc0080
	s_addc_u32 s30, s7, -1
	s_cmp_eq_u32 s17, s28
	s_cselect_b32 s28, s22, s19
	s_cselect_b32 s31, s21, s30
	s_cselect_b32 s30, s20, s29
	s_cselect_b32 s29, s23, s27
	v_lshl_add_u64 v[98:99], s[6:7], 0, v[206:207]
	s_add_i32 m0, s50, 0xc000
	ds_read_b128 v[164:167], v233
	ds_read_b128 v[168:171], v233 offset:1024
	ds_read_b128 v[172:175], v233 offset:2048
	ds_read_b128 v[176:179], v233 offset:3072
	ds_read_b128 v[180:183], v233 offset:4096
	ds_read_b128 v[184:187], v233 offset:5120
	ds_read_b128 v[188:191], v233 offset:6144
	ds_read_b128 v[192:195], v233 offset:7168
	global_load_lds_dwordx4 v[98:99], off
	v_lshl_add_u64 v[98:99], s[6:7], 0, v[208:209]
	s_add_i32 m0, s50, 0xe000
	s_nop 0
	global_load_lds_dwordx4 v[98:99], off
	s_cmp_lg_u32 s98, 0
	s_cbranch_scc1 .Lfi_a_2
	s_waitcnt vmcnt(8)
.Lfi_a_2:
	s_waitcnt lgkmcnt(0)
	s_barrier
	s_setprio 1
	v_mfma_f32_16x16x32_bf16 v[136:139], v[124:127], v[164:167], v[136:139]
	v_mfma_f32_16x16x32_bf16 v[128:131], v[140:143], v[164:167], v[128:131]
	v_mfma_f32_16x16x32_bf16 v[112:115], v[124:127], v[172:175], v[112:115]
	v_mfma_f32_16x16x32_bf16 v[108:111], v[140:143], v[172:175], v[108:111]
	v_mfma_f32_16x16x32_bf16 v[94:97], v[124:127], v[180:183], v[94:97]
	v_mfma_f32_16x16x32_bf16 v[90:93], v[140:143], v[180:183], v[90:93]
	v_mfma_f32_16x16x32_bf16 v[78:81], v[124:127], v[188:191], v[78:81]
	v_mfma_f32_16x16x32_bf16 v[74:77], v[140:143], v[188:191], v[74:77]
	v_mfma_f32_16x16x32_bf16 v[136:139], v[132:135], v[168:171], v[136:139]
	v_mfma_f32_16x16x32_bf16 v[128:131], v[144:147], v[168:171], v[128:131]
	v_mfma_f32_16x16x32_bf16 v[112:115], v[132:135], v[176:179], v[112:115]
	v_mfma_f32_16x16x32_bf16 v[108:111], v[144:147], v[176:179], v[108:111]
	v_mfma_f32_16x16x32_bf16 v[94:97], v[132:135], v[184:187], v[94:97]
	v_mfma_f32_16x16x32_bf16 v[90:93], v[144:147], v[184:187], v[90:93]
	v_mfma_f32_16x16x32_bf16 v[78:81], v[132:135], v[192:195], v[78:81]
	v_mfma_f32_16x16x32_bf16 v[74:77], v[144:147], v[192:195], v[74:77]
	s_setprio 0
	s_setprio 1
	v_mfma_f32_16x16x32_bf16 v[120:123], v[148:151], v[164:167], v[120:123]
	v_mfma_f32_16x16x32_bf16 v[116:119], v[156:159], v[164:167], v[116:119]
	v_mfma_f32_16x16x32_bf16 v[104:107], v[148:151], v[172:175], v[104:107]
	v_mfma_f32_16x16x32_bf16 v[98:101], v[156:159], v[172:175], v[100:103]
	v_mfma_f32_16x16x32_bf16 v[86:89], v[148:151], v[180:183], v[86:89]
	v_mfma_f32_16x16x32_bf16 v[82:85], v[156:159], v[180:183], v[82:85]
	v_mfma_f32_16x16x32_bf16 v[70:73], v[148:151], v[188:191], v[70:73]
	v_mfma_f32_16x16x32_bf16 v[66:69], v[156:159], v[188:191], v[66:69]
	v_mfma_f32_16x16x32_bf16 v[120:123], v[152:155], v[168:171], v[120:123]
	v_mfma_f32_16x16x32_bf16 v[116:119], v[160:163], v[168:171], v[116:119]
	v_mfma_f32_16x16x32_bf16 v[104:107], v[152:155], v[176:179], v[104:107]
	v_mfma_f32_16x16x32_bf16 v[98:101], v[160:163], v[176:179], v[98:101]
	v_mfma_f32_16x16x32_bf16 v[86:89], v[152:155], v[184:187], v[86:89]
	v_mfma_f32_16x16x32_bf16 v[82:85], v[160:163], v[184:187], v[82:85]
	v_mfma_f32_16x16x32_bf16 v[70:73], v[152:155], v[192:195], v[70:73]
	v_mfma_f32_16x16x32_bf16 v[66:69], v[160:163], v[192:195], v[66:69]
	s_setprio 0
	s_barrier
	s_mov_b32 m0, s46
	v_lshl_add_u64 v[214:215], s[28:29], 0, v[198:199]
	s_add_u32 s66, s28, 0x40000
	ds_read_b128 v[164:167], v233 offset:16384
	ds_read_b128 v[168:171], v233 offset:17408
	ds_read_b128 v[172:175], v233 offset:18432
	ds_read_b128 v[176:179], v233 offset:19456
	ds_read_b128 v[180:183], v233 offset:20480
	ds_read_b128 v[184:187], v233 offset:21504
	ds_read_b128 v[188:191], v233 offset:22528
	ds_read_b128 v[192:195], v233 offset:23552
	global_load_lds_dwordx4 v[214:215], off
	v_lshl_add_u64 v[216:217], s[28:29], 0, v[202:203]
	s_mov_b32 m0, s47
	s_addc_u32 s67, s29, 0
	global_load_lds_dwordx4 v[216:217], off
	v_lshl_add_u64 v[102:103], s[66:67], 0, v[198:199]
	s_mov_b32 m0, s48
	v_lshl_add_u64 v[218:219], s[30:31], 0, v[196:197]
	global_load_lds_dwordx4 v[102:103], off
	v_lshl_add_u64 v[102:103], s[66:67], 0, v[202:203]
	s_mov_b32 m0, s49
	v_lshl_add_u64 v[220:221], s[30:31], 0, v[200:201]
	global_load_lds_dwordx4 v[102:103], off
	s_mov_b32 m0, s50
	s_nop 0
	global_load_lds_dwordx4 v[218:219], off
	s_mov_b32 m0, s51
	s_nop 0
	global_load_lds_dwordx4 v[220:221], off
	s_cmp_lg_u32 s98, 0
	s_cbranch_scc1 .Lfi_b_2
	s_waitcnt vmcnt(8)
; #define PG8_STAGE(bufoff, gbase, voff) do { _Pragma("unroll") for (int _i = 0; _i < 2; ++_i) \
;         __builtin_amdgcn_global_load_lds((const unsigned*)((const char*)(gbase) + (voff)[_i]), (PG8_LAS unsigned*)(lds + (bufoff) + ldsw + _i * 8192), 16, 0, 0); } while (0)
; #define PG8_LDA(dst, b, h) do { _Pragma("unroll") for (int m = 0; m < 4; ++m) _Pragma("unroll") for (int k = 0; k < 2; ++k) dst[m][k] = *(const PG8_LAS bf16x8*)(lds + PG8_SA(b, h) + aoff + m * 2048 + k * 1024); } while (0)
; #define PG8_LDB(dst, b, h) do { _Pragma("unroll") for (int n = 0; n < 2; ++n) _Pragma("unroll") for (int k = 0; k < 2; ++k) dst[n][k] = *(const PG8_LAS bf16x8*)(lds + PG8_SB(b, h) + boff + n * 2048 + k * 1024); } while (0)
; #define PG8_MMA(ai, bj, At, Bt) do { __builtin_amdgcn_s_setprio(1); _Pragma("unroll") for (int m = 0; m < 4; ++m) _Pragma("unroll") for (int n = 0; n < 2; ++n) _Pragma("unroll") for (int k = 0; k < 2; ++k) \
;         acc[ai][bj][m][n] = __builtin_amdgcn_mfma_f32_16x16x32_bf16(Bt[n][k], At[m][k], acc[ai][bj][m][n], 0, 0, 0); __builtin_amdgcn_s_setprio(0); } while (0)
; #define PG8_WAIT_V(n) asm volatile("s_waitcnt vmcnt(" #n ")" ::: "memory")
; #define PG8_WAIT_L(n) do { asm volatile("s_waitcnt lgkmcnt(" #n ")" ::: "memory"); __builtin_amdgcn_s_waitcnt(0xC07F); } while (0)
; #define PG8_BAR __builtin_amdgcn_s_barrier()
; #define PG8_SCHED __builtin_amdgcn_sched_barrier(0)
; template <class Epi, class Sched, bool SEG3 = false>
; __device__ __forceinline__ void gemm_phase(PG8_LAS unsigned char* lds, const Gemm g, const Sched& S, const Epi& E) {
;     ...
;             PG8_WAIT_V(8); PG8_WAIT_L(0); PG8_BAR; if (cur.half != 0) { PG8_MMA(1, 0, At, B0); PG8_MMA(1, 1, At, B1); } PG8_BAR; PG8_SCHED;
;             PG8_LDB(B0, 1, 0); PG8_LDB(B1, 1, 1); PG8_SCHED; PG8_LDA(At, 1, 0); PG8_STAGE(PG8_SA(0, 1), a2 + hsA, voffA);
;             PG8_WAIT_V(8); PG8_WAIT_L(0); PG8_BAR; if (cur.half != 1) { PG8_MMA(0, 0, At, B0); PG8_MMA(0, 1, At, B1); } PG8_BAR; PG8_SCHED;
;             PG8_LDA(At, 1, 1); PG8_STAGE(PG8_SB(1, 0), b3, voffB); PG8_STAGE(PG8_SB(1, 1), b3 + hsB, voffB); PG8_STAGE(PG8_SA(1, 0), a3, voffA);
.Lfi_b_2:
	s_mov_b32 s98, 0
	s_waitcnt lgkmcnt(0)
	s_barrier
	s_setprio 1
	v_mfma_f32_16x16x32_bf16 v[62:65], v[124:127], v[164:167], v[62:65]
	v_mfma_f32_16x16x32_bf16 v[58:61], v[140:143], v[164:167], v[58:61]
	v_mfma_f32_16x16x32_bf16 v[46:49], v[124:127], v[172:175], v[46:49]
	v_mfma_f32_16x16x32_bf16 v[42:45], v[140:143], v[172:175], v[42:45]
	v_mfma_f32_16x16x32_bf16 v[30:33], v[124:127], v[180:183], v[30:33]
	v_mfma_f32_16x16x32_bf16 v[26:29], v[140:143], v[180:183], v[26:29]
	v_mfma_f32_16x16x32_bf16 v[14:17], v[124:127], v[188:191], v[14:17]
	v_mfma_f32_16x16x32_bf16 v[10:13], v[140:143], v[188:191], v[10:13]
	v_mfma_f32_16x16x32_bf16 v[62:65], v[132:135], v[168:171], v[62:65]
	v_mfma_f32_16x16x32_bf16 v[58:61], v[144:147], v[168:171], v[58:61]
	v_mfma_f32_16x16x32_bf16 v[46:49], v[132:135], v[176:179], v[46:49]
	v_mfma_f32_16x16x32_bf16 v[42:45], v[144:147], v[176:179], v[42:45]
	v_mfma_f32_16x16x32_bf16 v[30:33], v[132:135], v[184:187], v[30:33]
	v_mfma_f32_16x16x32_bf16 v[26:29], v[144:147], v[184:187], v[26:29]
	v_mfma_f32_16x16x32_bf16 v[14:17], v[132:135], v[192:195], v[14:17]
	v_mfma_f32_16x16x32_bf16 v[10:13], v[144:147], v[192:195], v[10:13]
	s_setprio 0
	s_setprio 1
	v_mfma_f32_16x16x32_bf16 v[54:57], v[148:151], v[164:167], v[54:57]
	v_mfma_f32_16x16x32_bf16 v[50:53], v[156:159], v[164:167], v[50:53]
	v_mfma_f32_16x16x32_bf16 v[38:41], v[148:151], v[172:175], v[38:41]
	v_mfma_f32_16x16x32_bf16 v[34:37], v[156:159], v[172:175], v[34:37]
	v_mfma_f32_16x16x32_bf16 v[22:25], v[148:151], v[180:183], v[22:25]
	v_mfma_f32_16x16x32_bf16 v[18:21], v[156:159], v[180:183], v[18:21]
	v_mfma_f32_16x16x32_bf16 v[6:9], v[148:151], v[188:191], v[6:9]
	v_mfma_f32_16x16x32_bf16 v[2:5], v[156:159], v[188:191], v[2:5]
	v_mfma_f32_16x16x32_bf16 v[54:57], v[152:155], v[168:171], v[54:57]
	v_mfma_f32_16x16x32_bf16 v[50:53], v[160:163], v[168:171], v[50:53]
	v_mfma_f32_16x16x32_bf16 v[38:41], v[152:155], v[176:179], v[38:41]
	v_mfma_f32_16x16x32_bf16 v[34:37], v[160:163], v[176:179], v[34:37]
	v_mfma_f32_16x16x32_bf16 v[22:25], v[152:155], v[184:187], v[22:25]
	v_mfma_f32_16x16x32_bf16 v[18:21], v[160:163], v[184:187], v[18:21]
	v_mfma_f32_16x16x32_bf16 v[6:9], v[152:155], v[192:195], v[6:9]
	v_mfma_f32_16x16x32_bf16 v[2:5], v[160:163], v[192:195], v[2:5]
	s_setprio 0
	s_barrier
	ds_read_b128 v[124:127], v234
	ds_read_b128 v[132:135], v234 offset:1024
	ds_read_b128 v[140:143], v234 offset:2048
	ds_read_b128 v[144:147], v234 offset:3072
	ds_read_b128 v[148:151], v235
	ds_read_b128 v[152:155], v235 offset:1024
	ds_read_b128 v[156:159], v235 offset:2048
	ds_read_b128 v[160:163], v235 offset:3072
	s_add_u32 s30, s30, 0x40000
	s_addc_u32 s31, s31, 0
	s_mov_b32 m0, s52
	v_lshl_add_u64 v[102:103], s[30:31], 0, v[196:197]
	ds_read_b128 v[164:167], v233 offset:32768
	ds_read_b128 v[168:171], v233 offset:33792
	ds_read_b128 v[172:175], v233 offset:34816
	ds_read_b128 v[176:179], v233 offset:35840
	ds_read_b128 v[180:183], v233 offset:36864
	ds_read_b128 v[184:187], v233 offset:37888
	ds_read_b128 v[188:191], v233 offset:38912
	ds_read_b128 v[192:195], v233 offset:39936
	global_load_lds_dwordx4 v[102:103], off
	v_lshl_add_u64 v[102:103], s[30:31], 0, v[200:201]
	s_mov_b32 m0, s53
	s_nop 0
	global_load_lds_dwordx4 v[102:103], off
	s_waitcnt vmcnt(8)
	s_waitcnt lgkmcnt(0)
	s_waitcnt lgkmcnt(0)
	s_barrier
	s_setprio 1
	v_mfma_f32_16x16x32_bf16 v[136:139], v[124:127], v[164:167], v[136:139]
	v_mfma_f32_16x16x32_bf16 v[128:131], v[140:143], v[164:167], v[128:131]
	v_mfma_f32_16x16x32_bf16 v[112:115], v[124:127], v[172:175], v[112:115]
	v_mfma_f32_16x16x32_bf16 v[108:111], v[140:143], v[172:175], v[108:111]
	v_mfma_f32_16x16x32_bf16 v[94:97], v[124:127], v[180:183], v[94:97]
	v_mfma_f32_16x16x32_bf16 v[90:93], v[140:143], v[180:183], v[90:93]
	v_mfma_f32_16x16x32_bf16 v[78:81], v[124:127], v[188:191], v[78:81]
	v_mfma_f32_16x16x32_bf16 v[74:77], v[140:143], v[188:191], v[74:77]
	v_mfma_f32_16x16x32_bf16 v[136:139], v[132:135], v[168:171], v[136:139]
	v_mfma_f32_16x16x32_bf16 v[128:131], v[144:147], v[168:171], v[128:131]
	v_mfma_f32_16x16x32_bf16 v[112:115], v[132:135], v[176:179], v[112:115]
	v_mfma_f32_16x16x32_bf16 v[108:111], v[144:147], v[176:179], v[108:111]
	v_mfma_f32_16x16x32_bf16 v[94:97], v[132:135], v[184:187], v[94:97]
	v_mfma_f32_16x16x32_bf16 v[90:93], v[144:147], v[184:187], v[90:93]
	v_mfma_f32_16x16x32_bf16 v[78:81], v[132:135], v[192:195], v[78:81]
	v_mfma_f32_16x16x32_bf16 v[74:77], v[144:147], v[192:195], v[74:77]
	s_setprio 0
	s_setprio 1
	v_mfma_f32_16x16x32_bf16 v[120:123], v[148:151], v[164:167], v[120:123]
	v_mfma_f32_16x16x32_bf16 v[116:119], v[156:159], v[164:167], v[116:119]
	v_mfma_f32_16x16x32_bf16 v[102:105], v[148:151], v[172:175], v[104:107]
	v_mfma_f32_16x16x32_bf16 v[98:101], v[156:159], v[172:175], v[98:101]
	v_mfma_f32_16x16x32_bf16 v[86:89], v[148:151], v[180:183], v[86:89]
	v_mfma_f32_16x16x32_bf16 v[82:85], v[156:159], v[180:183], v[82:85]
	v_mfma_f32_16x16x32_bf16 v[70:73], v[148:151], v[188:191], v[70:73]
	v_mfma_f32_16x16x32_bf16 v[66:69], v[156:159], v[188:191], v[66:69]
	v_mfma_f32_16x16x32_bf16 v[120:123], v[152:155], v[168:171], v[120:123]
	v_mfma_f32_16x16x32_bf16 v[116:119], v[160:163], v[168:171], v[116:119]
	v_mfma_f32_16x16x32_bf16 v[104:107], v[152:155], v[176:179], v[102:105]
	v_mfma_f32_16x16x32_bf16 v[100:103], v[160:163], v[176:179], v[98:101]
	v_mfma_f32_16x16x32_bf16 v[86:89], v[152:155], v[184:187], v[86:89]
	v_mfma_f32_16x16x32_bf16 v[82:85], v[160:163], v[184:187], v[82:85]
	v_mfma_f32_16x16x32_bf16 v[70:73], v[152:155], v[192:195], v[70:73]
	v_mfma_f32_16x16x32_bf16 v[66:69], v[160:163], v[192:195], v[66:69]
	s_setprio 0
	s_barrier
; #define PG8_STAGE(bufoff, gbase, voff) do { _Pragma("unroll") for (int _i = 0; _i < 2; ++_i) \
;         __builtin_amdgcn_global_load_lds((const unsigned*)((const char*)(gbase) + (voff)[_i]), (PG8_LAS unsigned*)(lds + (bufoff) + ldsw + _i * 8192), 16, 0, 0); } while (0)
; #define PG8_LDA(dst, b, h) do { _Pragma("unroll") for (int m = 0; m < 4; ++m) _Pragma("unroll") for (int k = 0; k < 2; ++k) dst[m][k] = *(const PG8_LAS bf16x8*)(lds + PG8_SA(b, h) + aoff + m * 2048 + k * 1024); } while (0)
; #define PG8_MMA(ai, bj, At, Bt) do { __builtin_amdgcn_s_setprio(1); _Pragma("unroll") for (int m = 0; m < 4; ++m) _Pragma("unroll") for (int n = 0; n < 2; ++n) _Pragma("unroll") for (int k = 0; k < 2; ++k) \
;         acc[ai][bj][m][n] = __builtin_amdgcn_mfma_f32_16x16x32_bf16(Bt[n][k], At[m][k], acc[ai][bj][m][n], 0, 0, 0); __builtin_amdgcn_s_setprio(0); } while (0)
; #define PG8_WAIT_V(n) asm volatile("s_waitcnt vmcnt(" #n ")" ::: "memory")
; #define PG8_WAIT_L(n) do { asm volatile("s_waitcnt lgkmcnt(" #n ")" ::: "memory"); __builtin_amdgcn_s_waitcnt(0xC07F); } while (0)
; #define PG8_BAR __builtin_amdgcn_s_barrier()
; #define PG8_SCHED __builtin_amdgcn_sched_barrier(0)
; template <class Epi, class Sched, bool SEG3 = false>
; __device__ __forceinline__ void gemm_phase(PG8_LAS unsigned char* lds, const Gemm g, const Sched& S, const Epi& E) {
;     ...
;             PG8_LDA(At, 1, 1); PG8_STAGE(PG8_SB(1, 0), b3, voffB); PG8_STAGE(PG8_SB(1, 1), b3 + hsB, voffB); PG8_STAGE(PG8_SA(1, 0), a3, voffA);
;             PG8_WAIT_V(8); PG8_WAIT_L(0); PG8_BAR; if (cur.half != 0) { PG8_MMA(1, 0, At, B0); PG8_MMA(1, 1, At, B1); } PG8_BAR; PG8_SCHED;
;         }
	s_mov_b32 m0, s55
	v_lshl_add_u64 v[98:99], v[214:215], 0, s[12:13]
	s_add_u32 s28, s28, 0x40080
	ds_read_b128 v[164:167], v233 offset:49152
	ds_read_b128 v[168:171], v233 offset:50176
	ds_read_b128 v[172:175], v233 offset:51200
	ds_read_b128 v[176:179], v233 offset:52224
	ds_read_b128 v[180:183], v233 offset:53248
	ds_read_b128 v[184:187], v233 offset:54272
	ds_read_b128 v[188:191], v233 offset:55296
	ds_read_b128 v[192:195], v233 offset:56320
	global_load_lds_dwordx4 v[98:99], off
	v_lshl_add_u64 v[98:99], v[216:217], 0, s[12:13]
	s_mov_b32 m0, s56
	s_addc_u32 s29, s29, 0
	global_load_lds_dwordx4 v[98:99], off
	v_lshl_add_u64 v[98:99], s[28:29], 0, v[198:199]
	s_mov_b32 m0, s59
	s_nop 0
	global_load_lds_dwordx4 v[98:99], off
	v_lshl_add_u64 v[98:99], s[28:29], 0, v[202:203]
	s_mov_b32 m0, s60
	s_nop 0
	global_load_lds_dwordx4 v[98:99], off
	v_lshl_add_u64 v[98:99], v[218:219], 0, s[12:13]
	s_mov_b32 m0, s57
	s_nop 0
	global_load_lds_dwordx4 v[98:99], off
	v_lshl_add_u64 v[98:99], v[220:221], 0, s[12:13]
	s_mov_b32 m0, s58
	s_nop 0
	global_load_lds_dwordx4 v[98:99], off
	s_waitcnt vmcnt(8)
	s_waitcnt lgkmcnt(0)
	s_waitcnt lgkmcnt(0)
	s_barrier
	s_setprio 1
	v_mfma_f32_16x16x32_bf16 v[62:65], v[124:127], v[164:167], v[62:65]
	v_mfma_f32_16x16x32_bf16 v[58:61], v[140:143], v[164:167], v[58:61]
	v_mfma_f32_16x16x32_bf16 v[46:49], v[124:127], v[172:175], v[46:49]
	v_mfma_f32_16x16x32_bf16 v[42:45], v[140:143], v[172:175], v[42:45]
	v_mfma_f32_16x16x32_bf16 v[30:33], v[124:127], v[180:183], v[30:33]
	v_mfma_f32_16x16x32_bf16 v[26:29], v[140:143], v[180:183], v[26:29]
	v_mfma_f32_16x16x32_bf16 v[14:17], v[124:127], v[188:191], v[14:17]
	v_mfma_f32_16x16x32_bf16 v[10:13], v[140:143], v[188:191], v[10:13]
	v_mfma_f32_16x16x32_bf16 v[62:65], v[132:135], v[168:171], v[62:65]
	v_mfma_f32_16x16x32_bf16 v[58:61], v[144:147], v[168:171], v[58:61]
	v_mfma_f32_16x16x32_bf16 v[46:49], v[132:135], v[176:179], v[46:49]
	v_mfma_f32_16x16x32_bf16 v[42:45], v[144:147], v[176:179], v[42:45]
	v_mfma_f32_16x16x32_bf16 v[30:33], v[132:135], v[184:187], v[30:33]
	v_mfma_f32_16x16x32_bf16 v[26:29], v[144:147], v[184:187], v[26:29]
	v_mfma_f32_16x16x32_bf16 v[14:17], v[132:135], v[192:195], v[14:17]
	v_mfma_f32_16x16x32_bf16 v[10:13], v[144:147], v[192:195], v[10:13]
	s_setprio 0
	s_setprio 1
	v_mfma_f32_16x16x32_bf16 v[54:57], v[148:151], v[164:167], v[54:57]
	v_mfma_f32_16x16x32_bf16 v[50:53], v[156:159], v[164:167], v[50:53]
	v_mfma_f32_16x16x32_bf16 v[38:41], v[148:151], v[172:175], v[38:41]
	v_mfma_f32_16x16x32_bf16 v[34:37], v[156:159], v[172:175], v[34:37]
	v_mfma_f32_16x16x32_bf16 v[22:25], v[148:151], v[180:183], v[22:25]
	v_mfma_f32_16x16x32_bf16 v[18:21], v[156:159], v[180:183], v[18:21]
	v_mfma_f32_16x16x32_bf16 v[6:9], v[148:151], v[188:191], v[6:9]
	v_mfma_f32_16x16x32_bf16 v[2:5], v[156:159], v[188:191], v[2:5]
	v_mfma_f32_16x16x32_bf16 v[54:57], v[152:155], v[168:171], v[54:57]
	v_mfma_f32_16x16x32_bf16 v[50:53], v[160:163], v[168:171], v[50:53]
	v_mfma_f32_16x16x32_bf16 v[38:41], v[152:155], v[176:179], v[38:41]
	v_mfma_f32_16x16x32_bf16 v[34:37], v[160:163], v[176:179], v[34:37]
	v_mfma_f32_16x16x32_bf16 v[22:25], v[152:155], v[184:187], v[22:25]
	v_mfma_f32_16x16x32_bf16 v[18:21], v[160:163], v[184:187], v[18:21]
	v_mfma_f32_16x16x32_bf16 v[6:9], v[152:155], v[192:195], v[6:9]
	v_mfma_f32_16x16x32_bf16 v[2:5], v[160:163], v[192:195], v[2:5]
	s_setprio 0
	s_barrier
	s_add_u32 s6, s6, 0x100
	s_addc_u32 s7, s7, 0
	s_add_u32 s19, s19, 0x100
	s_addc_u32 s27, s27, 0
	s_cmp_ge_i32 s65, s25
	s_mov_b32 s28, s65
	s_cbranch_scc0 .LBB0_2007
	s_and_b64 vcc, exec, s[14:15]
	s_cbranch_vccz .LBB0_2010

;     template <int AI> __device__ __forceinline__ void half_rows(AccT acc, int row0, int col0, int seg) const {
;         v4u gw[4][2], pw[4][2];
; #pragma unroll
;         for (int m = 0; m < 4; ++m)
; #pragma unroll
;             for (int bj = 0; bj < 2; ++bj) { gw[m][bj] = *(const v4u*)ZP(Zg, row0 + m * 16, ZGATE + seg * DM + col0 + bj * HALF);
;                 pw[m][bj] = (v4u){0u, 0u, 0u, 0u}; if (seg > 0) pw[m][bj] = *(const v4u*)(ACC + (size_t)(row0 + m * 16) * DM + col0 + bj * HALF); }
;     __device__ __forceinline__ void operator()(AccT acc, const Unit& u, int wr, int wc, int fr, int fq) const {
;         const int upm = u.pm, upn = u.pn, uhalf = u.half, seg = u.seg;
;         const int col0 = upn * BM + wc * 32 + 8 * fq, rbase = upm * BM + wr * 64 + fr;
;         if (uhalf != 1) half_rows<0>(acc, rbase, col0, seg);
;         if (uhalf != 0) half_rows<1>(acc, rbase + HALF, col0, seg);
.LBB0_2010:
	s_mov_b32 s98, 1
	s_lshl_b32 s19, s26, 8
	s_lshl_b32 s6, s64, 10
	s_add_i32 s6, s19, s6
	s_addk_i32 s6, 0x2400
	v_lshl_add_u32 v214, s24, 8, v1
	s_cmp_gt_i32 s64, 0
	s_cselect_b64 s[24:25], -1, 0
	s_ashr_i32 s17, s6, 8
	v_ashrrev_i32_e32 v215, 31, v214
	v_mad_i64_i32 v[98:99], s[6:7], s17, v236, v[214:215]
	v_lshlrev_b64 v[98:99], 9, v[98:99]
	v_lshl_add_u64 v[124:125], v[204:205], 0, v[98:99]
	global_load_dwordx4 v[192:195], v[124:125], off
	v_or_b32_e32 v224, s19, v230
	v_ashrrev_i32_e32 v225, 31, v224
	v_lshl_add_u64 v[216:217], v[224:225], 1, s[10:11]
	v_lshlrev_b64 v[226:227], 11, v[214:215]
	s_cmp_lt_i32 s64, 1
	v_lshl_add_u64 v[98:99], v[216:217], 0, v[226:227]
	s_cbranch_scc1 .LBB0_2015
	global_load_dwordx4 v[188:191], v[98:99], off
	s_branch .LBB0_2016

; #define LAS __attribute__((address_space(3)))
; #define PSCALE(k, v) ((kargs()->li == 1 && (k) == lo) ? 0.f : (v))
; template <int K> __device__ __forceinline__ void sample_resid_units(LAS unsigned char* lds, const bf16* Aop, int lda, const bf16* Bt, int ldb, bf16* X, const float* gate, float scale,
;                                                    bf16* XB, float* SSQ, const float* gam, int tid, int vcu, int G) {
;     LAS float* P = (LAS float*)lds;
;     LAS float* R = P + 8 * 1024;
;     const int lane = tid & 63, w = __builtin_amdgcn_readfirstlane(tid >> 6), qq = lane & 15, q4 = lane >> 4;
;     for (int un = vcu; un < 256; un += G) {
;         const int rt = un >> 4, cs = un & 15, pn = cs >> 2, wc = cs & 3; const size_t row0 = (size_t)NPROMPT + 16 * rt;
;         constexpr int kper = K >> 3; const int kbeg = w * kper;
;         f32x4 acc[4];
; #pragma unroll
;         for (int ct = 0; ct < 4; ++ct) acc[ct] = (f32x4){0.f, 0.f, 0.f, 0.f};
;         const bf16* ap = Aop + (row0 + qq) * (size_t)lda + kbeg + 8 * q4;
;         const bf16* bp = Bt + (size_t)(256 * pn + 32 * wc + qq) * ldb + kbeg + 8 * q4;
; #pragma unroll 4
;         for (int k0 = 0; k0 < kper; k0 += 32) {
;             const bf16x8 af = *(const bf16x8*)(ap + k0);
; #pragma unroll
;             for (int ct = 0; ct < 4; ++ct) { const bf16x8 bf = *(const bf16x8*)(bp + (size_t)(128 * (ct >> 1) + 16 * (ct & 1)) * ldb + k0);
;                 acc[ct] = __builtin_amdgcn_mfma_f32_16x16x32_bf16(bf, af, acc[ct], 0, 0, 0); } }
; __global__ void __launch_bounds__(NWAVES * 64, 2) fwd(Args args_unused) {
;     ...
;         if (IN(pb + 7)) {
;             PH_PTRS PH_LAYER
;             sample_resid_units<DM>(lds, MG, DM, (const bf16*)(wl + WL_O), DM, X, modl + 5 * DM, PSCALE(pb + 7, 1.0f), XB, SSQ, GAM + (size_t)(l * 3 + 2) * NSEQ * DM, tid, vcu, G);
.LBB0_2108:
	s_mov_b32 s98, 0
	s_cmp_lt_i32 s84, 11
	s_cselect_b64 s[0:1], -1, 0
	s_cmp_gt_i32 s85, 10
	s_cselect_b64 s[4:5], -1, 0
	s_and_b64 s[0:1], s[0:1], s[4:5]
	s_andn2_b64 vcc, exec, s[0:1]
	s_cbranch_vccnz .LBB0_2214
	s_mov_b64 s[0:1], s[82:83]
	s_load_dwordx2 s[4:5], s[0:1], 0x148
	s_mov_b32 s24, 0
	v_readlane_b32 s20, v254, 3
	s_mov_b32 s3, s2
	s_waitcnt lgkmcnt(0)
	s_add_u32 s0, s4, 0xcf00000
	s_addc_u32 s1, s5, 0
	s_add_u32 s8, s4, 0x15000000
	s_addc_u32 s9, s5, 0
	s_add_u32 s44, s4, 0x19100000
	s_addc_u32 s45, s5, 0
	s_add_u32 s10, s4, 0xcc00000
	s_addc_u32 s11, s5, 0
	s_add_u32 s46, s4, 0x3000000
	s_addc_u32 s47, s5, 0
	s_add_u32 s12, s4, 0xb105000
	s_addc_u32 s13, s5, 0
	s_add_u32 s14, s4, 0xbc60000
	s_load_dword s33, s[82:83], 0x168
	v_mov_b32_e32 v2, v0
	s_addc_u32 s15, s5, 0
	s_mov_b32 s17, 0
	s_waitcnt lgkmcnt(0)
	s_cmpk_gt_i32 s20, 0xff
	v_readfirstlane_b32 s4, v2
	s_cbranch_scc1 .LBB0_2116
	s_ashr_i32 s16, s4, 6
	s_lshl_b32 s4, s16, 2
	s_add_i32 s18, s24, s4
	s_lshl_b32 s4, s16, 7
	s_ashr_i32 s5, s4, 31
	s_lshl_b64 s[4:5], s[4:5], 1
	s_add_u32 s6, s44, s4
	s_addc_u32 s7, s45, s5
	s_add_u32 s4, s46, s4
	v_and_b32_e32 v4, 15, v2
	v_and_b32_e32 v3, 63, v2
	v_mov_b32_e32 v7, 0
	v_and_b32_e32 v6, 48, v2
	s_addc_u32 s5, s47, s5
	v_ashrrev_i32_e32 v12, 7, v2
	v_lshlrev_b32_e32 v5, 1, v2
	v_lshl_add_u64 v[8:9], s[6:7], 0, v[6:7]
	v_lshl_add_u64 v[10:11], s[4:5], 0, v[6:7]
	s_lshl_b32 s6, s16, 12
	v_lshl_add_u32 v6, v3, 2, s24
	v_lshrrev_b32_e32 v1, 3, v2
	v_lshl_add_u32 v13, v4, 2, s24
	v_and_b32_e32 v14, 0xc0, v5
	v_ashrrev_i32_e32 v5, 1, v2
	v_lshlrev_b32_e32 v15, 4, v12
	v_lshlrev_b32_e32 v12, 10, v12
	v_and_b32_e32 v5, 0xffffff80, v5
	v_and_b32_e32 v15, 16, v15
	v_and_b32_e32 v1, 14, v1
	v_add3_u32 v12, v13, v14, v12
	v_add_u32_e32 v14, s6, v6
	v_mbcnt_lo_u32_b32 v6, -1, 0
	v_or3_b32 v1, v5, v15, v1
	v_lshlrev_b32_e32 v5, 5, v2
	v_mbcnt_hi_u32_b32 v16, -1, v6
	v_lshlrev_b32_e32 v20, 5, v4
	v_and_b32_e32 v15, 0x200, v5
	v_and_b32_e32 v6, 64, v16
	v_cmp_gt_u32_e32 vcc, 16, v3
	v_cmp_gt_i32_e64 s[4:5], 16, v2
	v_ashrrev_i32_e32 v3, 31, v2
	s_lshl_b32 s21, s20, 5
	s_lshl_b32 s22, s33, 5
	s_mov_b32 s23, 0x8000
	s_mov_b32 s25, 0x40000
	s_mov_b32 s26, 0x48000
	v_add_u32_e32 v15, v12, v15
	s_mov_b32 s27, 0x9000
	v_mov_b64_e32 v[12:13], s[12:13]
	v_xor_b32_e32 v17, 16, v16
	v_add_u32_e32 v18, 64, v6
	v_xor_b32_e32 v19, 32, v16
	v_add_u32_e32 v20, s18, v20
	s_branch .LBB0_2112

; #define PG8_STAGE(bufoff, gbase, voff) do { _Pragma("unroll") for (int _i = 0; _i < 2; ++_i) \
;         __builtin_amdgcn_global_load_lds((const unsigned*)((const char*)(gbase) + (voff)[_i]), (PG8_LAS unsigned*)(lds + (bufoff) + ldsw + _i * 8192), 16, 0, 0); } while (0)
; #define PG8_LDA(dst, b, h) do { _Pragma("unroll") for (int m = 0; m < 4; ++m) _Pragma("unroll") for (int k = 0; k < 2; ++k) dst[m][k] = *(const PG8_LAS bf16x8*)(lds + PG8_SA(b, h) + aoff + m * 2048 + k * 1024); } while (0)
; #define PG8_LDB(dst, b, h) do { _Pragma("unroll") for (int n = 0; n < 2; ++n) _Pragma("unroll") for (int k = 0; k < 2; ++k) dst[n][k] = *(const PG8_LAS bf16x8*)(lds + PG8_SB(b, h) + boff + n * 2048 + k * 1024); } while (0)
; #define PG8_MMA(ai, bj, At, Bt) do { __builtin_amdgcn_s_setprio(1); _Pragma("unroll") for (int m = 0; m < 4; ++m) _Pragma("unroll") for (int n = 0; n < 2; ++n) _Pragma("unroll") for (int k = 0; k < 2; ++k) \
;         acc[ai][bj][m][n] = __builtin_amdgcn_mfma_f32_16x16x32_bf16(Bt[n][k], At[m][k], acc[ai][bj][m][n], 0, 0, 0); __builtin_amdgcn_s_setprio(0); } while (0)
; #define PG8_WAIT_V(n) asm volatile("s_waitcnt vmcnt(" #n ")" ::: "memory")
; #define PG8_BAR __builtin_amdgcn_s_barrier()
; template <class Epi, class Sched, bool SEG3 = false>
; __device__ __forceinline__ void gemm_phase(PG8_LAS unsigned char* lds, const Gemm g, const Sched& S, const Epi& E) {
;     ...
;         for (int t = 0; t < ntc; t += 2) {
;             bf16x8 At[4][2], B0[2][2], B1[2][2];
;             const bool last = (t == ntc - 2);
;             const char* a1 = cA + (size_t)(t + 1) * kstep;
;             const char* a2 = last ? nA : cA + (size_t)(t + 2) * kstep; const char* b2 = last ? nB : cB + (size_t)(t + 2) * kstep;
;             const char* a3 = a2 + kstep; const char* b3 = b2 + kstep;
;             PG8_LDB(B0, 0, 0); PG8_LDB(B1, 0, 1); PG8_SCHED; PG8_LDA(At, 0, 0); PG8_STAGE(PG8_SA(1, 1), a1 + hsA, voffA);
;             PG8_WAIT_V(8); PG8_WAIT_L(0); PG8_BAR; if (cur.half != 1) { PG8_MMA(0, 0, At, B0); PG8_MMA(0, 1, At, B1); } PG8_BAR; PG8_SCHED;
;             PG8_LDA(At, 0, 1); PG8_STAGE(PG8_SB(0, 0), b2, voffB); PG8_STAGE(PG8_SB(0, 1), b2 + hsB, voffB); PG8_STAGE(PG8_SA(0, 0), a2, voffA);
;             PG8_WAIT_V(8); PG8_WAIT_L(0); PG8_BAR; if (cur.half != 0) { PG8_MMA(1, 0, At, B0); PG8_MMA(1, 1, At, B1); } PG8_BAR; PG8_SCHED;
.LBB0_2133:
	ds_read_b128 v[34:37], v207
	ds_read_b128 v[38:41], v207 offset:1024
	ds_read_b128 v[42:45], v207 offset:2048
	ds_read_b128 v[46:49], v207 offset:3072
	ds_read_b128 v[114:117], v208
	ds_read_b128 v[126:129], v208 offset:1024
	ds_read_b128 v[138:141], v208 offset:2048
	ds_read_b128 v[150:153], v208 offset:3072
	s_add_i32 s70, s40, 2
	s_add_u32 s41, s38, 0xfffc0080
	s_addc_u32 s42, s39, -1
	s_cmp_eq_u32 s64, s40
	s_cselect_b32 s40, s37, s68
	s_cselect_b32 s43, s25, s42
	s_cselect_b32 s42, s27, s41
	s_cselect_b32 s41, s35, s69
	v_lshl_add_u64 v[218:219], s[38:39], 0, v[178:179]
	s_add_i32 m0, s52, 0xc000
	ds_read_b128 v[162:165], v209
	ds_read_b128 v[166:169], v209 offset:1024
	ds_read_b128 v[186:189], v209 offset:2048
	ds_read_b128 v[190:193], v209 offset:3072
	ds_read_b128 v[194:197], v209 offset:4096
	ds_read_b128 v[198:201], v209 offset:5120
	ds_read_b128 v[202:205], v209 offset:6144
	ds_read_b128 v[214:217], v209 offset:7168
	global_load_lds_dwordx4 v[218:219], off
	v_lshl_add_u64 v[218:219], s[38:39], 0, v[180:181]
	s_add_i32 m0, s52, 0xe000
	s_nop 0
	global_load_lds_dwordx4 v[218:219], off
	s_cmp_lg_u32 s98, 0
	s_cbranch_scc1 .Lfi_a_3
	s_waitcnt vmcnt(8)
.Lfi_a_3:
	s_waitcnt lgkmcnt(0)
	s_barrier
	s_setprio 1
	v_mfma_f32_16x16x32_bf16 v[158:161], v[34:37], v[162:165], v[158:161]
	v_mfma_f32_16x16x32_bf16 v[154:157], v[42:45], v[162:165], v[154:157]
	v_mfma_f32_16x16x32_bf16 v[134:137], v[34:37], v[186:189], v[134:137]
	v_mfma_f32_16x16x32_bf16 v[130:133], v[42:45], v[186:189], v[130:133]
	v_mfma_f32_16x16x32_bf16 v[110:113], v[34:37], v[194:197], v[110:113]
	v_mfma_f32_16x16x32_bf16 v[106:109], v[42:45], v[194:197], v[106:109]
	v_mfma_f32_16x16x32_bf16 v[94:97], v[34:37], v[202:205], v[94:97]
	v_mfma_f32_16x16x32_bf16 v[90:93], v[42:45], v[202:205], v[90:93]
	v_mfma_f32_16x16x32_bf16 v[158:161], v[38:41], v[166:169], v[158:161]
	v_mfma_f32_16x16x32_bf16 v[154:157], v[46:49], v[166:169], v[154:157]
	v_mfma_f32_16x16x32_bf16 v[134:137], v[38:41], v[190:193], v[134:137]
	v_mfma_f32_16x16x32_bf16 v[130:133], v[46:49], v[190:193], v[130:133]
	v_mfma_f32_16x16x32_bf16 v[110:113], v[38:41], v[198:201], v[110:113]
	v_mfma_f32_16x16x32_bf16 v[106:109], v[46:49], v[198:201], v[106:109]
	v_mfma_f32_16x16x32_bf16 v[94:97], v[38:41], v[214:217], v[94:97]
	v_mfma_f32_16x16x32_bf16 v[90:93], v[46:49], v[214:217], v[90:93]
	s_setprio 0
	s_setprio 1
	v_mfma_f32_16x16x32_bf16 v[146:149], v[114:117], v[162:165], v[146:149]
	v_mfma_f32_16x16x32_bf16 v[142:145], v[138:141], v[162:165], v[142:145]
	v_mfma_f32_16x16x32_bf16 v[122:125], v[114:117], v[186:189], v[122:125]
	v_mfma_f32_16x16x32_bf16 v[118:121], v[138:141], v[186:189], v[118:121]
	v_mfma_f32_16x16x32_bf16 v[102:105], v[114:117], v[194:197], v[102:105]
	v_mfma_f32_16x16x32_bf16 v[98:101], v[138:141], v[194:197], v[98:101]
	v_mfma_f32_16x16x32_bf16 v[86:89], v[114:117], v[202:205], v[86:89]
	v_mfma_f32_16x16x32_bf16 v[82:85], v[138:141], v[202:205], v[82:85]
	v_mfma_f32_16x16x32_bf16 v[146:149], v[126:129], v[166:169], v[146:149]
	v_mfma_f32_16x16x32_bf16 v[142:145], v[150:153], v[166:169], v[142:145]
	v_mfma_f32_16x16x32_bf16 v[122:125], v[126:129], v[190:193], v[122:125]
	v_mfma_f32_16x16x32_bf16 v[118:121], v[150:153], v[190:193], v[118:121]
	v_mfma_f32_16x16x32_bf16 v[102:105], v[126:129], v[198:201], v[102:105]
	v_mfma_f32_16x16x32_bf16 v[98:101], v[150:153], v[198:201], v[98:101]
	v_mfma_f32_16x16x32_bf16 v[86:89], v[126:129], v[214:217], v[86:89]
	v_mfma_f32_16x16x32_bf16 v[82:85], v[150:153], v[214:217], v[82:85]
	s_setprio 0
	s_barrier
	s_mov_b32 m0, s48
	v_lshl_add_u64 v[218:219], s[40:41], 0, v[172:173]
	s_add_u32 s72, s40, 0x40000
	ds_read_b128 v[162:165], v209 offset:16384
	ds_read_b128 v[166:169], v209 offset:17408
	ds_read_b128 v[186:189], v209 offset:18432
	ds_read_b128 v[190:193], v209 offset:19456
	ds_read_b128 v[194:197], v209 offset:20480
	ds_read_b128 v[198:201], v209 offset:21504
	ds_read_b128 v[202:205], v209 offset:22528
	ds_read_b128 v[214:217], v209 offset:23552
	global_load_lds_dwordx4 v[218:219], off
	v_lshl_add_u64 v[220:221], s[40:41], 0, v[176:177]
	s_mov_b32 m0, s49
	s_addc_u32 s73, s41, 0
	global_load_lds_dwordx4 v[220:221], off
	v_lshl_add_u64 v[222:223], s[72:73], 0, v[172:173]
	s_mov_b32 m0, s50
	v_lshl_add_u64 v[224:225], s[42:43], 0, v[174:175]
	global_load_lds_dwordx4 v[222:223], off
	v_lshl_add_u64 v[222:223], s[72:73], 0, v[176:177]
	s_mov_b32 m0, s51
	s_nop 0
	global_load_lds_dwordx4 v[222:223], off
	v_lshl_add_u64 v[222:223], s[42:43], 0, v[170:171]
	s_mov_b32 m0, s52
	s_nop 0
	global_load_lds_dwordx4 v[222:223], off
	s_mov_b32 m0, s53
	s_nop 0
	global_load_lds_dwordx4 v[224:225], off
	s_cmp_lg_u32 s98, 0
	s_cbranch_scc1 .Lfi_b_3
	s_waitcnt vmcnt(8)
; #define PG8_STAGE(bufoff, gbase, voff) do { _Pragma("unroll") for (int _i = 0; _i < 2; ++_i) \
;         __builtin_amdgcn_global_load_lds((const unsigned*)((const char*)(gbase) + (voff)[_i]), (PG8_LAS unsigned*)(lds + (bufoff) + ldsw + _i * 8192), 16, 0, 0); } while (0)
; #define PG8_LDA(dst, b, h) do { _Pragma("unroll") for (int m = 0; m < 4; ++m) _Pragma("unroll") for (int k = 0; k < 2; ++k) dst[m][k] = *(const PG8_LAS bf16x8*)(lds + PG8_SA(b, h) + aoff + m * 2048 + k * 1024); } while (0)
; #define PG8_LDB(dst, b, h) do { _Pragma("unroll") for (int n = 0; n < 2; ++n) _Pragma("unroll") for (int k = 0; k < 2; ++k) dst[n][k] = *(const PG8_LAS bf16x8*)(lds + PG8_SB(b, h) + boff + n * 2048 + k * 1024); } while (0)
; #define PG8_MMA(ai, bj, At, Bt) do { __builtin_amdgcn_s_setprio(1); _Pragma("unroll") for (int m = 0; m < 4; ++m) _Pragma("unroll") for (int n = 0; n < 2; ++n) _Pragma("unroll") for (int k = 0; k < 2; ++k) \
;         acc[ai][bj][m][n] = __builtin_amdgcn_mfma_f32_16x16x32_bf16(Bt[n][k], At[m][k], acc[ai][bj][m][n], 0, 0, 0); __builtin_amdgcn_s_setprio(0); } while (0)
; #define PG8_WAIT_V(n) asm volatile("s_waitcnt vmcnt(" #n ")" ::: "memory")
; #define PG8_WAIT_L(n) do { asm volatile("s_waitcnt lgkmcnt(" #n ")" ::: "memory"); __builtin_amdgcn_s_waitcnt(0xC07F); } while (0)
; #define PG8_BAR __builtin_amdgcn_s_barrier()
; #define PG8_SCHED __builtin_amdgcn_sched_barrier(0)
; template <class Epi, class Sched, bool SEG3 = false>
; __device__ __forceinline__ void gemm_phase(PG8_LAS unsigned char* lds, const Gemm g, const Sched& S, const Epi& E) {
;     ...
;             PG8_WAIT_V(8); PG8_WAIT_L(0); PG8_BAR; if (cur.half != 0) { PG8_MMA(1, 0, At, B0); PG8_MMA(1, 1, At, B1); } PG8_BAR; PG8_SCHED;
;             PG8_LDB(B0, 1, 0); PG8_LDB(B1, 1, 1); PG8_SCHED; PG8_LDA(At, 1, 0); PG8_STAGE(PG8_SA(0, 1), a2 + hsA, voffA);
;             PG8_WAIT_V(8); PG8_WAIT_L(0); PG8_BAR; if (cur.half != 1) { PG8_MMA(0, 0, At, B0); PG8_MMA(0, 1, At, B1); } PG8_BAR; PG8_SCHED;
;             PG8_LDA(At, 1, 1); PG8_STAGE(PG8_SB(1, 0), b3, voffB); PG8_STAGE(PG8_SB(1, 1), b3 + hsB, voffB); PG8_STAGE(PG8_SA(1, 0), a3, voffA);
.Lfi_b_3:
	s_mov_b32 s98, 0
	s_waitcnt lgkmcnt(0)
	s_barrier
	s_setprio 1
	v_mfma_f32_16x16x32_bf16 v[78:81], v[34:37], v[162:165], v[78:81]
	v_mfma_f32_16x16x32_bf16 v[74:77], v[42:45], v[162:165], v[74:77]
	v_mfma_f32_16x16x32_bf16 v[62:65], v[34:37], v[186:189], v[62:65]
	v_mfma_f32_16x16x32_bf16 v[58:61], v[42:45], v[186:189], v[58:61]
	v_mfma_f32_16x16x32_bf16 v[30:33], v[34:37], v[194:197], v[30:33]
	v_mfma_f32_16x16x32_bf16 v[26:29], v[42:45], v[194:197], v[26:29]
	v_mfma_f32_16x16x32_bf16 v[14:17], v[34:37], v[202:205], v[14:17]
	v_mfma_f32_16x16x32_bf16 v[10:13], v[42:45], v[202:205], v[10:13]
	v_mfma_f32_16x16x32_bf16 v[78:81], v[38:41], v[166:169], v[78:81]
	v_mfma_f32_16x16x32_bf16 v[74:77], v[46:49], v[166:169], v[74:77]
	v_mfma_f32_16x16x32_bf16 v[62:65], v[38:41], v[190:193], v[62:65]
	v_mfma_f32_16x16x32_bf16 v[58:61], v[46:49], v[190:193], v[58:61]
	v_mfma_f32_16x16x32_bf16 v[30:33], v[38:41], v[198:201], v[30:33]
	v_mfma_f32_16x16x32_bf16 v[26:29], v[46:49], v[198:201], v[26:29]
	v_mfma_f32_16x16x32_bf16 v[14:17], v[38:41], v[214:217], v[14:17]
	v_mfma_f32_16x16x32_bf16 v[10:13], v[46:49], v[214:217], v[10:13]
	s_setprio 0
	s_setprio 1
	v_mfma_f32_16x16x32_bf16 v[22:25], v[114:117], v[194:197], v[22:25]
	v_mfma_f32_16x16x32_bf16 v[18:21], v[138:141], v[194:197], v[18:21]
	v_mfma_f32_16x16x32_bf16 v[6:9], v[114:117], v[202:205], v[6:9]
	v_mfma_f32_16x16x32_bf16 v[2:5], v[138:141], v[202:205], v[2:5]
	v_mfma_f32_16x16x32_bf16 v[34:37], v[114:117], v[162:165], v[70:73]
	v_mfma_f32_16x16x32_bf16 v[38:41], v[138:141], v[162:165], v[66:69]
	v_mfma_f32_16x16x32_bf16 v[42:45], v[114:117], v[186:189], v[54:57]
	v_mfma_f32_16x16x32_bf16 v[46:49], v[138:141], v[186:189], v[50:53]
	v_mfma_f32_16x16x32_bf16 v[22:25], v[126:129], v[198:201], v[22:25]
	v_mfma_f32_16x16x32_bf16 v[18:21], v[150:153], v[198:201], v[18:21]
	v_mfma_f32_16x16x32_bf16 v[6:9], v[126:129], v[214:217], v[6:9]
	v_mfma_f32_16x16x32_bf16 v[2:5], v[150:153], v[214:217], v[2:5]
	v_mfma_f32_16x16x32_bf16 v[34:37], v[126:129], v[166:169], v[34:37]
	v_mfma_f32_16x16x32_bf16 v[38:41], v[150:153], v[166:169], v[38:41]
	v_mfma_f32_16x16x32_bf16 v[42:45], v[126:129], v[190:193], v[42:45]
	v_mfma_f32_16x16x32_bf16 v[46:49], v[150:153], v[190:193], v[46:49]
	s_setprio 0
	s_barrier
	ds_read_b128 v[50:53], v210
	ds_read_b128 v[54:57], v210 offset:1024
	ds_read_b128 v[66:69], v210 offset:2048
	ds_read_b128 v[70:73], v210 offset:3072
	ds_read_b128 v[114:117], v211
	ds_read_b128 v[126:129], v211 offset:1024
	ds_read_b128 v[138:141], v211 offset:2048
	ds_read_b128 v[150:153], v211 offset:3072
	s_add_u32 s42, s42, 0x40000
	s_addc_u32 s43, s43, 0
	s_mov_b32 m0, s54
	v_lshl_add_u64 v[226:227], s[42:43], 0, v[170:171]
	ds_read_b128 v[162:165], v209 offset:32768
	ds_read_b128 v[166:169], v209 offset:33792
	ds_read_b128 v[186:189], v209 offset:34816
	ds_read_b128 v[190:193], v209 offset:35840
	ds_read_b128 v[194:197], v209 offset:36864
	ds_read_b128 v[198:201], v209 offset:37888
	ds_read_b128 v[202:205], v209 offset:38912
	ds_read_b128 v[214:217], v209 offset:39936
	global_load_lds_dwordx4 v[226:227], off
	v_lshl_add_u64 v[226:227], s[42:43], 0, v[174:175]
	s_mov_b32 m0, s55
	s_nop 0
	global_load_lds_dwordx4 v[226:227], off
	s_waitcnt vmcnt(8)
	s_waitcnt lgkmcnt(0)
	s_waitcnt lgkmcnt(0)
	s_barrier
	s_setprio 1
	v_mfma_f32_16x16x32_bf16 v[158:161], v[50:53], v[162:165], v[158:161]
	v_mfma_f32_16x16x32_bf16 v[154:157], v[66:69], v[162:165], v[154:157]
	v_mfma_f32_16x16x32_bf16 v[134:137], v[50:53], v[186:189], v[134:137]
	v_mfma_f32_16x16x32_bf16 v[130:133], v[66:69], v[186:189], v[130:133]
	v_mfma_f32_16x16x32_bf16 v[110:113], v[50:53], v[194:197], v[110:113]
	v_mfma_f32_16x16x32_bf16 v[106:109], v[66:69], v[194:197], v[106:109]
	v_mfma_f32_16x16x32_bf16 v[94:97], v[50:53], v[202:205], v[94:97]
	v_mfma_f32_16x16x32_bf16 v[90:93], v[66:69], v[202:205], v[90:93]
	v_mfma_f32_16x16x32_bf16 v[158:161], v[54:57], v[166:169], v[158:161]
	v_mfma_f32_16x16x32_bf16 v[154:157], v[70:73], v[166:169], v[154:157]
	v_mfma_f32_16x16x32_bf16 v[134:137], v[54:57], v[190:193], v[134:137]
	v_mfma_f32_16x16x32_bf16 v[130:133], v[70:73], v[190:193], v[130:133]
	v_mfma_f32_16x16x32_bf16 v[110:113], v[54:57], v[198:201], v[110:113]
	v_mfma_f32_16x16x32_bf16 v[106:109], v[70:73], v[198:201], v[106:109]
	v_mfma_f32_16x16x32_bf16 v[94:97], v[54:57], v[214:217], v[94:97]
	v_mfma_f32_16x16x32_bf16 v[90:93], v[70:73], v[214:217], v[90:93]
	s_setprio 0
	s_setprio 1
	v_mfma_f32_16x16x32_bf16 v[146:149], v[114:117], v[162:165], v[146:149]
	v_mfma_f32_16x16x32_bf16 v[142:145], v[138:141], v[162:165], v[142:145]
	v_mfma_f32_16x16x32_bf16 v[122:125], v[114:117], v[186:189], v[122:125]
	v_mfma_f32_16x16x32_bf16 v[118:121], v[138:141], v[186:189], v[118:121]
	v_mfma_f32_16x16x32_bf16 v[102:105], v[114:117], v[194:197], v[102:105]
	v_mfma_f32_16x16x32_bf16 v[98:101], v[138:141], v[194:197], v[98:101]
	v_mfma_f32_16x16x32_bf16 v[86:89], v[114:117], v[202:205], v[86:89]
	v_mfma_f32_16x16x32_bf16 v[82:85], v[138:141], v[202:205], v[82:85]
	v_mfma_f32_16x16x32_bf16 v[146:149], v[126:129], v[166:169], v[146:149]
	v_mfma_f32_16x16x32_bf16 v[142:145], v[150:153], v[166:169], v[142:145]
	v_mfma_f32_16x16x32_bf16 v[122:125], v[126:129], v[190:193], v[122:125]
	v_mfma_f32_16x16x32_bf16 v[118:121], v[150:153], v[190:193], v[118:121]
	v_mfma_f32_16x16x32_bf16 v[102:105], v[126:129], v[198:201], v[102:105]
	v_mfma_f32_16x16x32_bf16 v[98:101], v[150:153], v[198:201], v[98:101]
	v_mfma_f32_16x16x32_bf16 v[86:89], v[126:129], v[214:217], v[86:89]
	v_mfma_f32_16x16x32_bf16 v[82:85], v[150:153], v[214:217], v[82:85]
	s_setprio 0
	s_barrier
; #define PG8_STAGE(bufoff, gbase, voff) do { _Pragma("unroll") for (int _i = 0; _i < 2; ++_i) \
;         __builtin_amdgcn_global_load_lds((const unsigned*)((const char*)(gbase) + (voff)[_i]), (PG8_LAS unsigned*)(lds + (bufoff) + ldsw + _i * 8192), 16, 0, 0); } while (0)
; #define PG8_LDA(dst, b, h) do { _Pragma("unroll") for (int m = 0; m < 4; ++m) _Pragma("unroll") for (int k = 0; k < 2; ++k) dst[m][k] = *(const PG8_LAS bf16x8*)(lds + PG8_SA(b, h) + aoff + m * 2048 + k * 1024); } while (0)
; #define PG8_MMA(ai, bj, At, Bt) do { __builtin_amdgcn_s_setprio(1); _Pragma("unroll") for (int m = 0; m < 4; ++m) _Pragma("unroll") for (int n = 0; n < 2; ++n) _Pragma("unroll") for (int k = 0; k < 2; ++k) \
;         acc[ai][bj][m][n] = __builtin_amdgcn_mfma_f32_16x16x32_bf16(Bt[n][k], At[m][k], acc[ai][bj][m][n], 0, 0, 0); __builtin_amdgcn_s_setprio(0); } while (0)
; #define PG8_WAIT_V(n) asm volatile("s_waitcnt vmcnt(" #n ")" ::: "memory")
; #define PG8_WAIT_L(n) do { asm volatile("s_waitcnt lgkmcnt(" #n ")" ::: "memory"); __builtin_amdgcn_s_waitcnt(0xC07F); } while (0)
; #define PG8_BAR __builtin_amdgcn_s_barrier()
; #define PG8_SCHED __builtin_amdgcn_sched_barrier(0)
; template <class Epi, class Sched, bool SEG3 = false>
; __device__ __forceinline__ void gemm_phase(PG8_LAS unsigned char* lds, const Gemm g, const Sched& S, const Epi& E) {
;     ...
;             PG8_LDA(At, 1, 1); PG8_STAGE(PG8_SB(1, 0), b3, voffB); PG8_STAGE(PG8_SB(1, 1), b3 + hsB, voffB); PG8_STAGE(PG8_SA(1, 0), a3, voffA);
;             PG8_WAIT_V(8); PG8_WAIT_L(0); PG8_BAR; if (cur.half != 0) { PG8_MMA(1, 0, At, B0); PG8_MMA(1, 1, At, B1); } PG8_BAR; PG8_SCHED;
;         }
	s_mov_b32 m0, s58
	v_lshl_add_u64 v[218:219], v[218:219], 0, s[18:19]
	s_add_u32 s40, s40, 0x40080
	ds_read_b128 v[162:165], v209 offset:49152
	ds_read_b128 v[166:169], v209 offset:50176
	ds_read_b128 v[186:189], v209 offset:51200
	ds_read_b128 v[190:193], v209 offset:52224
	ds_read_b128 v[194:197], v209 offset:53248
	ds_read_b128 v[198:201], v209 offset:54272
	ds_read_b128 v[202:205], v209 offset:55296
	ds_read_b128 v[214:217], v209 offset:56320
	global_load_lds_dwordx4 v[218:219], off
	v_lshl_add_u64 v[218:219], v[220:221], 0, s[18:19]
	s_mov_b32 m0, s59
	s_addc_u32 s41, s41, 0
	global_load_lds_dwordx4 v[218:219], off
	v_lshl_add_u64 v[218:219], s[40:41], 0, v[172:173]
	s_mov_b32 m0, s62
	s_nop 0
	global_load_lds_dwordx4 v[218:219], off
	v_lshl_add_u64 v[218:219], s[40:41], 0, v[176:177]
	s_mov_b32 m0, s63
	s_nop 0
	global_load_lds_dwordx4 v[218:219], off
	v_lshl_add_u64 v[218:219], v[222:223], 0, s[18:19]
	s_mov_b32 m0, s60
	s_nop 0
	global_load_lds_dwordx4 v[218:219], off
	v_lshl_add_u64 v[218:219], v[224:225], 0, s[18:19]
	s_mov_b32 m0, s61
	s_nop 0
	global_load_lds_dwordx4 v[218:219], off
	s_waitcnt vmcnt(8)
	s_waitcnt lgkmcnt(0)
	s_waitcnt lgkmcnt(0)
	s_barrier
	s_setprio 1
	v_mfma_f32_16x16x32_bf16 v[78:81], v[50:53], v[162:165], v[78:81]
	v_mfma_f32_16x16x32_bf16 v[74:77], v[66:69], v[162:165], v[74:77]
	v_mfma_f32_16x16x32_bf16 v[62:65], v[50:53], v[186:189], v[62:65]
	v_mfma_f32_16x16x32_bf16 v[58:61], v[66:69], v[186:189], v[58:61]
	v_mfma_f32_16x16x32_bf16 v[30:33], v[50:53], v[194:197], v[30:33]
	v_mfma_f32_16x16x32_bf16 v[26:29], v[66:69], v[194:197], v[26:29]
	v_mfma_f32_16x16x32_bf16 v[14:17], v[50:53], v[202:205], v[14:17]
	v_mfma_f32_16x16x32_bf16 v[10:13], v[66:69], v[202:205], v[10:13]
	v_mfma_f32_16x16x32_bf16 v[78:81], v[54:57], v[166:169], v[78:81]
	v_mfma_f32_16x16x32_bf16 v[74:77], v[70:73], v[166:169], v[74:77]
	v_mfma_f32_16x16x32_bf16 v[62:65], v[54:57], v[190:193], v[62:65]
	v_mfma_f32_16x16x32_bf16 v[58:61], v[70:73], v[190:193], v[58:61]
	v_mfma_f32_16x16x32_bf16 v[30:33], v[54:57], v[198:201], v[30:33]
	v_mfma_f32_16x16x32_bf16 v[26:29], v[70:73], v[198:201], v[26:29]
	v_mfma_f32_16x16x32_bf16 v[14:17], v[54:57], v[214:217], v[14:17]
	v_mfma_f32_16x16x32_bf16 v[10:13], v[70:73], v[214:217], v[10:13]
	s_setprio 0
	s_setprio 1
	v_mfma_f32_16x16x32_bf16 v[34:37], v[114:117], v[162:165], v[34:37]
	v_mfma_f32_16x16x32_bf16 v[70:73], v[126:129], v[166:169], v[34:37]
	v_mfma_f32_16x16x32_bf16 v[34:37], v[138:141], v[162:165], v[38:41]
	v_mfma_f32_16x16x32_bf16 v[66:69], v[150:153], v[166:169], v[34:37]
	v_mfma_f32_16x16x32_bf16 v[34:37], v[114:117], v[186:189], v[42:45]
	v_mfma_f32_16x16x32_bf16 v[54:57], v[126:129], v[190:193], v[34:37]
	v_mfma_f32_16x16x32_bf16 v[34:37], v[138:141], v[186:189], v[46:49]
	v_mfma_f32_16x16x32_bf16 v[22:25], v[114:117], v[194:197], v[22:25]
	v_mfma_f32_16x16x32_bf16 v[18:21], v[138:141], v[194:197], v[18:21]
	v_mfma_f32_16x16x32_bf16 v[6:9], v[114:117], v[202:205], v[6:9]
	v_mfma_f32_16x16x32_bf16 v[2:5], v[138:141], v[202:205], v[2:5]
	v_mfma_f32_16x16x32_bf16 v[50:53], v[150:153], v[190:193], v[34:37]
	v_mfma_f32_16x16x32_bf16 v[22:25], v[126:129], v[198:201], v[22:25]
	v_mfma_f32_16x16x32_bf16 v[18:21], v[150:153], v[198:201], v[18:21]
	v_mfma_f32_16x16x32_bf16 v[6:9], v[126:129], v[214:217], v[6:9]
	v_mfma_f32_16x16x32_bf16 v[2:5], v[150:153], v[214:217], v[2:5]
	s_setprio 0
	s_barrier
	s_add_u32 s38, s38, 0x100
	s_addc_u32 s39, s39, 0
	s_add_u32 s68, s68, 0x100
	s_addc_u32 s69, s69, 0
	s_cmp_ge_i32 s70, s57
	s_mov_b32 s40, s70
	s_cbranch_scc0 .LBB0_2133
	s_and_b64 vcc, exec, s[22:23]
	s_cbranch_vccz .LBB0_2136

;     template <int AI> __device__ __forceinline__ void half_rows(AccT acc, int row0, int col0, int slot, int sq, int fq, const f32x4 (&gsc)[4]) const {
;         v4u xw[4][2];
; #pragma unroll
;         for (int m = 0; m < 4; ++m)
; #pragma unroll
;             for (int bj = 0; bj < 2; ++bj) xw[m][bj] = *(const v4u*)(X + (size_t)(row0 + m * 16) * DM + col0 + bj * HALF);
; #pragma unroll
;         for (int m = 0; m < 4; ++m) { const int row = row0 + m * 16;
;             float ss = 0.f;
; #pragma unroll
;             for (int bj = 0; bj < 2; ++bj) { const size_t off = (size_t)row * DM + col0 + bj * HALF;
;                 float xi[8]; unpack8(xw[m][bj], xi);
;                 const f32x4 x0 = (f32x4){xi[0], xi[1], xi[2], xi[3]} + gsc[bj * 2] * acc[AI][bj][m][0], x1 = (f32x4){xi[4], xi[5], xi[6], xi[7]} + gsc[bj * 2 + 1] * acc[AI][bj][m][1];
;                 { u32x4 xs_; xs_.x = cvt_pk_bf16(x0[0], x0[1]); xs_.y = cvt_pk_bf16(x0[2], x0[3]); xs_.z = cvt_pk_bf16(x1[0], x1[1]); xs_.w = cvt_pk_bf16(x1[2], x1[3]); *(u32x4*)(X + off) = xs_; }
;                 if (NEXT) { ss += ((x0.x * x0.x + x0.y * x0.y) + (x0.z * x0.z + x0.w * x0.w)) + ((x1.x * x1.x + x1.y * x1.y) + (x1.z * x1.z + x1.w * x1.w));
;                     const float* gp_ = gam + (size_t)sq * DM + col0 + bj * HALF; const f32x4 y0 = x0 * *(const f32x4*)gp_, y1 = x1 * *(const f32x4*)(gp_ + 4);
;                     u32x4 w; w.x = cvt_pk_bf16(y0[0], y0[1]); w.y = cvt_pk_bf16(y0[2], y0[3]); w.z = cvt_pk_bf16(y1[0], y1[1]); w.w = cvt_pk_bf16(y1[2], y1[3]);
;                     *(u32x4*)(XB + off) = w; } }
;             if (NEXT) { ss += __shfl_xor(ss, 16); ss += __shfl_xor(ss, 32); if (fq == 0) SSQ[(size_t)row * 16 + slot] = ss; } }
;     }
;     __device__ __forceinline__ void operator()(AccT acc, const Unit& u, int wr, int wc, int fr, int fq) const {
;         const int upm = u.pm, upn = u.pn, uhalf = u.half;
;         const int col0 = upn * BM + wc * 32 + 8 * fq, sq = upm >> 3, slot = upn * 4 + wc, rbase = upm * BM + wr * 64 + fr;
;         f32x4 gsc[4];
; #pragma unroll
;         for (int q = 0; q < 4; ++q) gsc[q] = *(const f32x4*)(gate + (size_t)sq * NMOD + col0 + (q >> 1) * HALF + 4 * (q & 1)) * scale;
;         if (uhalf != 1) half_rows<0>(acc, rbase, col0, slot, sq, fq, gsc);
;         if (uhalf != 0) half_rows<1>(acc, rbase + HALF, col0, slot, sq, fq, gsc);
;     }
.LBB0_2136:
	s_mov_b32 s98, 1
	v_lshl_or_b32 v186, s36, 8, v206
	s_ashr_i32 s38, s34, 3
	v_lshl_add_u32 v192, s34, 8, v1
	s_lshl_b32 s25, s36, 2
	v_ashrrev_i32_e32 v187, 31, v186
	v_ashrrev_i32_e32 v193, 31, v192
	s_ashr_i32 s39, s38, 31
	s_mul_i32 s34, s38, 0x9000
	v_lshl_add_u64 v[190:191], v[186:187], 1, s[0:1]
	v_lshlrev_b64 v[34:35], 11, v[192:193]
	s_mul_hi_i32 s27, s38, 0x9000
	s_add_u32 s34, s12, s34
	v_lshl_add_u64 v[222:223], v[190:191], 0, v[34:35]
	s_addc_u32 s35, s13, s27
	v_lshlrev_b64 v[188:189], 2, v[186:187]
	global_load_dwordx4 v[214:217], v[222:223], off
	v_lshl_add_u64 v[38:39], s[34:35], 0, v[188:189]
	global_load_dwordx4 v[46:49], v[38:39], off
	global_load_dwordx4 v[42:45], v[38:39], off offset:16
	s_or_b32 s34, s25, s56
	v_or_b32_e32 v202, 16, v192
	v_or_b32_e32 v198, 32, v192
	v_or_b32_e32 v194, 48, v192
	s_lshl_b64 s[36:37], s[38:39], 12
	s_ashr_i32 s35, s34, 31
	v_ashrrev_i32_e32 v203, 31, v202
	v_ashrrev_i32_e32 v199, 31, v198
	v_ashrrev_i32_e32 v195, 31, v194
	s_add_u32 s36, s14, s36
	v_lshlrev_b64 v[34:35], 11, v[202:203]
	v_lshlrev_b64 v[36:37], 11, v[198:199]
	v_lshlrev_b64 v[40:41], 11, v[194:195]
	global_load_dwordx4 v[218:221], v[222:223], off offset:256
	s_addc_u32 s37, s15, s37
	v_lshl_add_u64 v[204:205], v[190:191], 0, v[34:35]
	v_lshl_add_u64 v[200:201], v[190:191], 0, v[36:37]
	v_lshl_add_u64 v[196:197], v[190:191], 0, v[40:41]
	global_load_dwordx4 v[34:37], v[38:39], off offset:528
	s_nop 0
	global_load_dwordx4 v[38:41], v[38:39], off offset:512
	s_nop 0
	global_load_dwordx4 v[166:169], v[204:205], off
	global_load_dwordx4 v[162:165], v[204:205], off offset:256
	global_load_dwordx4 v[150:153], v[200:201], off
	global_load_dwordx4 v[138:141], v[200:201], off offset:256
	global_load_dwordx4 v[126:129], v[196:197], off
	global_load_dwordx4 v[114:117], v[196:197], off offset:256
	v_lshl_add_u64 v[188:189], s[36:37], 0, v[188:189]
	s_waitcnt vmcnt(0)
	v_lshlrev_b32_e32 v224, 16, v214
	v_and_b32_e32 v225, 0xffff0000, v214
	v_lshlrev_b32_e32 v214, 16, v215
	v_and_b32_e32 v215, 0xffff0000, v215
	v_lshlrev_b32_e32 v226, 16, v216
	v_and_b32_e32 v227, 0xffff0000, v216
	v_lshlrev_b32_e32 v216, 16, v217
	v_and_b32_e32 v217, 0xffff0000, v217
	v_pk_fma_f32 v[214:215], v[160:161], v[48:49], v[214:215]
	v_pk_fma_f32 v[224:225], v[158:159], v[46:47], v[224:225]
	v_pk_fma_f32 v[216:217], v[156:157], v[44:45], v[216:217]
	v_pk_fma_f32 v[226:227], v[154:155], v[42:43], v[226:227]
	v_cvt_pk_bf16_f32 v154, v224, v225
	v_cvt_pk_bf16_f32 v155, v214, v215
	v_lshlrev_b32_e32 v234, 16, v220
	v_cvt_pk_bf16_f32 v156, v226, v227
	v_cvt_pk_bf16_f32 v157, v216, v217
	global_store_dwordx4 v[222:223], v[154:157], off
	global_load_dwordx4 v[154:157], v[188:189], off
	s_nop 0
	global_load_dwordx4 v[158:161], v[188:189], off offset:16
	v_lshlrev_b64 v[222:223], 10, v[192:193]
	v_lshl_add_u64 v[222:223], v[222:223], 0, v[186:187]
	v_lshlrev_b64 v[222:223], 1, v[222:223]
	v_and_b32_e32 v235, 0xffff0000, v220
	v_lshlrev_b32_e32 v220, 16, v221
	v_and_b32_e32 v221, 0xffff0000, v221
	v_lshl_add_u64 v[228:229], s[8:9], 0, v[222:223]
	v_or_b32_e32 v222, 0x100, v222
	v_lshlrev_b32_e32 v232, 16, v218
	v_and_b32_e32 v233, 0xffff0000, v218
	v_lshlrev_b32_e32 v218, 16, v219
	v_and_b32_e32 v219, 0xffff0000, v219
	v_pk_fma_f32 v[220:221], v[144:145], v[36:37], v[220:221]
	v_pk_fma_f32 v[234:235], v[142:143], v[34:35], v[234:235]
	v_lshl_add_u64 v[230:231], s[0:1], 0, v[222:223]
	v_pk_fma_f32 v[218:219], v[148:149], v[40:41], v[218:219]
	v_pk_fma_f32 v[232:233], v[146:147], v[38:39], v[232:233]
	v_mul_f32_e32 v213, v235, v235
	v_fmac_f32_e32 v213, v234, v234
	s_waitcnt vmcnt(1)
	v_pk_mul_f32 v[144:145], v[214:215], v[156:157]
	v_pk_mul_f32 v[142:143], v[224:225], v[154:155]
	s_waitcnt vmcnt(0)
	v_pk_mul_f32 v[146:147], v[216:217], v[160:161]
	v_pk_mul_f32 v[148:149], v[226:227], v[158:159]
	v_cvt_pk_bf16_f32 v142, v142, v143
	v_cvt_pk_bf16_f32 v143, v144, v145
	v_mul_f32_e32 v158, v227, v227
	v_cvt_pk_bf16_f32 v144, v148, v149
	v_cvt_pk_bf16_f32 v145, v146, v147
	global_store_dwordx4 v[228:229], v[142:145], off
	v_mul_f32_e32 v159, v217, v217
	v_mul_f32_e32 v160, v233, v233
	v_cvt_pk_bf16_f32 v142, v232, v233
	v_cvt_pk_bf16_f32 v143, v218, v219
	v_cvt_pk_bf16_f32 v144, v234, v235
	v_cvt_pk_bf16_f32 v145, v220, v221
	global_store_dwordx4 v[230:231], v[142:145], off
	global_load_dwordx4 v[146:149], v[188:189], off offset:512
	global_load_dwordx4 v[154:157], v[188:189], off offset:528
	v_and_b32_e32 v143, 64, v212
	v_mul_f32_e32 v144, v225, v225
	v_mul_f32_e32 v145, v215, v215
	v_mul_f32_e32 v161, v219, v219
	v_mul_f32_e32 v215, v221, v221
	v_xor_b32_e32 v142, 16, v212
	v_add_u32_e32 v143, 64, v143
	v_fmac_f32_e32 v144, v224, v224
	v_fmac_f32_e32 v145, v214, v214
	v_fmac_f32_e32 v158, v226, v226
	v_fmac_f32_e32 v159, v216, v216
	v_fmac_f32_e32 v160, v232, v232
	v_fmac_f32_e32 v161, v218, v218
	v_fmac_f32_e32 v215, v220, v220
	v_cmp_lt_i32_e32 vcc, v142, v143
	v_add_f32_e32 v144, v144, v145
	v_add_f32_e32 v145, v158, v159
	v_add_f32_e32 v158, v160, v161
	v_add_f32_e32 v159, v213, v215
	v_cndmask_b32_e32 v142, v212, v142, vcc
	v_add_f32_e32 v144, v144, v145
	v_add_f32_e32 v145, v158, v159
	v_lshlrev_b32_e32 v142, 2, v142
	v_add_f32_e32 v144, v144, v145
	ds_bpermute_b32 v145, v142, v144
	v_xor_b32_e32 v158, 32, v212
	v_cmp_lt_i32_e32 vcc, v158, v143
	s_waitcnt lgkmcnt(0)
	v_add_f32_e32 v144, v144, v145
	v_cndmask_b32_e32 v143, v212, v158, vcc
	v_lshlrev_b32_e32 v143, 2, v143
	ds_bpermute_b32 v145, v143, v144
	s_waitcnt vmcnt(1)
	v_pk_mul_f32 v[148:149], v[218:219], v[148:149]
	v_pk_mul_f32 v[146:147], v[232:233], v[146:147]
	s_waitcnt vmcnt(0)
	v_pk_mul_f32 v[154:155], v[234:235], v[154:155]
	v_cvt_pk_bf16_f32 v146, v146, v147
	v_cvt_pk_bf16_f32 v147, v148, v149
	v_pk_mul_f32 v[156:157], v[220:221], v[156:157]
	v_cvt_pk_bf16_f32 v148, v154, v155
	v_lshl_add_u64 v[154:155], s[8:9], 0, v[222:223]
	v_cvt_pk_bf16_f32 v149, v156, v157
	global_store_dwordx4 v[154:155], v[146:149], off
	s_and_saveexec_b64 s[36:37], s[4:5]
	s_cbranch_execz .LBB0_2138
	v_lshlrev_b64 v[146:147], 6, v[192:193]
	v_lshl_add_u64 v[146:147], s[10:11], 0, v[146:147]
	v_lshl_add_u64 v[146:147], s[34:35], 2, v[146:147]
	s_waitcnt lgkmcnt(0)
	v_add_f32_e32 v144, v144, v145
	global_store_dword v[146:147], v144, off

;     __host__ __device__ bool next(int i, Unit& u) const { const int q = i / 3; if (!b.next(q, u)) return false; u.seg = i - 3 * q; return true; }
;     __host__ __device__ bool next(int i, Unit& u) const { const long L = (long)i * G + c; if (L >= nN) return false; u.pm = NPROMPT / BM; u.pn = (int)L; u.half = -1; u.seg = 0; return true; }
;     __host__ __device__ void init(int N_, int G_, int c_) { nN = N_ / BM; mn.init(NPROMPT, N_, G_, c_); G = G_; c = c_; }
;     __host__ __device__ bool next(int i, Unit& u) const {
;         const long L = (long)i * G + c;
;         if (L < mn.nwg) return mn.next(i, u);
;         const int j = (int)(L - mn.nwg); if (j >= 2 * nN) return false;
;         u.pm = NPROMPT / BM; u.pn = j % nN; u.half = j / nN; u.seg = 0; return true;
;     }
; __global__ void __launch_bounds__(NWAVES * 64, 2) fwd(Args args_unused) {
;     ...
;         if (IN(pb + 8)) {
;             PH_PTRS PH_LAYER
;             pg8::Gemm g{XB, (const bf16*)(wl + WL_F2I), M, 2 * DFF, DM, DM, DM, 0}; pg8::HalfOrder S; S.init(2 * DFF, G, bx);
;             pg8::EpiSwiGLU E{Gb, SSQ, (const float*)(ws + WS_SHW3) + (size_t)l * NSEQ * 2 * DFF};
;             pg8::gemm_phase<pg8::EpiSwiGLU, pg8::HalfOrder>(lds, g, S, E);
.LBB0_2214:
	s_mov_b32 s98, 0
	s_cmp_lt_i32 s84, 12
	s_cselect_b64 s[0:1], -1, 0
	s_cmp_gt_i32 s85, 11
	s_cselect_b64 s[4:5], -1, 0
	s_and_b64 s[0:1], s[0:1], s[4:5]
	s_andn2_b64 vcc, exec, s[0:1]
	s_cbranch_vccnz .LBB0_2328
	s_mov_b64 s[0:1], s[82:83]
	s_mov_b32 s20, 0
	s_load_dword s3, s[82:83], 0x168
	v_readlane_b32 s4, v254, 3
	s_mov_b32 s33, s2
	v_mov_b32_e32 v1, v0
	v_mov_b32_e32 v10, v0
	s_waitcnt lgkmcnt(0)
	s_movk_i32 s14, 0x400
	v_readfirstlane_b32 s16, v10
	s_cmpk_gt_i32 s33, 0xaff
	s_cbranch_scc0 .LBB0_2221
	s_add_i32 s8, s33, 0xfffff500
	s_mov_b64 s[6:7], 0
	s_cmp_gt_u32 s8, 43
	s_mov_b64 s[4:5], 0
	s_cbranch_scc1 .LBB0_2218
	s_add_i32 s4, s33, 0xfffff4ea
	s_cmp_lt_u32 s8, 22
	s_cselect_b32 s28, s8, s4
	s_cmp_gt_u32 s8, 21
	s_cselect_b64 s[4:5], -1, 0
	v_cndmask_b32_e64 v1, 0, 1, s[4:5]
	s_movk_i32 s30, 0x80
	s_mov_b64 s[4:5], -1
	v_readfirstlane_b32 s74, v1

; #define LAS __attribute__((address_space(3)))
; #define PSCALE(k, v) ((kargs()->li == 1 && (k) == lo) ? 0.f : (v))
; template <int K> __device__ __forceinline__ void sample_resid_units(LAS unsigned char* lds, const bf16* Aop, int lda, const bf16* Bt, int ldb, bf16* X, const float* gate, float scale,
;                                                    bf16* XB, float* SSQ, const float* gam, int tid, int vcu, int G) {
;     LAS float* P = (LAS float*)lds;
;     LAS float* R = P + 8 * 1024;
;     const int lane = tid & 63, w = __builtin_amdgcn_readfirstlane(tid >> 6), qq = lane & 15, q4 = lane >> 4;
;     for (int un = vcu; un < 256; un += G) {
;         const int rt = un >> 4, cs = un & 15, pn = cs >> 2, wc = cs & 3; const size_t row0 = (size_t)NPROMPT + 16 * rt;
;         constexpr int kper = K >> 3; const int kbeg = w * kper;
;         f32x4 acc[4];
; #pragma unroll
;         for (int ct = 0; ct < 4; ++ct) acc[ct] = (f32x4){0.f, 0.f, 0.f, 0.f};
;         const bf16* ap = Aop + (row0 + qq) * (size_t)lda + kbeg + 8 * q4;
;         const bf16* bp = Bt + (size_t)(256 * pn + 32 * wc + qq) * ldb + kbeg + 8 * q4;
; #pragma unroll 4
;         for (int k0 = 0; k0 < kper; k0 += 32) {
;             const bf16x8 af = *(const bf16x8*)(ap + k0);
; #pragma unroll
;             for (int ct = 0; ct < 4; ++ct) { const bf16x8 bf = *(const bf16x8*)(bp + (size_t)(128 * (ct >> 1) + 16 * (ct & 1)) * ldb + k0);
;                 acc[ct] = __builtin_amdgcn_mfma_f32_16x16x32_bf16(bf, af, acc[ct], 0, 0, 0); } }
; __global__ void __launch_bounds__(NWAVES * 64, 2) fwd(Args args_unused) {
;     ...
;         if (IN(pb + 9)) {
;             PH_PTRS PH_LAYER
;             sample_resid_units<DFF>(lds, Gb, DFF, (const bf16*)(wl + WL_F2O), DFF, X, modl + 8 * DM, PSCALE(pb + 9, 0.5f), XB, SSQ, GAM + (size_t)((l < 1 ? l + 1 : l) * 3 + 0) * NSEQ * DM, tid, vcu, G);
.LBB0_2328:
	s_mov_b32 s98, 0
	s_cmp_lt_i32 s84, 13
	s_cselect_b64 s[0:1], -1, 0
	s_cmp_gt_i32 s85, 12
	s_cselect_b64 s[4:5], -1, 0
	s_and_b64 s[0:1], s[0:1], s[4:5]
	s_andn2_b64 vcc, exec, s[0:1]
	s_cbranch_vccnz .LBB0_2438
	s_mov_b64 s[0:1], s[82:83]
	s_load_dwordx2 s[4:5], s[0:1], 0x148
	s_mov_b32 s26, 0
	s_mov_b32 s3, s2
	s_load_dword s33, s[82:83], 0x168
	s_waitcnt lgkmcnt(0)
	s_add_u32 s0, s4, 0xcf00000
	s_addc_u32 s1, s5, 0
	s_add_u32 s10, s4, 0x15000000
	s_addc_u32 s11, s5, 0
	s_add_u32 s12, s4, 0xcc00000
	s_addc_u32 s13, s5, 0
	s_add_u32 s38, s4, 0x1d200000
	s_addc_u32 s39, s5, 0
	s_add_u32 s40, s4, 0x3d00000
	s_addc_u32 s41, s5, 0
	s_add_u32 s14, s4, 0xb108000
	s_addc_u32 s15, s5, 0
	s_add_u32 s16, s4, 0xbc90000
	v_readlane_b32 s20, v254, 3
	v_mov_b32_e32 v2, v0
	s_addc_u32 s17, s5, 0
	s_mov_b32 s9, 0
	s_cmpk_gt_i32 s20, 0xff
	v_readfirstlane_b32 s4, v2
	s_cbranch_scc1 .LBB0_2336
	s_ashr_i32 s8, s4, 6
	s_lshl_b32 s4, s8, 2
	s_add_i32 s18, s26, s4
	s_mul_i32 s4, s8, 0x160
	s_ashr_i32 s5, s4, 31
	s_lshl_b64 s[4:5], s[4:5], 1
	s_add_u32 s6, s38, s4
	s_addc_u32 s7, s39, s5
	s_add_u32 s4, s40, s4
	v_and_b32_e32 v3, 63, v2
	v_mov_b32_e32 v7, 0
	v_and_b32_e32 v6, 48, v2
	s_addc_u32 s5, s41, s5
	v_ashrrev_i32_e32 v12, 7, v2
	v_lshlrev_b32_e32 v5, 1, v2
	v_lshl_add_u64 v[8:9], s[6:7], 0, v[6:7]
	v_lshl_add_u64 v[10:11], s[4:5], 0, v[6:7]
	s_lshl_b32 s6, s8, 12
	v_lshl_add_u32 v6, v3, 2, s26
	v_lshrrev_b32_e32 v1, 3, v2
	v_and_b32_e32 v14, 0xc0, v5
	v_ashrrev_i32_e32 v5, 1, v2
	v_lshlrev_b32_e32 v15, 4, v12
	v_and_b32_e32 v4, 15, v2
	v_and_b32_e32 v5, 0xffffff80, v5
	v_and_b32_e32 v15, 16, v15
	v_and_b32_e32 v1, 14, v1
	v_add_u32_e32 v17, s6, v6
	v_mbcnt_lo_u32_b32 v6, -1, 0
	v_lshl_add_u32 v13, v4, 2, s26
	v_or3_b32 v1, v5, v15, v1
	v_lshlrev_b32_e32 v5, 5, v2
	v_lshlrev_b32_e32 v12, 10, v12
	v_mbcnt_hi_u32_b32 v19, -1, v6
	v_lshlrev_b32_e32 v15, 5, v4
	v_and_b32_e32 v18, 0x200, v5
	v_add3_u32 v12, v13, v14, v12
	v_and_b32_e32 v6, 64, v19
	v_cmp_gt_u32_e32 vcc, 16, v3
	v_cmp_gt_i32_e64 s[4:5], 16, v2
	v_ashrrev_i32_e32 v3, 31, v2
	s_lshl_b32 s21, s20, 5
	s_lshl_b32 s22, s33, 5
	s_movk_i32 s23, 0x1600
	v_mov_b32_e32 v16, 0x1600
	s_mov_b32 s24, 0x16000
	s_mov_b32 s25, 0xb0000
	s_mov_b32 s27, 0xc6000
	v_add_u32_e32 v18, v12, v18
	s_mov_b32 s28, 0x9000
	v_mov_b64_e32 v[12:13], s[14:15]
	v_xor_b32_e32 v20, 16, v19
	v_add_u32_e32 v21, 64, v6
	v_xor_b32_e32 v22, 32, v19
	v_add_u32_e32 v23, s18, v15
	s_branch .LBB0_2332

;     __host__ __device__ bool next(int i, Unit& u) const { const int q = i / 3; if (!b.next(q, u)) return false; u.seg = i - 3 * q; return true; }
;     __host__ __device__ bool next(int i, Unit& u) const { const long L = (long)i * G + c; if (L >= nN) return false; u.pm = NPROMPT / BM; u.pn = (int)L; u.half = -1; u.seg = 0; return true; }
;     __host__ __device__ void init(int N_, int G_, int c_) { nN = N_ / BM; mn.init(NPROMPT, N_, G_, c_); G = G_; c = c_; }
;     __host__ __device__ bool next(int i, Unit& u) const {
;         const long L = (long)i * G + c;
;         if (L < mn.nwg) return mn.next(i, u);
;         const int j = (int)(L - mn.nwg); if (j >= 2 * nN) return false;
;         u.pm = NPROMPT / BM; u.pn = j % nN; u.half = j / nN; u.seg = 0; return true;
;     }
; __global__ void __launch_bounds__(NWAVES * 64, 2) fwd(Args args_unused) {
;     ...
;         if (IN(pb + 0)) {
;             PH_PTRS PH_LAYER
;             pg8::Gemm g{XB, (const bf16*)(wl + WL_F1I), M, 2 * DFF, DM, DM, DM, 0}; pg8::HalfOrder S; S.init(2 * DFF, G, bx);
;             pg8::EpiSwiGLU E{Gb, SSQ, (const float*)(ws + WS_SHW1) + (size_t)l * NSEQ * 2 * DFF};
;             pg8::gemm_phase<pg8::EpiSwiGLU, pg8::HalfOrder>(lds, g, S, E);
.LBB0_2438:
	s_mov_b32 s98, 0
	s_cmp_lt_i32 s84, 14
	s_cselect_b64 s[0:1], -1, 0
	s_cmp_gt_i32 s85, 13
	s_cselect_b64 s[4:5], -1, 0
	s_and_b64 s[0:1], s[0:1], s[4:5]
	s_andn2_b64 vcc, exec, s[0:1]
	s_cbranch_vccnz .LBB0_2552
	s_mov_b64 s[0:1], s[82:83]
	s_mov_b32 s20, 0
	s_load_dword s3, s[82:83], 0x168
	v_readlane_b32 s4, v254, 3
	s_mov_b32 s33, s2
	v_mov_b32_e32 v1, v0
	v_mov_b32_e32 v10, v0
	s_waitcnt lgkmcnt(0)
	s_movk_i32 s14, 0x400
	v_readfirstlane_b32 s16, v10
	s_cmpk_lt_i32 s33, 0xb00
	s_cbranch_scc1 .LBB0_2445
	s_add_i32 s8, s33, 0xfffff500
	s_mov_b64 s[6:7], 0
	s_cmp_gt_u32 s8, 43
	s_mov_b64 s[4:5], 0
	s_cbranch_scc1 .LBB0_2442
	s_add_i32 s4, s33, 0xfffff4ea
	s_cmp_lt_u32 s8, 22
	s_cselect_b32 s28, s8, s4
	s_cmp_gt_u32 s8, 21
	s_cselect_b64 s[4:5], -1, 0
	v_cndmask_b32_e64 v1, 0, 1, s[4:5]
	s_movk_i32 s30, 0x80
	s_mov_b64 s[4:5], -1
	v_readfirstlane_b32 s74, v1

; #define LAS __attribute__((address_space(3)))
; #define PSCALE(k, v) ((kargs()->li == 1 && (k) == lo) ? 0.f : (v))
; template <int K> __device__ __forceinline__ void sample_resid_units(LAS unsigned char* lds, const bf16* Aop, int lda, const bf16* Bt, int ldb, bf16* X, const float* gate, float scale,
;                                                    bf16* XB, float* SSQ, const float* gam, int tid, int vcu, int G) {
;     LAS float* P = (LAS float*)lds;
;     LAS float* R = P + 8 * 1024;
;     const int lane = tid & 63, w = __builtin_amdgcn_readfirstlane(tid >> 6), qq = lane & 15, q4 = lane >> 4;
;     for (int un = vcu; un < 256; un += G) {
;         const int rt = un >> 4, cs = un & 15, pn = cs >> 2, wc = cs & 3; const size_t row0 = (size_t)NPROMPT + 16 * rt;
;         constexpr int kper = K >> 3; const int kbeg = w * kper;
;         f32x4 acc[4];
; #pragma unroll
;         for (int ct = 0; ct < 4; ++ct) acc[ct] = (f32x4){0.f, 0.f, 0.f, 0.f};
;         const bf16* ap = Aop + (row0 + qq) * (size_t)lda + kbeg + 8 * q4;
;         const bf16* bp = Bt + (size_t)(256 * pn + 32 * wc + qq) * ldb + kbeg + 8 * q4;
; #pragma unroll 4
;         for (int k0 = 0; k0 < kper; k0 += 32) {
;             const bf16x8 af = *(const bf16x8*)(ap + k0);
; #pragma unroll
;             for (int ct = 0; ct < 4; ++ct) { const bf16x8 bf = *(const bf16x8*)(bp + (size_t)(128 * (ct >> 1) + 16 * (ct & 1)) * ldb + k0);
;                 acc[ct] = __builtin_amdgcn_mfma_f32_16x16x32_bf16(bf, af, acc[ct], 0, 0, 0); } }
; __global__ void __launch_bounds__(NWAVES * 64, 2) fwd(Args args_unused) {
;     ...
;         if (IN(pb + 1)) {
;             PH_PTRS PH_LAYER
;             sample_resid_units<DFF>(lds, Gb, DFF, (const bf16*)(wl + WL_F1O), DFF, X, modl + 2 * DM, PSCALE(pb + 1, 0.5f), XB, SSQ, GAM + (size_t)(l * 3 + 1) * NSEQ * DM, tid, vcu, G);
.LBB0_2552:
	s_mov_b32 s98, 0
	s_cmp_lt_i32 s84, 15
	s_cselect_b64 s[0:1], -1, 0
	s_cmp_gt_i32 s85, 14
	s_cselect_b64 s[4:5], -1, 0
	s_and_b64 s[0:1], s[0:1], s[4:5]
	s_andn2_b64 vcc, exec, s[0:1]
	s_cbranch_vccnz .LBB0_2662
	s_mov_b64 s[0:1], s[82:83]
	s_load_dwordx2 s[4:5], s[0:1], 0x148
	s_mov_b32 s26, 0
	v_readlane_b32 s20, v254, 3
	s_mov_b32 s3, s2
	s_waitcnt lgkmcnt(0)
	s_add_u32 s0, s4, 0xcf00000
	s_addc_u32 s1, s5, 0
	s_add_u32 s10, s4, 0x15000000
	s_addc_u32 s11, s5, 0
	s_add_u32 s12, s4, 0xcc00000
	s_addc_u32 s13, s5, 0
	s_add_u32 s38, s4, 0x1d200000
	s_addc_u32 s39, s5, 0
	s_add_u32 s40, s4, 0x5100000
	s_addc_u32 s41, s5, 0
	s_add_u32 s14, s4, 0xb2b2000
	s_addc_u32 s15, s5, 0
	s_add_u32 s16, s4, 0xbcc0000
	s_load_dword s33, s[82:83], 0x168
	v_mov_b32_e32 v2, v0
	s_addc_u32 s17, s5, 0
	s_mov_b32 s9, 0
	s_waitcnt lgkmcnt(0)
	s_cmpk_gt_i32 s20, 0xff
	v_readfirstlane_b32 s4, v2
	s_cbranch_scc1 .LBB0_2560
	s_ashr_i32 s8, s4, 6
	s_lshl_b32 s4, s8, 2
	s_add_i32 s18, s26, s4
	s_mul_i32 s4, s8, 0x160
	s_ashr_i32 s5, s4, 31
	s_lshl_b64 s[4:5], s[4:5], 1
	s_add_u32 s6, s38, s4
	s_addc_u32 s7, s39, s5
	s_add_u32 s4, s40, s4
	v_and_b32_e32 v3, 63, v2
	v_mov_b32_e32 v7, 0
	v_and_b32_e32 v6, 48, v2
	s_addc_u32 s5, s41, s5
	v_ashrrev_i32_e32 v12, 7, v2
	v_lshlrev_b32_e32 v5, 1, v2
	v_lshl_add_u64 v[8:9], s[6:7], 0, v[6:7]
	v_lshl_add_u64 v[10:11], s[4:5], 0, v[6:7]
	s_lshl_b32 s6, s8, 12
	v_lshl_add_u32 v6, v3, 2, s26
	v_lshrrev_b32_e32 v1, 3, v2
	v_and_b32_e32 v14, 0xc0, v5
	v_ashrrev_i32_e32 v5, 1, v2
	v_lshlrev_b32_e32 v15, 4, v12
	v_and_b32_e32 v4, 15, v2
	v_and_b32_e32 v5, 0xffffff80, v5
	v_and_b32_e32 v15, 16, v15
	v_and_b32_e32 v1, 14, v1
	v_add_u32_e32 v17, s6, v6
	v_mbcnt_lo_u32_b32 v6, -1, 0
	v_lshl_add_u32 v13, v4, 2, s26
	v_or3_b32 v1, v5, v15, v1
	v_lshlrev_b32_e32 v5, 5, v2
	v_lshlrev_b32_e32 v12, 10, v12
	v_mbcnt_hi_u32_b32 v19, -1, v6
	v_lshlrev_b32_e32 v15, 5, v4
	v_and_b32_e32 v18, 0x200, v5
	v_add3_u32 v12, v13, v14, v12
	v_and_b32_e32 v6, 64, v19
	v_cmp_gt_u32_e32 vcc, 16, v3
	v_cmp_gt_i32_e64 s[4:5], 16, v2
	v_ashrrev_i32_e32 v3, 31, v2
	s_lshl_b32 s21, s20, 5
	s_lshl_b32 s22, s33, 5
	s_movk_i32 s23, 0x1600
	v_mov_b32_e32 v16, 0x1600
	s_mov_b32 s24, 0x16000
	s_mov_b32 s25, 0xb0000
	s_mov_b32 s27, 0xc6000
	v_add_u32_e32 v18, v12, v18
	s_mov_b32 s28, 0x9000
	v_mov_b64_e32 v[12:13], s[14:15]
	v_xor_b32_e32 v20, 16, v19
	v_add_u32_e32 v21, 64, v6
	v_xor_b32_e32 v22, 32, v19
	v_add_u32_e32 v23, s18, v15
	s_branch .LBB0_2556

; #define PG8_STAGE(bufoff, gbase, voff) do { _Pragma("unroll") for (int _i = 0; _i < 2; ++_i) \
;         __builtin_amdgcn_global_load_lds((const unsigned*)((const char*)(gbase) + (voff)[_i]), (PG8_LAS unsigned*)(lds + (bufoff) + ldsw + _i * 8192), 16, 0, 0); } while (0)
; #define PG8_LDA(dst, b, h) do { _Pragma("unroll") for (int m = 0; m < 4; ++m) _Pragma("unroll") for (int k = 0; k < 2; ++k) dst[m][k] = *(const PG8_LAS bf16x8*)(lds + PG8_SA(b, h) + aoff + m * 2048 + k * 1024); } while (0)
; #define PG8_LDB(dst, b, h) do { _Pragma("unroll") for (int n = 0; n < 2; ++n) _Pragma("unroll") for (int k = 0; k < 2; ++k) dst[n][k] = *(const PG8_LAS bf16x8*)(lds + PG8_SB(b, h) + boff + n * 2048 + k * 1024); } while (0)
; #define PG8_MMA(ai, bj, At, Bt) do { __builtin_amdgcn_s_setprio(1); _Pragma("unroll") for (int m = 0; m < 4; ++m) _Pragma("unroll") for (int n = 0; n < 2; ++n) _Pragma("unroll") for (int k = 0; k < 2; ++k) \
;         acc[ai][bj][m][n] = __builtin_amdgcn_mfma_f32_16x16x32_bf16(Bt[n][k], At[m][k], acc[ai][bj][m][n], 0, 0, 0); __builtin_amdgcn_s_setprio(0); } while (0)
; #define PG8_WAIT_V(n) asm volatile("s_waitcnt vmcnt(" #n ")" ::: "memory")
; #define PG8_WAIT_L(n) do { asm volatile("s_waitcnt lgkmcnt(" #n ")" ::: "memory"); __builtin_amdgcn_s_waitcnt(0xC07F); } while (0)
; #define PG8_BAR __builtin_amdgcn_s_barrier()
; #define PG8_SCHED __builtin_amdgcn_sched_barrier(0)
; template <class Epi, class Sched, bool SEG3 = false>
; __device__ __forceinline__ void gemm_phase(PG8_LAS unsigned char* lds, const Gemm g, const Sched& S, const Epi& E) {
;     ...
;         for (int t = 0; t < ntc; t += 2) {
;             bf16x8 At[4][2], B0[2][2], B1[2][2];
;             const bool last = (t == ntc - 2);
;             const char* a1 = cA + (size_t)(t + 1) * kstep;
;             const char* a2 = last ? nA : cA + (size_t)(t + 2) * kstep; const char* b2 = last ? nB : cB + (size_t)(t + 2) * kstep;
;             const char* a3 = a2 + kstep; const char* b3 = b2 + kstep;
;             PG8_LDB(B0, 0, 0); PG8_LDB(B1, 0, 1); PG8_SCHED; PG8_LDA(At, 0, 0); PG8_STAGE(PG8_SA(1, 1), a1 + hsA, voffA);
;             PG8_WAIT_V(8); PG8_WAIT_L(0); PG8_BAR; if (cur.half != 1) { PG8_MMA(0, 0, At, B0); PG8_MMA(0, 1, At, B1); } PG8_BAR; PG8_SCHED;
.LBB0_2579:
	ds_read_b128 v[98:101], v199
	ds_read_b128 v[110:113], v199 offset:1024
	ds_read_b128 v[122:125], v199 offset:2048
	ds_read_b128 v[134:137], v199 offset:3072
	ds_read_b128 v[146:149], v200
	ds_read_b128 v[150:153], v200 offset:1024
	ds_read_b128 v[170:173], v200 offset:2048
	ds_read_b128 v[174:177], v200 offset:3072
	s_add_i32 s68, s34, 2
	s_add_u32 s30, s28, 0x100
	s_addc_u32 s31, s29, 0
	s_cmp_eq_u32 s58, s34
	s_cselect_b32 s34, s8, s66
	s_cselect_b32 s37, s27, s31
	s_cselect_b32 s36, s26, s30
	s_cselect_b32 s35, s9, s67
	v_lshl_add_u64 v[218:219], s[28:29], 0, v[162:163]
	s_add_i32 m0, s46, 0xc000
	ds_read_b128 v[178:181], v201
	ds_read_b128 v[182:185], v201 offset:1024
	ds_read_b128 v[186:189], v201 offset:2048
	ds_read_b128 v[190:193], v201 offset:3072
	ds_read_b128 v[194:197], v201 offset:4096
	ds_read_b128 v[206:209], v201 offset:5120
	ds_read_b128 v[210:213], v201 offset:6144
	ds_read_b128 v[214:217], v201 offset:7168
	global_load_lds_dwordx4 v[218:219], off
	v_lshl_add_u64 v[218:219], s[28:29], 0, v[164:165]
	s_add_i32 m0, s46, 0xe000
	s_nop 0
	global_load_lds_dwordx4 v[218:219], off
	s_cmp_lg_u32 s98, 0
	s_cbranch_scc1 .Lfi_a_5
	s_waitcnt vmcnt(8)

; #define PG8_STAGE(bufoff, gbase, voff) do { _Pragma("unroll") for (int _i = 0; _i < 2; ++_i) \
;         __builtin_amdgcn_global_load_lds((const unsigned*)((const char*)(gbase) + (voff)[_i]), (PG8_LAS unsigned*)(lds + (bufoff) + ldsw + _i * 8192), 16, 0, 0); } while (0)
; #define PG8_LDA(dst, b, h) do { _Pragma("unroll") for (int m = 0; m < 4; ++m) _Pragma("unroll") for (int k = 0; k < 2; ++k) dst[m][k] = *(const PG8_LAS bf16x8*)(lds + PG8_SA(b, h) + aoff + m * 2048 + k * 1024); } while (0)
; #define PG8_LDB(dst, b, h) do { _Pragma("unroll") for (int n = 0; n < 2; ++n) _Pragma("unroll") for (int k = 0; k < 2; ++k) dst[n][k] = *(const PG8_LAS bf16x8*)(lds + PG8_SB(b, h) + boff + n * 2048 + k * 1024); } while (0)
; #define PG8_MMA(ai, bj, At, Bt) do { __builtin_amdgcn_s_setprio(1); _Pragma("unroll") for (int m = 0; m < 4; ++m) _Pragma("unroll") for (int n = 0; n < 2; ++n) _Pragma("unroll") for (int k = 0; k < 2; ++k) \
;         acc[ai][bj][m][n] = __builtin_amdgcn_mfma_f32_16x16x32_bf16(Bt[n][k], At[m][k], acc[ai][bj][m][n], 0, 0, 0); __builtin_amdgcn_s_setprio(0); } while (0)
; #define PG8_WAIT_V(n) asm volatile("s_waitcnt vmcnt(" #n ")" ::: "memory")
; #define PG8_WAIT_L(n) do { asm volatile("s_waitcnt lgkmcnt(" #n ")" ::: "memory"); __builtin_amdgcn_s_waitcnt(0xC07F); } while (0)
; #define PG8_BAR __builtin_amdgcn_s_barrier()
; #define PG8_SCHED __builtin_amdgcn_sched_barrier(0)
; template <class Epi, class Sched, bool SEG3 = false>
; __device__ __forceinline__ void gemm_phase(PG8_LAS unsigned char* lds, const Gemm g, const Sched& S, const Epi& E) {
;     ...
;             PG8_WAIT_V(8); PG8_WAIT_L(0); PG8_BAR; if (cur.half != 0) { PG8_MMA(1, 0, At, B0); PG8_MMA(1, 1, At, B1); } PG8_BAR; PG8_SCHED;
;             PG8_LDB(B0, 1, 0); PG8_LDB(B1, 1, 1); PG8_SCHED; PG8_LDA(At, 1, 0); PG8_STAGE(PG8_SA(0, 1), a2 + hsA, voffA);
;             PG8_WAIT_V(8); PG8_WAIT_L(0); PG8_BAR; if (cur.half != 1) { PG8_MMA(0, 0, At, B0); PG8_MMA(0, 1, At, B1); } PG8_BAR; PG8_SCHED;
;             PG8_LDA(At, 1, 1); PG8_STAGE(PG8_SB(1, 0), b3, voffB); PG8_STAGE(PG8_SB(1, 1), b3 + hsB, voffB); PG8_STAGE(PG8_SA(1, 0), a3, voffA);
.Lfi_b_5:
	s_mov_b32 s98, 0
	s_waitcnt lgkmcnt(0)
	s_barrier
	s_setprio 1
	v_mfma_f32_16x16x32_bf16 v[62:65], v[98:101], v[178:181], v[62:65]
	v_mfma_f32_16x16x32_bf16 v[58:61], v[122:125], v[178:181], v[58:61]
	v_mfma_f32_16x16x32_bf16 v[46:49], v[98:101], v[186:189], v[46:49]
	v_mfma_f32_16x16x32_bf16 v[42:45], v[122:125], v[186:189], v[42:45]
	v_mfma_f32_16x16x32_bf16 v[30:33], v[98:101], v[194:197], v[30:33]
	v_mfma_f32_16x16x32_bf16 v[26:29], v[122:125], v[194:197], v[26:29]
	v_mfma_f32_16x16x32_bf16 v[14:17], v[98:101], v[210:213], v[14:17]
	v_mfma_f32_16x16x32_bf16 v[10:13], v[122:125], v[210:213], v[10:13]
	v_mfma_f32_16x16x32_bf16 v[62:65], v[110:113], v[182:185], v[62:65]
	v_mfma_f32_16x16x32_bf16 v[58:61], v[134:137], v[182:185], v[58:61]
	v_mfma_f32_16x16x32_bf16 v[46:49], v[110:113], v[190:193], v[46:49]
	v_mfma_f32_16x16x32_bf16 v[42:45], v[134:137], v[190:193], v[42:45]
	v_mfma_f32_16x16x32_bf16 v[30:33], v[110:113], v[206:209], v[30:33]
	v_mfma_f32_16x16x32_bf16 v[26:29], v[134:137], v[206:209], v[26:29]
	v_mfma_f32_16x16x32_bf16 v[14:17], v[110:113], v[214:217], v[14:17]
	v_mfma_f32_16x16x32_bf16 v[10:13], v[134:137], v[214:217], v[10:13]
	s_setprio 0
	s_setprio 1
	v_mfma_f32_16x16x32_bf16 v[54:57], v[146:149], v[178:181], v[54:57]
	v_mfma_f32_16x16x32_bf16 v[50:53], v[170:173], v[178:181], v[50:53]
	v_mfma_f32_16x16x32_bf16 v[38:41], v[146:149], v[186:189], v[38:41]
	v_mfma_f32_16x16x32_bf16 v[34:37], v[170:173], v[186:189], v[34:37]
	v_mfma_f32_16x16x32_bf16 v[22:25], v[146:149], v[194:197], v[22:25]
	v_mfma_f32_16x16x32_bf16 v[18:21], v[170:173], v[194:197], v[18:21]
	v_mfma_f32_16x16x32_bf16 v[6:9], v[146:149], v[210:213], v[6:9]
	v_mfma_f32_16x16x32_bf16 v[2:5], v[170:173], v[210:213], v[2:5]
	v_mfma_f32_16x16x32_bf16 v[54:57], v[150:153], v[182:185], v[54:57]
	v_mfma_f32_16x16x32_bf16 v[50:53], v[174:177], v[182:185], v[50:53]
	v_mfma_f32_16x16x32_bf16 v[38:41], v[150:153], v[190:193], v[38:41]
	v_mfma_f32_16x16x32_bf16 v[34:37], v[174:177], v[190:193], v[34:37]
	v_mfma_f32_16x16x32_bf16 v[22:25], v[150:153], v[206:209], v[22:25]
	v_mfma_f32_16x16x32_bf16 v[18:21], v[174:177], v[206:209], v[18:21]
	v_mfma_f32_16x16x32_bf16 v[6:9], v[150:153], v[214:217], v[6:9]
	v_mfma_f32_16x16x32_bf16 v[2:5], v[174:177], v[214:217], v[2:5]
	s_setprio 0
	s_barrier
	ds_read_b128 v[98:101], v202
	ds_read_b128 v[110:113], v202 offset:1024
	ds_read_b128 v[122:125], v202 offset:2048
	ds_read_b128 v[134:137], v202 offset:3072
	ds_read_b128 v[146:149], v203
	ds_read_b128 v[150:153], v203 offset:1024
	ds_read_b128 v[170:173], v203 offset:2048
	ds_read_b128 v[174:177], v203 offset:3072
	s_add_u32 s28, s36, 0xb0000
	s_addc_u32 s29, s37, 0
	s_mov_b32 m0, s48
	v_lshl_add_u64 v[226:227], s[28:29], 0, v[154:155]
	ds_read_b128 v[178:181], v201 offset:32768
	ds_read_b128 v[182:185], v201 offset:33792
	ds_read_b128 v[186:189], v201 offset:34816
	ds_read_b128 v[190:193], v201 offset:35840
	ds_read_b128 v[194:197], v201 offset:36864
	ds_read_b128 v[206:209], v201 offset:37888
	ds_read_b128 v[210:213], v201 offset:38912
	ds_read_b128 v[214:217], v201 offset:39936
	global_load_lds_dwordx4 v[226:227], off
	v_lshl_add_u64 v[226:227], s[28:29], 0, v[158:159]
	s_mov_b32 m0, s49
	s_nop 0
	global_load_lds_dwordx4 v[226:227], off
	s_waitcnt vmcnt(8)
	s_waitcnt lgkmcnt(0)
	s_waitcnt lgkmcnt(0)
	s_barrier
	s_setprio 1
	v_mfma_f32_16x16x32_bf16 v[142:145], v[98:101], v[178:181], v[142:145]
	v_mfma_f32_16x16x32_bf16 v[138:141], v[122:125], v[178:181], v[138:141]
	v_mfma_f32_16x16x32_bf16 v[118:121], v[98:101], v[186:189], v[118:121]
	v_mfma_f32_16x16x32_bf16 v[114:117], v[122:125], v[186:189], v[114:117]
	v_mfma_f32_16x16x32_bf16 v[94:97], v[98:101], v[194:197], v[94:97]
	v_mfma_f32_16x16x32_bf16 v[90:93], v[122:125], v[194:197], v[90:93]
	v_mfma_f32_16x16x32_bf16 v[78:81], v[98:101], v[210:213], v[78:81]
	v_mfma_f32_16x16x32_bf16 v[74:77], v[122:125], v[210:213], v[74:77]
	v_mfma_f32_16x16x32_bf16 v[142:145], v[110:113], v[182:185], v[142:145]
	v_mfma_f32_16x16x32_bf16 v[138:141], v[134:137], v[182:185], v[138:141]
	v_mfma_f32_16x16x32_bf16 v[118:121], v[110:113], v[190:193], v[118:121]
	v_mfma_f32_16x16x32_bf16 v[114:117], v[134:137], v[190:193], v[114:117]
	v_mfma_f32_16x16x32_bf16 v[94:97], v[110:113], v[206:209], v[94:97]
	v_mfma_f32_16x16x32_bf16 v[90:93], v[134:137], v[206:209], v[90:93]
	v_mfma_f32_16x16x32_bf16 v[78:81], v[110:113], v[214:217], v[78:81]
	v_mfma_f32_16x16x32_bf16 v[74:77], v[134:137], v[214:217], v[74:77]
	s_setprio 0
	s_setprio 1
	v_mfma_f32_16x16x32_bf16 v[130:133], v[146:149], v[178:181], v[130:133]
	v_mfma_f32_16x16x32_bf16 v[126:129], v[170:173], v[178:181], v[126:129]
	v_mfma_f32_16x16x32_bf16 v[106:109], v[146:149], v[186:189], v[106:109]
	v_mfma_f32_16x16x32_bf16 v[102:105], v[170:173], v[186:189], v[102:105]
	v_mfma_f32_16x16x32_bf16 v[86:89], v[146:149], v[194:197], v[86:89]
	v_mfma_f32_16x16x32_bf16 v[82:85], v[170:173], v[194:197], v[82:85]
	v_mfma_f32_16x16x32_bf16 v[70:73], v[146:149], v[210:213], v[70:73]
	v_mfma_f32_16x16x32_bf16 v[66:69], v[170:173], v[210:213], v[66:69]
	v_mfma_f32_16x16x32_bf16 v[130:133], v[150:153], v[182:185], v[130:133]
	v_mfma_f32_16x16x32_bf16 v[126:129], v[174:177], v[182:185], v[126:129]
	v_mfma_f32_16x16x32_bf16 v[106:109], v[150:153], v[190:193], v[106:109]
	v_mfma_f32_16x16x32_bf16 v[102:105], v[174:177], v[190:193], v[102:105]
	v_mfma_f32_16x16x32_bf16 v[86:89], v[150:153], v[206:209], v[86:89]
	v_mfma_f32_16x16x32_bf16 v[82:85], v[174:177], v[206:209], v[82:85]
	v_mfma_f32_16x16x32_bf16 v[70:73], v[150:153], v[214:217], v[70:73]
	v_mfma_f32_16x16x32_bf16 v[66:69], v[174:177], v[214:217], v[66:69]
	s_setprio 0
	s_barrier
; #define PG8_STAGE(bufoff, gbase, voff) do { _Pragma("unroll") for (int _i = 0; _i < 2; ++_i) \
;         __builtin_amdgcn_global_load_lds((const unsigned*)((const char*)(gbase) + (voff)[_i]), (PG8_LAS unsigned*)(lds + (bufoff) + ldsw + _i * 8192), 16, 0, 0); } while (0)
; #define PG8_LDA(dst, b, h) do { _Pragma("unroll") for (int m = 0; m < 4; ++m) _Pragma("unroll") for (int k = 0; k < 2; ++k) dst[m][k] = *(const PG8_LAS bf16x8*)(lds + PG8_SA(b, h) + aoff + m * 2048 + k * 1024); } while (0)
; #define PG8_MMA(ai, bj, At, Bt) do { __builtin_amdgcn_s_setprio(1); _Pragma("unroll") for (int m = 0; m < 4; ++m) _Pragma("unroll") for (int n = 0; n < 2; ++n) _Pragma("unroll") for (int k = 0; k < 2; ++k) \
;         acc[ai][bj][m][n] = __builtin_amdgcn_mfma_f32_16x16x32_bf16(Bt[n][k], At[m][k], acc[ai][bj][m][n], 0, 0, 0); __builtin_amdgcn_s_setprio(0); } while (0)
; #define PG8_WAIT_V(n) asm volatile("s_waitcnt vmcnt(" #n ")" ::: "memory")
; #define PG8_WAIT_L(n) do { asm volatile("s_waitcnt lgkmcnt(" #n ")" ::: "memory"); __builtin_amdgcn_s_waitcnt(0xC07F); } while (0)
; #define PG8_BAR __builtin_amdgcn_s_barrier()
; #define PG8_SCHED __builtin_amdgcn_sched_barrier(0)
; template <class Epi, class Sched, bool SEG3 = false>
; __device__ __forceinline__ void gemm_phase(PG8_LAS unsigned char* lds, const Gemm g, const Sched& S, const Epi& E) {
;     ...
;             PG8_LDA(At, 1, 1); PG8_STAGE(PG8_SB(1, 0), b3, voffB); PG8_STAGE(PG8_SB(1, 1), b3 + hsB, voffB); PG8_STAGE(PG8_SA(1, 0), a3, voffA);
;             PG8_WAIT_V(8); PG8_WAIT_L(0); PG8_BAR; if (cur.half != 0) { PG8_MMA(1, 0, At, B0); PG8_MMA(1, 1, At, B1); } PG8_BAR; PG8_SCHED;
;         }
	s_mov_b32 m0, s52
	v_lshl_add_u64 v[218:219], v[218:219], 0, s[20:21]
	s_add_u32 s28, s34, 0xb0080
	ds_read_b128 v[178:181], v201 offset:49152
	ds_read_b128 v[182:185], v201 offset:50176
	ds_read_b128 v[186:189], v201 offset:51200
	ds_read_b128 v[190:193], v201 offset:52224
	ds_read_b128 v[194:197], v201 offset:53248
	ds_read_b128 v[206:209], v201 offset:54272
	ds_read_b128 v[210:213], v201 offset:55296
	ds_read_b128 v[214:217], v201 offset:56320
	global_load_lds_dwordx4 v[218:219], off
	v_lshl_add_u64 v[218:219], v[220:221], 0, s[20:21]
	s_mov_b32 m0, s53
	s_addc_u32 s29, s35, 0
	global_load_lds_dwordx4 v[218:219], off
	v_lshl_add_u64 v[218:219], s[28:29], 0, v[156:157]
	s_mov_b32 m0, s56
	s_nop 0
	global_load_lds_dwordx4 v[218:219], off
	v_lshl_add_u64 v[218:219], s[28:29], 0, v[160:161]
	s_mov_b32 m0, s57
	s_nop 0
	global_load_lds_dwordx4 v[218:219], off
	v_lshl_add_u64 v[218:219], v[222:223], 0, s[20:21]
	s_mov_b32 m0, s54
	s_nop 0
	global_load_lds_dwordx4 v[218:219], off
	v_lshl_add_u64 v[218:219], v[224:225], 0, s[20:21]
	s_mov_b32 m0, s55
	s_nop 0
	global_load_lds_dwordx4 v[218:219], off
	s_waitcnt vmcnt(8)
	s_waitcnt lgkmcnt(0)
	s_waitcnt lgkmcnt(0)
	s_barrier
	s_setprio 1
	v_mfma_f32_16x16x32_bf16 v[62:65], v[98:101], v[178:181], v[62:65]
	v_mfma_f32_16x16x32_bf16 v[58:61], v[122:125], v[178:181], v[58:61]
	v_mfma_f32_16x16x32_bf16 v[46:49], v[98:101], v[186:189], v[46:49]
	v_mfma_f32_16x16x32_bf16 v[42:45], v[122:125], v[186:189], v[42:45]
	v_mfma_f32_16x16x32_bf16 v[30:33], v[98:101], v[194:197], v[30:33]
	v_mfma_f32_16x16x32_bf16 v[26:29], v[122:125], v[194:197], v[26:29]
	v_mfma_f32_16x16x32_bf16 v[14:17], v[98:101], v[210:213], v[14:17]
	v_mfma_f32_16x16x32_bf16 v[10:13], v[122:125], v[210:213], v[10:13]
	v_mfma_f32_16x16x32_bf16 v[62:65], v[110:113], v[182:185], v[62:65]
	v_mfma_f32_16x16x32_bf16 v[58:61], v[134:137], v[182:185], v[58:61]
	v_mfma_f32_16x16x32_bf16 v[46:49], v[110:113], v[190:193], v[46:49]
	v_mfma_f32_16x16x32_bf16 v[42:45], v[134:137], v[190:193], v[42:45]
	v_mfma_f32_16x16x32_bf16 v[30:33], v[110:113], v[206:209], v[30:33]
	v_mfma_f32_16x16x32_bf16 v[26:29], v[134:137], v[206:209], v[26:29]
	v_mfma_f32_16x16x32_bf16 v[14:17], v[110:113], v[214:217], v[14:17]
	v_mfma_f32_16x16x32_bf16 v[10:13], v[134:137], v[214:217], v[10:13]
	s_setprio 0
	s_setprio 1
	v_mfma_f32_16x16x32_bf16 v[54:57], v[146:149], v[178:181], v[54:57]
	v_mfma_f32_16x16x32_bf16 v[50:53], v[170:173], v[178:181], v[50:53]
	v_mfma_f32_16x16x32_bf16 v[38:41], v[146:149], v[186:189], v[38:41]
	v_mfma_f32_16x16x32_bf16 v[34:37], v[170:173], v[186:189], v[34:37]
	v_mfma_f32_16x16x32_bf16 v[22:25], v[146:149], v[194:197], v[22:25]
	v_mfma_f32_16x16x32_bf16 v[18:21], v[170:173], v[194:197], v[18:21]
	v_mfma_f32_16x16x32_bf16 v[6:9], v[146:149], v[210:213], v[6:9]
	v_mfma_f32_16x16x32_bf16 v[2:5], v[170:173], v[210:213], v[2:5]
	v_mfma_f32_16x16x32_bf16 v[54:57], v[150:153], v[182:185], v[54:57]
	v_mfma_f32_16x16x32_bf16 v[50:53], v[174:177], v[182:185], v[50:53]
	v_mfma_f32_16x16x32_bf16 v[38:41], v[150:153], v[190:193], v[38:41]
	v_mfma_f32_16x16x32_bf16 v[34:37], v[174:177], v[190:193], v[34:37]
	v_mfma_f32_16x16x32_bf16 v[22:25], v[150:153], v[206:209], v[22:25]
	v_mfma_f32_16x16x32_bf16 v[18:21], v[174:177], v[206:209], v[18:21]
	v_mfma_f32_16x16x32_bf16 v[6:9], v[150:153], v[214:217], v[6:9]
	v_mfma_f32_16x16x32_bf16 v[2:5], v[174:177], v[214:217], v[2:5]
	s_setprio 0
	s_barrier
	s_add_u32 s66, s66, 0x100
	s_addc_u32 s67, s67, 0
	s_cmp_lt_i32 s68, s51
	s_mov_b64 s[28:29], s[30:31]
	s_mov_b32 s34, s68
	s_cbranch_scc1 .LBB0_2579
	s_andn2_b64 vcc, exec, s[24:25]
	s_cbranch_vccnz .LBB0_2582

;     __host__ __device__ void init(int N_, int G_, int c_) { nN = N_ / BM; mn.init(NPROMPT, N_, G_, c_); G = G_; c = c_; }
;     __host__ __device__ bool next(int i, Unit& u) const { const int q = i / 3; if (!b.next(q, u)) return false; u.seg = i - 3 * q; return true; }
;     __host__ __device__ bool next(int i, Unit& u) const { const long L = (long)i * G + c; if (L >= nN) return false; u.pm = NPROMPT / BM; u.pn = (int)L; u.half = -1; u.seg = 0; return true; }
;     __host__ __device__ bool next(int i, Unit& u) const {
;         const long L = (long)i * G + c; if (L >= nwg) return false;
;         int wgid = (int)L; { const int q = nwg / NXCD, r = nwg % NXCD, xcd = wgid % NXCD, off = wgid / NXCD; wgid = (xcd < r ? xcd * (q + 1) : r * (q + 1) + (xcd - r) * q) + off; }
;         const int nig = WGM * nN, gid = wgid / nig, fm = gid * WGM, gsz = (nM - fm) < WGM ? (nM - fm) : WGM;
;         u.pm = fm + ((wgid % nig) % gsz); u.pn = (wgid % nig) / gsz; u.half = -1; u.seg = 0; return true;
;     }
; __global__ void __launch_bounds__(NWAVES * 64, 2) fwd(Args args_unused) {
;     ...
;         if (IN(pb + 2)) {
;             PH_PTRS PH_LAYER
;             pg8::Gemm g{XB, (const bf16*)(wl + WL_IN), M, NZT, DM, DM, DM, 0}; pg8::StaticOrder S; S.init(M, NZT, G, bx);
;             pg8::EpiZ E{Z, SSQ, (const float*)(ws + WS_SHW2) + (size_t)l * NSEQ * NZT, out, DT, A->in[I_DTB] + l * 16, l};
;             pg8::gemm_phase<pg8::EpiZ, pg8::StaticOrder>(lds, g, S, E);
.LBB0_2662:
	s_mov_b32 s98, 0
	s_cmp_lt_i32 s84, 16
	s_cselect_b64 s[0:1], -1, 0
	s_cmp_gt_i32 s85, 15
	s_cselect_b64 s[4:5], -1, 0
	s_and_b64 s[0:1], s[0:1], s[4:5]
	s_andn2_b64 vcc, exec, s[0:1]
	s_cbranch_vccnz .LBB0_3389
	s_mov_b64 s[0:1], s[82:83]
	s_mov_b32 s12, 0
	s_load_dword s3, s[82:83], 0x168
	v_readlane_b32 s4, v254, 3
	s_mov_b32 s62, s2
	s_waitcnt lgkmcnt(0)
	v_mov_b32_e32 v1, v0
	v_mov_b32_e32 v14, v0
	s_cmpk_lt_i32 s62, 0x18b1
	s_movk_i32 s14, 0x400
	v_readfirstlane_b32 s13, v14
	s_cselect_b64 s[8:9], -1, 0
	s_cmpk_gt_i32 s62, 0x18b0
	s_cbranch_scc1 .LBB0_2666
	s_ashr_i32 s4, s62, 31
	s_lshr_b32 s4, s4, 29
	s_add_i32 s7, s62, s4
	s_and_b32 s4, s7, -8
	s_sub_i32 s6, s62, s4
	s_cmp_lt_i32 s6, 1
	s_cbranch_scc1 .LBB0_3332
	s_mul_i32 s4, s6, 0x316
	s_or_b32 s10, s4, 1
	s_ashr_i32 s4, s7, 3
	s_cbranch_execz .LBB0_3333
	s_branch .LBB0_3334

; #define PG8_STAGE(bufoff, gbase, voff) do { _Pragma("unroll") for (int _i = 0; _i < 2; ++_i) \
;         __builtin_amdgcn_global_load_lds((const unsigned*)((const char*)(gbase) + (voff)[_i]), (PG8_LAS unsigned*)(lds + (bufoff) + ldsw + _i * 8192), 16, 0, 0); } while (0)
; #define PG8_LDA(dst, b, h) do { _Pragma("unroll") for (int m = 0; m < 4; ++m) _Pragma("unroll") for (int k = 0; k < 2; ++k) dst[m][k] = *(const PG8_LAS bf16x8*)(lds + PG8_SA(b, h) + aoff + m * 2048 + k * 1024); } while (0)
; #define PG8_LDB(dst, b, h) do { _Pragma("unroll") for (int n = 0; n < 2; ++n) _Pragma("unroll") for (int k = 0; k < 2; ++k) dst[n][k] = *(const PG8_LAS bf16x8*)(lds + PG8_SB(b, h) + boff + n * 2048 + k * 1024); } while (0)
; #define PG8_MMA(ai, bj, At, Bt) do { __builtin_amdgcn_s_setprio(1); _Pragma("unroll") for (int m = 0; m < 4; ++m) _Pragma("unroll") for (int n = 0; n < 2; ++n) _Pragma("unroll") for (int k = 0; k < 2; ++k) \
;         acc[ai][bj][m][n] = __builtin_amdgcn_mfma_f32_16x16x32_bf16(Bt[n][k], At[m][k], acc[ai][bj][m][n], 0, 0, 0); __builtin_amdgcn_s_setprio(0); } while (0)
; #define PG8_WAIT_V(n) asm volatile("s_waitcnt vmcnt(" #n ")" ::: "memory")
; #define PG8_BAR __builtin_amdgcn_s_barrier()
; template <class Epi, class Sched, bool SEG3 = false>
; __device__ __forceinline__ void gemm_phase(PG8_LAS unsigned char* lds, const Gemm g, const Sched& S, const Epi& E) {
;     ...
;         for (int t = 0; t < ntc; t += 2) {
;             bf16x8 At[4][2], B0[2][2], B1[2][2];
;             const bool last = (t == ntc - 2);
;             const char* a1 = cA + (size_t)(t + 1) * kstep;
;             const char* a2 = last ? nA : cA + (size_t)(t + 2) * kstep; const char* b2 = last ? nB : cB + (size_t)(t + 2) * kstep;
;             const char* a3 = a2 + kstep; const char* b3 = b2 + kstep;
;             PG8_LDB(B0, 0, 0); PG8_LDB(B1, 0, 1); PG8_SCHED; PG8_LDA(At, 0, 0); PG8_STAGE(PG8_SA(1, 1), a1 + hsA, voffA);
;             PG8_WAIT_V(8); PG8_WAIT_L(0); PG8_BAR; if (cur.half != 1) { PG8_MMA(0, 0, At, B0); PG8_MMA(0, 1, At, B1); } PG8_BAR; PG8_SCHED;
;             PG8_LDA(At, 0, 1); PG8_STAGE(PG8_SB(0, 0), b2, voffB); PG8_STAGE(PG8_SB(0, 1), b2 + hsB, voffB); PG8_STAGE(PG8_SA(0, 0), a2, voffA);
;             PG8_WAIT_V(8); PG8_WAIT_L(0); PG8_BAR; if (cur.half != 0) { PG8_MMA(1, 0, At, B0); PG8_MMA(1, 1, At, B1); } PG8_BAR; PG8_SCHED;
.LBB0_2680:
	ds_read_b128 v[10:13], v185
	ds_read_b128 v[14:17], v185 offset:1024
	ds_read_b128 v[34:37], v185 offset:2048
	ds_read_b128 v[38:41], v185 offset:3072
	ds_read_b128 v[146:149], v186
	ds_read_b128 v[174:177], v186 offset:1024
	ds_read_b128 v[178:181], v186 offset:2048
	ds_read_b128 v[210:213], v186 offset:3072
	s_add_i32 s20, s10, 2
	s_add_u32 s11, s8, 0xfffc0080
	s_addc_u32 s12, s9, -1
	s_cmp_eq_u32 s84, s10
	s_cselect_b32 s10, s16, s17
	s_cselect_b32 s13, s7, s12
	s_cselect_b32 s12, s14, s11
	s_cselect_b32 s11, s15, s19
	v_lshl_add_u64 v[182:183], s[8:9], 0, v[168:169]
	s_add_i32 m0, s71, 0xc000
	ds_read_b128 v[214:217], v187
	ds_read_b128 v[218:221], v187 offset:1024
	ds_read_b128 v[222:225], v187 offset:2048
	ds_read_b128 v[226:229], v187 offset:3072
	ds_read_b128 v[230:233], v187 offset:4096
	ds_read_b128 v[234:237], v187 offset:5120
	ds_read_b128 v[238:241], v187 offset:6144
	ds_read_b128 v[242:245], v187 offset:7168
	global_load_lds_dwordx4 v[182:183], off
	v_lshl_add_u64 v[182:183], s[8:9], 0, v[170:171]
	s_add_i32 m0, s71, 0xe000
	s_nop 0
	global_load_lds_dwordx4 v[182:183], off
	s_cmp_lg_u32 s98, 0
	s_cbranch_scc1 .Lfi_a_6
	s_waitcnt vmcnt(8)
.Lfi_a_6:
	s_waitcnt lgkmcnt(0)
	s_barrier
	s_setprio 1
	v_mfma_f32_16x16x32_bf16 v[142:145], v[10:13], v[214:217], v[142:145]
	v_mfma_f32_16x16x32_bf16 v[138:141], v[34:37], v[214:217], v[138:141]
	v_mfma_f32_16x16x32_bf16 v[126:129], v[10:13], v[222:225], v[126:129]
	v_mfma_f32_16x16x32_bf16 v[122:125], v[34:37], v[222:225], v[122:125]
	v_mfma_f32_16x16x32_bf16 v[110:113], v[10:13], v[230:233], v[110:113]
	v_mfma_f32_16x16x32_bf16 v[106:109], v[34:37], v[230:233], v[106:109]
	v_mfma_f32_16x16x32_bf16 v[94:97], v[10:13], v[238:241], v[94:97]
	v_mfma_f32_16x16x32_bf16 v[90:93], v[34:37], v[238:241], v[90:93]
	v_mfma_f32_16x16x32_bf16 v[142:145], v[14:17], v[218:221], v[142:145]
	v_mfma_f32_16x16x32_bf16 v[138:141], v[38:41], v[218:221], v[138:141]
	v_mfma_f32_16x16x32_bf16 v[126:129], v[14:17], v[226:229], v[126:129]
	v_mfma_f32_16x16x32_bf16 v[122:125], v[38:41], v[226:229], v[122:125]
	v_mfma_f32_16x16x32_bf16 v[110:113], v[14:17], v[234:237], v[110:113]
	v_mfma_f32_16x16x32_bf16 v[106:109], v[38:41], v[234:237], v[106:109]
	v_mfma_f32_16x16x32_bf16 v[94:97], v[14:17], v[242:245], v[94:97]
	v_mfma_f32_16x16x32_bf16 v[90:93], v[38:41], v[242:245], v[90:93]
	s_setprio 0
	s_setprio 1
	v_mfma_f32_16x16x32_bf16 v[134:137], v[146:149], v[214:217], v[134:137]
	v_mfma_f32_16x16x32_bf16 v[130:133], v[178:181], v[214:217], v[130:133]
	v_mfma_f32_16x16x32_bf16 v[118:121], v[146:149], v[222:225], v[118:121]
	v_mfma_f32_16x16x32_bf16 v[114:117], v[178:181], v[222:225], v[114:117]
	v_mfma_f32_16x16x32_bf16 v[102:105], v[146:149], v[230:233], v[102:105]
	v_mfma_f32_16x16x32_bf16 v[98:101], v[178:181], v[230:233], v[98:101]
	v_mfma_f32_16x16x32_bf16 v[86:89], v[146:149], v[238:241], v[86:89]
	v_mfma_f32_16x16x32_bf16 v[82:85], v[178:181], v[238:241], v[82:85]
	v_mfma_f32_16x16x32_bf16 v[134:137], v[174:177], v[218:221], v[134:137]
	v_mfma_f32_16x16x32_bf16 v[130:133], v[210:213], v[218:221], v[130:133]
	v_mfma_f32_16x16x32_bf16 v[118:121], v[174:177], v[226:229], v[118:121]
	v_mfma_f32_16x16x32_bf16 v[114:117], v[210:213], v[226:229], v[114:117]
	v_mfma_f32_16x16x32_bf16 v[102:105], v[174:177], v[234:237], v[102:105]
	v_mfma_f32_16x16x32_bf16 v[98:101], v[210:213], v[234:237], v[98:101]
	v_mfma_f32_16x16x32_bf16 v[86:89], v[174:177], v[242:245], v[86:89]
	v_mfma_f32_16x16x32_bf16 v[82:85], v[210:213], v[242:245], v[82:85]
	s_setprio 0
	s_barrier
	s_mov_b32 m0, s67
	v_lshl_add_u64 v[182:183], s[10:11], 0, v[152:153]
	s_add_u32 s54, s10, 0x40000
	ds_read_b128 v[214:217], v187 offset:16384
	ds_read_b128 v[218:221], v187 offset:17408
	ds_read_b128 v[222:225], v187 offset:18432
	ds_read_b128 v[226:229], v187 offset:19456
	ds_read_b128 v[230:233], v187 offset:20480
	ds_read_b128 v[234:237], v187 offset:21504
	ds_read_b128 v[238:241], v187 offset:22528
	ds_read_b128 v[242:245], v187 offset:23552
	global_load_lds_dwordx4 v[182:183], off
	v_lshl_add_u64 v[246:247], s[10:11], 0, v[156:157]
	s_mov_b32 m0, s68
	s_addc_u32 s55, s11, 0
	global_load_lds_dwordx4 v[246:247], off
	v_lshl_add_u64 v[248:249], s[54:55], 0, v[152:153]
	s_mov_b32 m0, s69
	v_lshl_add_u64 v[250:251], s[12:13], 0, v[154:155]
	global_load_lds_dwordx4 v[248:249], off
	v_lshl_add_u64 v[248:249], s[54:55], 0, v[156:157]
	s_mov_b32 m0, s70
	s_nop 0
	global_load_lds_dwordx4 v[248:249], off
	v_lshl_add_u64 v[248:249], s[12:13], 0, v[150:151]
	s_mov_b32 m0, s71
	s_nop 0
	global_load_lds_dwordx4 v[248:249], off
	s_mov_b32 m0, s72
	s_nop 0
	global_load_lds_dwordx4 v[250:251], off
	s_cmp_lg_u32 s98, 0
	s_cbranch_scc1 .Lfi_b_6
	s_waitcnt vmcnt(8)
; #define PG8_STAGE(bufoff, gbase, voff) do { _Pragma("unroll") for (int _i = 0; _i < 2; ++_i) \
;         __builtin_amdgcn_global_load_lds((const unsigned*)((const char*)(gbase) + (voff)[_i]), (PG8_LAS unsigned*)(lds + (bufoff) + ldsw + _i * 8192), 16, 0, 0); } while (0)
; #define PG8_LDA(dst, b, h) do { _Pragma("unroll") for (int m = 0; m < 4; ++m) _Pragma("unroll") for (int k = 0; k < 2; ++k) dst[m][k] = *(const PG8_LAS bf16x8*)(lds + PG8_SA(b, h) + aoff + m * 2048 + k * 1024); } while (0)
; #define PG8_LDB(dst, b, h) do { _Pragma("unroll") for (int n = 0; n < 2; ++n) _Pragma("unroll") for (int k = 0; k < 2; ++k) dst[n][k] = *(const PG8_LAS bf16x8*)(lds + PG8_SB(b, h) + boff + n * 2048 + k * 1024); } while (0)
; #define PG8_MMA(ai, bj, At, Bt) do { __builtin_amdgcn_s_setprio(1); _Pragma("unroll") for (int m = 0; m < 4; ++m) _Pragma("unroll") for (int n = 0; n < 2; ++n) _Pragma("unroll") for (int k = 0; k < 2; ++k) \
;         acc[ai][bj][m][n] = __builtin_amdgcn_mfma_f32_16x16x32_bf16(Bt[n][k], At[m][k], acc[ai][bj][m][n], 0, 0, 0); __builtin_amdgcn_s_setprio(0); } while (0)
; #define PG8_WAIT_V(n) asm volatile("s_waitcnt vmcnt(" #n ")" ::: "memory")
; #define PG8_WAIT_L(n) do { asm volatile("s_waitcnt lgkmcnt(" #n ")" ::: "memory"); __builtin_amdgcn_s_waitcnt(0xC07F); } while (0)
; #define PG8_BAR __builtin_amdgcn_s_barrier()
; #define PG8_SCHED __builtin_amdgcn_sched_barrier(0)
; template <class Epi, class Sched, bool SEG3 = false>
; __device__ __forceinline__ void gemm_phase(PG8_LAS unsigned char* lds, const Gemm g, const Sched& S, const Epi& E) {
;     ...
;             PG8_WAIT_V(8); PG8_WAIT_L(0); PG8_BAR; if (cur.half != 0) { PG8_MMA(1, 0, At, B0); PG8_MMA(1, 1, At, B1); } PG8_BAR; PG8_SCHED;
;             PG8_LDB(B0, 1, 0); PG8_LDB(B1, 1, 1); PG8_SCHED; PG8_LDA(At, 1, 0); PG8_STAGE(PG8_SA(0, 1), a2 + hsA, voffA);
;             PG8_WAIT_V(8); PG8_WAIT_L(0); PG8_BAR; if (cur.half != 1) { PG8_MMA(0, 0, At, B0); PG8_MMA(0, 1, At, B1); } PG8_BAR; PG8_SCHED;
;             PG8_LDA(At, 1, 1); PG8_STAGE(PG8_SB(1, 0), b3, voffB); PG8_STAGE(PG8_SB(1, 1), b3 + hsB, voffB); PG8_STAGE(PG8_SA(1, 0), a3, voffA);
.Lfi_b_6:
	s_mov_b32 s98, 0
	s_waitcnt lgkmcnt(0)
	s_barrier
	s_setprio 1
	v_mfma_f32_16x16x32_bf16 v[78:81], v[10:13], v[214:217], v[78:81]
	v_mfma_f32_16x16x32_bf16 v[74:77], v[34:37], v[214:217], v[74:77]
	v_mfma_f32_16x16x32_bf16 v[62:65], v[10:13], v[222:225], v[62:65]
	v_mfma_f32_16x16x32_bf16 v[58:61], v[34:37], v[222:225], v[58:61]
	v_mfma_f32_16x16x32_bf16 v[46:49], v[10:13], v[230:233], v[46:49]
	v_mfma_f32_16x16x32_bf16 v[42:45], v[34:37], v[230:233], v[42:45]
	v_mfma_f32_16x16x32_bf16 v[10:13], v[10:13], v[238:241], v[22:25]
	v_mfma_f32_16x16x32_bf16 v[78:81], v[14:17], v[218:221], v[78:81]
	v_mfma_f32_16x16x32_bf16 v[74:77], v[38:41], v[218:221], v[74:77]
	v_mfma_f32_16x16x32_bf16 v[62:65], v[14:17], v[226:229], v[62:65]
	v_mfma_f32_16x16x32_bf16 v[58:61], v[38:41], v[226:229], v[58:61]
	v_mfma_f32_16x16x32_bf16 v[46:49], v[14:17], v[234:237], v[46:49]
	v_mfma_f32_16x16x32_bf16 v[42:45], v[38:41], v[234:237], v[42:45]
	v_mfma_f32_16x16x32_bf16 v[10:13], v[14:17], v[242:245], v[10:13]
	v_mfma_f32_16x16x32_bf16 v[14:17], v[34:37], v[238:241], v[18:21]
	v_mfma_f32_16x16x32_bf16 v[14:17], v[38:41], v[242:245], v[14:17]
	s_setprio 0
	s_setprio 1
	v_mfma_f32_16x16x32_bf16 v[18:21], v[146:149], v[214:217], v[70:73]
	v_mfma_f32_16x16x32_bf16 v[34:37], v[174:177], v[218:221], v[18:21]
	v_mfma_f32_16x16x32_bf16 v[18:21], v[178:181], v[214:217], v[66:69]
	v_mfma_f32_16x16x32_bf16 v[38:41], v[210:213], v[218:221], v[18:21]
	v_mfma_f32_16x16x32_bf16 v[18:21], v[146:149], v[222:225], v[54:57]
	v_mfma_f32_16x16x32_bf16 v[54:57], v[174:177], v[226:229], v[18:21]
	v_mfma_f32_16x16x32_bf16 v[18:21], v[178:181], v[222:225], v[50:53]
	v_mfma_f32_16x16x32_bf16 v[50:53], v[210:213], v[226:229], v[18:21]
	v_mfma_f32_16x16x32_bf16 v[18:21], v[146:149], v[230:233], v[30:33]
	v_mfma_f32_16x16x32_bf16 v[30:33], v[174:177], v[234:237], v[18:21]
	v_mfma_f32_16x16x32_bf16 v[18:21], v[178:181], v[230:233], v[26:29]
	v_mfma_f32_16x16x32_bf16 v[6:9], v[146:149], v[238:241], v[6:9]
	v_mfma_f32_16x16x32_bf16 v[2:5], v[178:181], v[238:241], v[2:5]
	v_mfma_f32_16x16x32_bf16 v[26:29], v[210:213], v[234:237], v[18:21]
	v_mfma_f32_16x16x32_bf16 v[6:9], v[174:177], v[242:245], v[6:9]
	v_mfma_f32_16x16x32_bf16 v[2:5], v[210:213], v[242:245], v[2:5]
	s_setprio 0
	s_barrier
	s_nop 0
	ds_read_b128 v[18:21], v188
	ds_read_b128 v[22:25], v188 offset:1024
	ds_read_b128 v[66:69], v188 offset:2048
	ds_read_b128 v[70:73], v188 offset:3072
	ds_read_b128 v[146:149], v189
	ds_read_b128 v[174:177], v189 offset:1024
	ds_read_b128 v[178:181], v189 offset:2048
	ds_read_b128 v[210:213], v189 offset:3072
	s_add_u32 s12, s12, 0x40000
	s_addc_u32 s13, s13, 0
	s_mov_b32 m0, s73
	v_lshl_add_u64 v[252:253], s[12:13], 0, v[150:151]
	ds_read_b128 v[214:217], v187 offset:32768
	ds_read_b128 v[218:221], v187 offset:33792
	ds_read_b128 v[222:225], v187 offset:34816
	ds_read_b128 v[226:229], v187 offset:35840
	ds_read_b128 v[230:233], v187 offset:36864
	ds_read_b128 v[234:237], v187 offset:37888
	ds_read_b128 v[238:241], v187 offset:38912
	ds_read_b128 v[242:245], v187 offset:39936
	global_load_lds_dwordx4 v[252:253], off
	v_lshl_add_u64 v[252:253], s[12:13], 0, v[154:155]
	s_mov_b32 m0, s74
	s_nop 0
	global_load_lds_dwordx4 v[252:253], off
	s_waitcnt vmcnt(8)
	s_waitcnt lgkmcnt(0)
	s_waitcnt lgkmcnt(0)
	s_barrier
	s_setprio 1
	v_mfma_f32_16x16x32_bf16 v[142:145], v[18:21], v[214:217], v[142:145]
	v_mfma_f32_16x16x32_bf16 v[138:141], v[66:69], v[214:217], v[138:141]
	v_mfma_f32_16x16x32_bf16 v[126:129], v[18:21], v[222:225], v[126:129]
	v_mfma_f32_16x16x32_bf16 v[122:125], v[66:69], v[222:225], v[122:125]
	v_mfma_f32_16x16x32_bf16 v[110:113], v[18:21], v[230:233], v[110:113]
	v_mfma_f32_16x16x32_bf16 v[106:109], v[66:69], v[230:233], v[106:109]
	v_mfma_f32_16x16x32_bf16 v[94:97], v[18:21], v[238:241], v[94:97]
	v_mfma_f32_16x16x32_bf16 v[90:93], v[66:69], v[238:241], v[90:93]
	v_mfma_f32_16x16x32_bf16 v[142:145], v[22:25], v[218:221], v[142:145]
	v_mfma_f32_16x16x32_bf16 v[138:141], v[70:73], v[218:221], v[138:141]
	v_mfma_f32_16x16x32_bf16 v[126:129], v[22:25], v[226:229], v[126:129]
	v_mfma_f32_16x16x32_bf16 v[122:125], v[70:73], v[226:229], v[122:125]
	v_mfma_f32_16x16x32_bf16 v[110:113], v[22:25], v[234:237], v[110:113]
	v_mfma_f32_16x16x32_bf16 v[106:109], v[70:73], v[234:237], v[106:109]
	v_mfma_f32_16x16x32_bf16 v[94:97], v[22:25], v[242:245], v[94:97]
	v_mfma_f32_16x16x32_bf16 v[90:93], v[70:73], v[242:245], v[90:93]
	s_setprio 0
	s_setprio 1
	v_mfma_f32_16x16x32_bf16 v[134:137], v[146:149], v[214:217], v[134:137]
	v_mfma_f32_16x16x32_bf16 v[130:133], v[178:181], v[214:217], v[130:133]
	v_mfma_f32_16x16x32_bf16 v[118:121], v[146:149], v[222:225], v[118:121]
	v_mfma_f32_16x16x32_bf16 v[114:117], v[178:181], v[222:225], v[114:117]
	v_mfma_f32_16x16x32_bf16 v[102:105], v[146:149], v[230:233], v[102:105]
	v_mfma_f32_16x16x32_bf16 v[98:101], v[178:181], v[230:233], v[98:101]
	v_mfma_f32_16x16x32_bf16 v[86:89], v[146:149], v[238:241], v[86:89]
	v_mfma_f32_16x16x32_bf16 v[82:85], v[178:181], v[238:241], v[82:85]
	v_mfma_f32_16x16x32_bf16 v[134:137], v[174:177], v[218:221], v[134:137]
	v_mfma_f32_16x16x32_bf16 v[130:133], v[210:213], v[218:221], v[130:133]
	v_mfma_f32_16x16x32_bf16 v[118:121], v[174:177], v[226:229], v[118:121]
	v_mfma_f32_16x16x32_bf16 v[114:117], v[210:213], v[226:229], v[114:117]
	v_mfma_f32_16x16x32_bf16 v[102:105], v[174:177], v[234:237], v[102:105]
	v_mfma_f32_16x16x32_bf16 v[98:101], v[210:213], v[234:237], v[98:101]
	v_mfma_f32_16x16x32_bf16 v[86:89], v[174:177], v[242:245], v[86:89]
	v_mfma_f32_16x16x32_bf16 v[82:85], v[210:213], v[242:245], v[82:85]
	s_setprio 0
	s_barrier
; #define PG8_STAGE(bufoff, gbase, voff) do { _Pragma("unroll") for (int _i = 0; _i < 2; ++_i) \
;         __builtin_amdgcn_global_load_lds((const unsigned*)((const char*)(gbase) + (voff)[_i]), (PG8_LAS unsigned*)(lds + (bufoff) + ldsw + _i * 8192), 16, 0, 0); } while (0)
; #define PG8_LDA(dst, b, h) do { _Pragma("unroll") for (int m = 0; m < 4; ++m) _Pragma("unroll") for (int k = 0; k < 2; ++k) dst[m][k] = *(const PG8_LAS bf16x8*)(lds + PG8_SA(b, h) + aoff + m * 2048 + k * 1024); } while (0)
; #define PG8_MMA(ai, bj, At, Bt) do { __builtin_amdgcn_s_setprio(1); _Pragma("unroll") for (int m = 0; m < 4; ++m) _Pragma("unroll") for (int n = 0; n < 2; ++n) _Pragma("unroll") for (int k = 0; k < 2; ++k) \
;         acc[ai][bj][m][n] = __builtin_amdgcn_mfma_f32_16x16x32_bf16(Bt[n][k], At[m][k], acc[ai][bj][m][n], 0, 0, 0); __builtin_amdgcn_s_setprio(0); } while (0)
; #define PG8_WAIT_V(n) asm volatile("s_waitcnt vmcnt(" #n ")" ::: "memory")
; #define PG8_WAIT_L(n) do { asm volatile("s_waitcnt lgkmcnt(" #n ")" ::: "memory"); __builtin_amdgcn_s_waitcnt(0xC07F); } while (0)
; #define PG8_BAR __builtin_amdgcn_s_barrier()
; #define PG8_SCHED __builtin_amdgcn_sched_barrier(0)
; template <class Epi, class Sched, bool SEG3 = false>
; __device__ __forceinline__ void gemm_phase(PG8_LAS unsigned char* lds, const Gemm g, const Sched& S, const Epi& E) {
;     ...
;             PG8_LDA(At, 1, 1); PG8_STAGE(PG8_SB(1, 0), b3, voffB); PG8_STAGE(PG8_SB(1, 1), b3 + hsB, voffB); PG8_STAGE(PG8_SA(1, 0), a3, voffA);
;             PG8_WAIT_V(8); PG8_WAIT_L(0); PG8_BAR; if (cur.half != 0) { PG8_MMA(1, 0, At, B0); PG8_MMA(1, 1, At, B1); } PG8_BAR; PG8_SCHED;
;         }
	s_mov_b32 m0, s77
	v_lshl_add_u64 v[182:183], v[182:183], 0, s[30:31]
	s_add_u32 s10, s10, 0x40080
	ds_read_b128 v[214:217], v187 offset:49152
	ds_read_b128 v[218:221], v187 offset:50176
	ds_read_b128 v[222:225], v187 offset:51200
	ds_read_b128 v[226:229], v187 offset:52224
	ds_read_b128 v[230:233], v187 offset:53248
	ds_read_b128 v[234:237], v187 offset:54272
	ds_read_b128 v[238:241], v187 offset:55296
	ds_read_b128 v[242:245], v187 offset:56320
	global_load_lds_dwordx4 v[182:183], off
	v_lshl_add_u64 v[182:183], v[246:247], 0, s[30:31]
	s_mov_b32 m0, s78
	s_addc_u32 s11, s11, 0
	global_load_lds_dwordx4 v[182:183], off
	v_lshl_add_u64 v[182:183], s[10:11], 0, v[152:153]
	s_mov_b32 m0, s82
	s_nop 0
	global_load_lds_dwordx4 v[182:183], off
	v_lshl_add_u64 v[182:183], s[10:11], 0, v[156:157]
	s_mov_b32 m0, s83
	s_nop 0
	global_load_lds_dwordx4 v[182:183], off
	v_lshl_add_u64 v[182:183], v[248:249], 0, s[30:31]
	s_mov_b32 m0, s80
	s_nop 0
	global_load_lds_dwordx4 v[182:183], off
	v_lshl_add_u64 v[182:183], v[250:251], 0, s[30:31]
	s_mov_b32 m0, s81
	s_nop 0
	global_load_lds_dwordx4 v[182:183], off
	s_waitcnt vmcnt(8)
	s_waitcnt lgkmcnt(0)
	s_waitcnt lgkmcnt(0)
	s_barrier
	s_setprio 1
	v_mfma_f32_16x16x32_bf16 v[78:81], v[18:21], v[214:217], v[78:81]
	v_mfma_f32_16x16x32_bf16 v[62:65], v[18:21], v[222:225], v[62:65]
	v_mfma_f32_16x16x32_bf16 v[46:49], v[18:21], v[230:233], v[46:49]
	v_mfma_f32_16x16x32_bf16 v[10:13], v[18:21], v[238:241], v[10:13]
	v_mfma_f32_16x16x32_bf16 v[78:81], v[22:25], v[218:221], v[78:81]
	v_mfma_f32_16x16x32_bf16 v[74:77], v[66:69], v[214:217], v[74:77]
	v_mfma_f32_16x16x32_bf16 v[62:65], v[22:25], v[226:229], v[62:65]
	v_mfma_f32_16x16x32_bf16 v[58:61], v[66:69], v[222:225], v[58:61]
	v_mfma_f32_16x16x32_bf16 v[46:49], v[22:25], v[234:237], v[46:49]
	v_mfma_f32_16x16x32_bf16 v[42:45], v[66:69], v[230:233], v[42:45]
	v_mfma_f32_16x16x32_bf16 v[22:25], v[22:25], v[242:245], v[10:13]
	v_mfma_f32_16x16x32_bf16 v[10:13], v[66:69], v[238:241], v[14:17]
	v_mfma_f32_16x16x32_bf16 v[74:77], v[70:73], v[218:221], v[74:77]
	v_mfma_f32_16x16x32_bf16 v[58:61], v[70:73], v[226:229], v[58:61]
	v_mfma_f32_16x16x32_bf16 v[42:45], v[70:73], v[234:237], v[42:45]
	v_mfma_f32_16x16x32_bf16 v[18:21], v[70:73], v[242:245], v[10:13]
	s_setprio 0
	s_setprio 1
	v_mfma_f32_16x16x32_bf16 v[10:13], v[146:149], v[214:217], v[34:37]
	v_mfma_f32_16x16x32_bf16 v[70:73], v[174:177], v[218:221], v[10:13]
	v_mfma_f32_16x16x32_bf16 v[10:13], v[178:181], v[214:217], v[38:41]
	v_mfma_f32_16x16x32_bf16 v[66:69], v[210:213], v[218:221], v[10:13]
	v_mfma_f32_16x16x32_bf16 v[10:13], v[146:149], v[222:225], v[54:57]
	v_mfma_f32_16x16x32_bf16 v[54:57], v[174:177], v[226:229], v[10:13]
	v_mfma_f32_16x16x32_bf16 v[10:13], v[178:181], v[222:225], v[50:53]
	v_mfma_f32_16x16x32_bf16 v[50:53], v[210:213], v[226:229], v[10:13]
	v_mfma_f32_16x16x32_bf16 v[10:13], v[146:149], v[230:233], v[30:33]
	v_mfma_f32_16x16x32_bf16 v[30:33], v[174:177], v[234:237], v[10:13]
	v_mfma_f32_16x16x32_bf16 v[10:13], v[178:181], v[230:233], v[26:29]
	v_mfma_f32_16x16x32_bf16 v[6:9], v[146:149], v[238:241], v[6:9]
	v_mfma_f32_16x16x32_bf16 v[2:5], v[178:181], v[238:241], v[2:5]
	v_mfma_f32_16x16x32_bf16 v[26:29], v[210:213], v[234:237], v[10:13]
	v_mfma_f32_16x16x32_bf16 v[6:9], v[174:177], v[242:245], v[6:9]
	v_mfma_f32_16x16x32_bf16 v[2:5], v[210:213], v[242:245], v[2:5]
	s_setprio 0
	s_barrier
	s_add_u32 s8, s8, 0x100
	s_addc_u32 s9, s9, 0
	s_add_u32 s17, s17, 0x100
	s_addc_u32 s19, s19, 0
	s_cmp_lt_i32 s20, s75
	s_mov_b32 s10, s20
	s_cbranch_scc1 .LBB0_2680
	s_andn2_b64 vcc, exec, s[36:37]
	s_cbranch_vccnz .LBB0_2683

;     __device__ __forceinline__ void operator()(AccT acc, const Unit& u, int wr, int wc, int fr, int fq) const {
;         const int col0 = u.pn * BM + wc * 32 + 8 * fq;
;         const bool uni = u.pm < NPROMPT / BM;
;         f32x4 sh[2][2] = {{(f32x4){0.f, 0.f, 0.f, 0.f}, (f32x4){0.f, 0.f, 0.f, 0.f}}, {(f32x4){0.f, 0.f, 0.f, 0.f}, (f32x4){0.f, 0.f, 0.f, 0.f}}};
;         if (uni) { const float* sw = SHW + (size_t)(u.pm >> 3) * NZT + col0;
; #pragma unroll
;             for (int bj = 0; bj < 2; ++bj) { sh[bj][0] = *(const f32x4*)(sw + bj * HALF); sh[bj][1] = *(const f32x4*)(sw + bj * HALF + 4); } }
;         float rs8[8];
; #pragma unroll
;         for (int r8 = 0; r8 < 8; ++r8) rs8[r8] = row_rs(SSQ, u.pm * BM + (r8 >> 2) * HALF + wr * 64 + (r8 & 3) * 16 + fr, fq);
;         const int side = (u.pn >= 6 && u.pn < 18) ? 1 : ((u.pn >= 22 && u.pn < 32) ? 2 : 0);
.LBB0_2683:
	s_mov_b32 s98, 1
	s_cmpk_gt_i32 s6, 0x7f
	v_lshl_or_b32 v174, s18, 8, v184
	s_cselect_b64 s[8:9], -1, 0
	s_cmpk_lt_i32 s6, 0x80
	s_mov_b64 s[10:11], -1
	s_cbranch_scc1 .LBB0_2685
	v_ashrrev_i32_e32 v175, 31, v174
	s_mov_b64 s[10:11], 0

; #define LAS __attribute__((address_space(3)))
; __device__ __forceinline__ void sample_merge_units(LAS unsigned char* lds, const bf16* OA, const bf16* YN, const bf16* HCG, const bf16* Wa, const bf16* Wb, const bf16* Wc,
;                                                    const bf16* Zg, bf16* MG, int tid, int vcu, int G) {
;     LAS float* P = (LAS float*)lds;
;     const int lane = tid & 63, w = __builtin_amdgcn_readfirstlane(tid >> 6), qq = lane & 15, q4 = lane >> 4;
;     for (int un = vcu; un < 256; un += G) {
;         const int rt = un >> 4, cs = un & 15, pn = cs >> 2, wc = cs & 3; const size_t row0 = (size_t)NPROMPT + 16 * rt;
;         __syncthreads();
; #pragma unroll
;         for (int pr = 0; pr < 3; ++pr) {
;             const bf16* Aop = pr == 0 ? OA : (pr == 1 ? YN : HCG); const bf16* Bt = pr == 0 ? Wa : (pr == 1 ? Wb : Wc); const int K = pr == 0 ? 512 : DM;
;             const int kper = K >> 3, kbeg = w * kper;
;             f32x4 acc[4];
; #pragma unroll
;             for (int ct = 0; ct < 4; ++ct) acc[ct] = (f32x4){0.f, 0.f, 0.f, 0.f};
;             const bf16* ap = Aop + (row0 + qq) * (size_t)DM + kbeg + 8 * q4;
;             const bf16* bp = Bt + (size_t)(256 * pn + 32 * wc + qq) * DM + kbeg + 8 * q4;
; #pragma unroll
;             for (int k0 = 0; k0 < kper; k0 += 32) {
;                 const bf16x8 af = *(const bf16x8*)(ap + k0);
; #pragma unroll
;                 for (int ct = 0; ct < 4; ++ct) { const bf16x8 bf = *(const bf16x8*)(bp + (size_t)(128 * (ct >> 1) + 16 * (ct & 1)) * DM + k0);
;                     acc[ct] = __builtin_amdgcn_mfma_f32_16x16x32_bf16(bf, af, acc[ct], 0, 0, 0); } }
; #pragma unroll
;             for (int ct = 0; ct < 4; ++ct)
; #pragma unroll
;                 for (int i = 0; i < 4; ++i) P[pr * 8192 + ((w * 4 + ct) * 4 + i) * 64 + lane] = acc[ct][i];
; __global__ void __launch_bounds__(NWAVES * 64, 2) fwd(Args args_unused) {
;     ...
;         if (IN(pb + 6)) {
;             PH_PTRS PH_LAYER
;             sample_merge_units(lds, OA, YN, HCG, (const bf16*)(wl + WL_A), (const bf16*)(wl + WL_B), (const bf16*)(wl + WL_C), Z, MG, tid, vcu, G);
.LBB0_4008:
	s_mov_b32 s98, 0
	s_cmp_lt_i32 s84, 20
	s_cselect_b64 s[0:1], -1, 0
	s_and_b64 s[0:1], s[0:1], s[4:5]
	s_andn2_b64 vcc, exec, s[0:1]
	s_cbranch_vccnz .LBB0_4132
	s_mov_b64 s[0:1], s[82:83]
	s_load_dwordx2 s[6:7], s[0:1], 0x148
	s_mov_b32 s16, 0
	s_mov_b32 s3, s2
	s_load_dword s33, s[82:83], 0x168
	s_waitcnt lgkmcnt(0)
	s_add_u32 s0, s6, 0x19100000
	s_addc_u32 s1, s7, 0
	s_add_u32 s4, s6, 0x1d200000
	s_addc_u32 s5, s7, 0
	s_add_u32 s34, s6, 0x5fb00000
	s_addc_u32 s35, s7, 0
	s_add_u32 s36, s6, 0x75e00000
	s_addc_u32 s37, s7, 0
	s_add_u32 s38, s6, 0x79f00000
	s_addc_u32 s39, s7, 0
	s_add_u32 s40, s6, 0x8900000
	s_addc_u32 s41, s7, 0
	s_add_u32 s42, s6, 0x7100000
	s_addc_u32 s43, s7, 0
	s_add_u32 s44, s6, 0x7300000
	v_readlane_b32 s10, v254, 3
	v_mov_b32_e32 v2, v0
	s_addc_u32 s45, s7, 0
	s_cmpk_gt_i32 s10, 0xff
	v_readfirstlane_b32 s8, v2
	s_cbranch_scc1 .LBB0_4012
	v_and_b32_e32 v3, 63, v2
	v_lshl_add_u32 v18, v3, 2, s16
	v_ashrrev_i32_e32 v3, 7, v2
	s_ashr_i32 s11, s8, 6
	v_ashrrev_i32_e32 v6, 1, v2
	s_add_i32 s9, s16, 0x10000
	v_lshlrev_b32_e32 v16, 10, v3
	s_andn2_b32 s8, s8, 63
	s_lshl_b32 s19, s11, 12
	v_and_b32_e32 v20, 0xffffff80, v6
	v_lshlrev_b32_e32 v6, 4, v3
	v_add_u32_e32 v3, s9, v16
	s_ashr_i32 s9, s8, 31
	v_lshrrev_b32_e32 v5, 3, v2
	s_or_b32 s20, s19, 0xc00
	s_lshl_b64 s[8:9], s[8:9], 1
	v_and_b32_e32 v1, 15, v2
	v_lshrrev_b32_e32 v4, 1, v2
	v_and_b32_e32 v5, 14, v5
	s_add_u32 s12, s36, s8
	v_and_or_b32 v4, v4, 48, v1
	v_and_or_b32 v21, v6, 16, v5
	v_lshlrev_b32_e32 v5, 5, v2
	s_addc_u32 s13, s37, s9
	v_and_b32_e32 v17, 0x200, v5
	v_lshlrev_b32_e32 v19, 2, v4
	s_add_u32 s8, s40, s8
	v_add3_u32 v22, v3, v17, v19
	v_and_b32_e32 v2, 48, v2
	v_mov_b32_e32 v3, 0
	s_addc_u32 s9, s41, s9
	v_lshl_add_u64 v[6:7], s[8:9], 0, v[2:3]
	s_lshl_b32 s8, s11, 7
	s_ashr_i32 s9, s8, 31
	s_or_b32 s21, s19, 0x100
	s_or_b32 s22, s19, 0x200
	s_or_b32 s23, s19, 0x300
	s_or_b32 s24, s19, 0x400
	s_or_b32 s25, s19, 0x500
	s_or_b32 s26, s19, 0x600
	s_or_b32 s27, s19, 0x700
	s_or_b32 s28, s19, 0x800
	s_or_b32 s29, s19, 0x900
	s_or_b32 s30, s19, 0xa00
	s_or_b32 s31, s19, 0xb00
	s_or_b32 s46, s19, 0xd00
	s_or_b32 s47, s19, 0xe00
	s_or_b32 s48, s19, 0xf00
	s_lshl_b64 s[8:9], s[8:9], 1
	v_lshl_add_u64 v[4:5], s[12:13], 0, v[2:3]
	s_add_u32 s12, s34, s8
	s_addc_u32 s13, s35, s9
	v_lshl_add_u64 v[8:9], s[12:13], 0, v[2:3]
	s_add_u32 s12, s42, s8
	s_addc_u32 s13, s43, s9
	v_lshl_add_u64 v[10:11], s[12:13], 0, v[2:3]
	s_add_u32 s12, s38, s8
	s_addc_u32 s13, s39, s9
	s_add_u32 s8, s44, s8
	s_addc_u32 s9, s45, s9
	v_lshl_add_u64 v[14:15], s[8:9], 0, v[2:3]
	s_add_i32 s8, s16, 0x11000
	v_add_u32_e32 v24, s8, v16
	s_add_i32 s8, s16, 0x12000
	s_waitcnt vmcnt(0)
	v_add_u32_e32 v25, s8, v16
	s_add_i32 s8, s16, 0x13000
	v_add_u32_e32 v26, s8, v16
	s_add_i32 s8, s16, 0x14000
	v_add_u32_e32 v27, s8, v16
	s_add_i32 s8, s16, 0x15000
	v_add_u32_e32 v28, s8, v16
	s_add_i32 s8, s16, 0x16000
	v_add_u32_e32 v29, s8, v16
	s_add_i32 s8, s16, 0x17000
	v_lshl_add_u64 v[12:13], s[12:13], 0, v[2:3]
	v_add_u32_e32 v2, 0x10000, v18
	v_add_u32_e32 v23, s16, v16
	v_add_u32_e32 v16, s8, v16
	v_add3_u32 v23, v23, v17, v19
	v_add3_u32 v24, v24, v17, v19
	v_add3_u32 v25, v25, v17, v19
	v_add3_u32 v26, v26, v17, v19
	v_add3_u32 v27, v27, v17, v19
	v_add3_u32 v28, v28, v17, v19
	v_add3_u32 v29, v29, v17, v19
	v_add3_u32 v30, v16, v17, v19
	s_mov_b32 s11, 0x8000
	v_or_b32_e32 v16, 0x8000, v1
	v_mov_b32_e32 v17, v3
	s_lshl_b32 s12, s10, 5
	s_lshl_b32 s13, s33, 5
	s_lshl_b32 s14, s10, 6
	s_lshl_b32 s15, s33, 6
	s_mov_b32 s17, 0x40000
	s_mov_b32 s18, 0x48000
	v_add_u32_e32 v31, s19, v18
	v_add_u32_e32 v32, s19, v2
	v_add_u32_e32 v33, s21, v2
	v_add_u32_e32 v34, s22, v2
	v_add_u32_e32 v35, s23, v2
	v_add_u32_e32 v36, s24, v2
	v_add_u32_e32 v37, s25, v2
	v_add_u32_e32 v38, s26, v2
	v_add_u32_e32 v39, s27, v2
	v_add_u32_e32 v40, s28, v2
	v_add_u32_e32 v41, s29, v2
	v_add_u32_e32 v42, s30, v2
	v_add_u32_e32 v43, s31, v2
	v_add_u32_e32 v44, s20, v2
	v_add_u32_e32 v45, s46, v2
	v_add_u32_e32 v46, s47, v2
	v_add_u32_e32 v47, s48, v2
	s_movk_i32 s19, 0xfe

; #define PG8_STAGE(bufoff, gbase, voff) do { _Pragma("unroll") for (int _i = 0; _i < 2; ++_i) \
;         __builtin_amdgcn_global_load_lds((const unsigned*)((const char*)(gbase) + (voff)[_i]), (PG8_LAS unsigned*)(lds + (bufoff) + ldsw + _i * 8192), 16, 0, 0); } while (0)
; #define PG8_LDA(dst, b, h) do { _Pragma("unroll") for (int m = 0; m < 4; ++m) _Pragma("unroll") for (int k = 0; k < 2; ++k) dst[m][k] = *(const PG8_LAS bf16x8*)(lds + PG8_SA(b, h) + aoff + m * 2048 + k * 1024); } while (0)
; #define PG8_LDB(dst, b, h) do { _Pragma("unroll") for (int n = 0; n < 2; ++n) _Pragma("unroll") for (int k = 0; k < 2; ++k) dst[n][k] = *(const PG8_LAS bf16x8*)(lds + PG8_SB(b, h) + boff + n * 2048 + k * 1024); } while (0)
; #define PG8_MMA(ai, bj, At, Bt) do { __builtin_amdgcn_s_setprio(1); _Pragma("unroll") for (int m = 0; m < 4; ++m) _Pragma("unroll") for (int n = 0; n < 2; ++n) _Pragma("unroll") for (int k = 0; k < 2; ++k) \
;         acc[ai][bj][m][n] = __builtin_amdgcn_mfma_f32_16x16x32_bf16(Bt[n][k], At[m][k], acc[ai][bj][m][n], 0, 0, 0); __builtin_amdgcn_s_setprio(0); } while (0)
; #define PG8_WAIT_V(n) asm volatile("s_waitcnt vmcnt(" #n ")" ::: "memory")
; #define PG8_WAIT_L(n) do { asm volatile("s_waitcnt lgkmcnt(" #n ")" ::: "memory"); __builtin_amdgcn_s_waitcnt(0xC07F); } while (0)
; #define PG8_BAR __builtin_amdgcn_s_barrier()
; #define PG8_SCHED __builtin_amdgcn_sched_barrier(0)
; template <class Epi, class Sched, bool SEG3 = false>
; __device__ __forceinline__ void gemm_phase(PG8_LAS unsigned char* lds, const Gemm g, const Sched& S, const Epi& E) {
;     ...
;             PG8_WAIT_V(8); PG8_WAIT_L(0); PG8_BAR; if (cur.half != 0) { PG8_MMA(1, 0, At, B0); PG8_MMA(1, 1, At, B1); } PG8_BAR; PG8_SCHED;
;             PG8_LDB(B0, 1, 0); PG8_LDB(B1, 1, 1); PG8_SCHED; PG8_LDA(At, 1, 0); PG8_STAGE(PG8_SA(0, 1), a2 + hsA, voffA);
;             PG8_WAIT_V(8); PG8_WAIT_L(0); PG8_BAR; if (cur.half != 1) { PG8_MMA(0, 0, At, B0); PG8_MMA(0, 1, At, B1); } PG8_BAR; PG8_SCHED;
;             PG8_LDA(At, 1, 1); PG8_STAGE(PG8_SB(1, 0), b3, voffB); PG8_STAGE(PG8_SB(1, 1), b3 + hsB, voffB); PG8_STAGE(PG8_SA(1, 0), a3, voffA);
.Lfi_b_7:
	s_mov_b32 s98, 0
	s_waitcnt lgkmcnt(0)
	s_barrier
	s_setprio 1
	v_mfma_f32_16x16x32_bf16 v[62:65], v[124:127], v[164:167], v[62:65]
	v_mfma_f32_16x16x32_bf16 v[58:61], v[140:143], v[164:167], v[58:61]
	v_mfma_f32_16x16x32_bf16 v[46:49], v[124:127], v[172:175], v[46:49]
	v_mfma_f32_16x16x32_bf16 v[42:45], v[140:143], v[172:175], v[42:45]
	v_mfma_f32_16x16x32_bf16 v[30:33], v[124:127], v[180:183], v[30:33]
	v_mfma_f32_16x16x32_bf16 v[26:29], v[140:143], v[180:183], v[26:29]
	v_mfma_f32_16x16x32_bf16 v[14:17], v[124:127], v[188:191], v[14:17]
	v_mfma_f32_16x16x32_bf16 v[10:13], v[140:143], v[188:191], v[10:13]
	v_mfma_f32_16x16x32_bf16 v[62:65], v[132:135], v[168:171], v[62:65]
	v_mfma_f32_16x16x32_bf16 v[58:61], v[144:147], v[168:171], v[58:61]
	v_mfma_f32_16x16x32_bf16 v[46:49], v[132:135], v[176:179], v[46:49]
	v_mfma_f32_16x16x32_bf16 v[42:45], v[144:147], v[176:179], v[42:45]
	v_mfma_f32_16x16x32_bf16 v[30:33], v[132:135], v[184:187], v[30:33]
	v_mfma_f32_16x16x32_bf16 v[26:29], v[144:147], v[184:187], v[26:29]
	v_mfma_f32_16x16x32_bf16 v[14:17], v[132:135], v[192:195], v[14:17]
	v_mfma_f32_16x16x32_bf16 v[10:13], v[144:147], v[192:195], v[10:13]
	s_setprio 0
	s_setprio 1
	v_mfma_f32_16x16x32_bf16 v[54:57], v[148:151], v[164:167], v[54:57]
	v_mfma_f32_16x16x32_bf16 v[50:53], v[156:159], v[164:167], v[50:53]
	v_mfma_f32_16x16x32_bf16 v[38:41], v[148:151], v[172:175], v[38:41]
	v_mfma_f32_16x16x32_bf16 v[34:37], v[156:159], v[172:175], v[34:37]
	v_mfma_f32_16x16x32_bf16 v[22:25], v[148:151], v[180:183], v[22:25]
	v_mfma_f32_16x16x32_bf16 v[18:21], v[156:159], v[180:183], v[18:21]
	v_mfma_f32_16x16x32_bf16 v[6:9], v[148:151], v[188:191], v[6:9]
	v_mfma_f32_16x16x32_bf16 v[2:5], v[156:159], v[188:191], v[2:5]
	v_mfma_f32_16x16x32_bf16 v[54:57], v[152:155], v[168:171], v[54:57]
	v_mfma_f32_16x16x32_bf16 v[50:53], v[160:163], v[168:171], v[50:53]
	v_mfma_f32_16x16x32_bf16 v[38:41], v[152:155], v[176:179], v[38:41]
	v_mfma_f32_16x16x32_bf16 v[34:37], v[160:163], v[176:179], v[34:37]
	v_mfma_f32_16x16x32_bf16 v[22:25], v[152:155], v[184:187], v[22:25]
	v_mfma_f32_16x16x32_bf16 v[18:21], v[160:163], v[184:187], v[18:21]
	v_mfma_f32_16x16x32_bf16 v[6:9], v[152:155], v[192:195], v[6:9]
	v_mfma_f32_16x16x32_bf16 v[2:5], v[160:163], v[192:195], v[2:5]
	s_setprio 0
	s_barrier
	ds_read_b128 v[124:127], v234
	ds_read_b128 v[132:135], v234 offset:1024
	ds_read_b128 v[140:143], v234 offset:2048
	ds_read_b128 v[144:147], v234 offset:3072
	ds_read_b128 v[148:151], v235
	ds_read_b128 v[152:155], v235 offset:1024
	ds_read_b128 v[156:159], v235 offset:2048
	ds_read_b128 v[160:163], v235 offset:3072
	s_add_u32 s30, s30, 0x40000
	s_addc_u32 s31, s31, 0
	s_mov_b32 m0, s52
	v_lshl_add_u64 v[102:103], s[30:31], 0, v[196:197]
	ds_read_b128 v[164:167], v233 offset:32768
	ds_read_b128 v[168:171], v233 offset:33792
	ds_read_b128 v[172:175], v233 offset:34816
	ds_read_b128 v[176:179], v233 offset:35840
	ds_read_b128 v[180:183], v233 offset:36864
	ds_read_b128 v[184:187], v233 offset:37888
	ds_read_b128 v[188:191], v233 offset:38912
	ds_read_b128 v[192:195], v233 offset:39936
	global_load_lds_dwordx4 v[102:103], off
	v_lshl_add_u64 v[102:103], s[30:31], 0, v[200:201]
	s_mov_b32 m0, s53
	s_nop 0
	global_load_lds_dwordx4 v[102:103], off
	s_waitcnt vmcnt(8)
	s_waitcnt lgkmcnt(0)
	s_waitcnt lgkmcnt(0)
	s_barrier
	s_setprio 1
	v_mfma_f32_16x16x32_bf16 v[136:139], v[124:127], v[164:167], v[136:139]
	v_mfma_f32_16x16x32_bf16 v[128:131], v[140:143], v[164:167], v[128:131]
	v_mfma_f32_16x16x32_bf16 v[112:115], v[124:127], v[172:175], v[112:115]
	v_mfma_f32_16x16x32_bf16 v[108:111], v[140:143], v[172:175], v[108:111]
	v_mfma_f32_16x16x32_bf16 v[94:97], v[124:127], v[180:183], v[94:97]
	v_mfma_f32_16x16x32_bf16 v[90:93], v[140:143], v[180:183], v[90:93]
	v_mfma_f32_16x16x32_bf16 v[78:81], v[124:127], v[188:191], v[78:81]
	v_mfma_f32_16x16x32_bf16 v[74:77], v[140:143], v[188:191], v[74:77]
	v_mfma_f32_16x16x32_bf16 v[136:139], v[132:135], v[168:171], v[136:139]
	v_mfma_f32_16x16x32_bf16 v[128:131], v[144:147], v[168:171], v[128:131]
	v_mfma_f32_16x16x32_bf16 v[112:115], v[132:135], v[176:179], v[112:115]
	v_mfma_f32_16x16x32_bf16 v[108:111], v[144:147], v[176:179], v[108:111]
	v_mfma_f32_16x16x32_bf16 v[94:97], v[132:135], v[184:187], v[94:97]
	v_mfma_f32_16x16x32_bf16 v[90:93], v[144:147], v[184:187], v[90:93]
	v_mfma_f32_16x16x32_bf16 v[78:81], v[132:135], v[192:195], v[78:81]
	v_mfma_f32_16x16x32_bf16 v[74:77], v[144:147], v[192:195], v[74:77]
	s_setprio 0
	s_setprio 1
	v_mfma_f32_16x16x32_bf16 v[120:123], v[148:151], v[164:167], v[120:123]
	v_mfma_f32_16x16x32_bf16 v[116:119], v[156:159], v[164:167], v[116:119]
	v_mfma_f32_16x16x32_bf16 v[102:105], v[148:151], v[172:175], v[104:107]
	v_mfma_f32_16x16x32_bf16 v[98:101], v[156:159], v[172:175], v[98:101]
	v_mfma_f32_16x16x32_bf16 v[86:89], v[148:151], v[180:183], v[86:89]
	v_mfma_f32_16x16x32_bf16 v[82:85], v[156:159], v[180:183], v[82:85]
	v_mfma_f32_16x16x32_bf16 v[70:73], v[148:151], v[188:191], v[70:73]
	v_mfma_f32_16x16x32_bf16 v[66:69], v[156:159], v[188:191], v[66:69]
	v_mfma_f32_16x16x32_bf16 v[120:123], v[152:155], v[168:171], v[120:123]
	v_mfma_f32_16x16x32_bf16 v[116:119], v[160:163], v[168:171], v[116:119]
	v_mfma_f32_16x16x32_bf16 v[104:107], v[152:155], v[176:179], v[102:105]
	v_mfma_f32_16x16x32_bf16 v[100:103], v[160:163], v[176:179], v[98:101]
	v_mfma_f32_16x16x32_bf16 v[86:89], v[152:155], v[184:187], v[86:89]
	v_mfma_f32_16x16x32_bf16 v[82:85], v[160:163], v[184:187], v[82:85]
	v_mfma_f32_16x16x32_bf16 v[70:73], v[152:155], v[192:195], v[70:73]
	v_mfma_f32_16x16x32_bf16 v[66:69], v[160:163], v[192:195], v[66:69]
	s_setprio 0
	s_barrier
; #define PG8_STAGE(bufoff, gbase, voff) do { _Pragma("unroll") for (int _i = 0; _i < 2; ++_i) \
;         __builtin_amdgcn_global_load_lds((const unsigned*)((const char*)(gbase) + (voff)[_i]), (PG8_LAS unsigned*)(lds + (bufoff) + ldsw + _i * 8192), 16, 0, 0); } while (0)
; #define PG8_LDA(dst, b, h) do { _Pragma("unroll") for (int m = 0; m < 4; ++m) _Pragma("unroll") for (int k = 0; k < 2; ++k) dst[m][k] = *(const PG8_LAS bf16x8*)(lds + PG8_SA(b, h) + aoff + m * 2048 + k * 1024); } while (0)
; #define PG8_MMA(ai, bj, At, Bt) do { __builtin_amdgcn_s_setprio(1); _Pragma("unroll") for (int m = 0; m < 4; ++m) _Pragma("unroll") for (int n = 0; n < 2; ++n) _Pragma("unroll") for (int k = 0; k < 2; ++k) \
;         acc[ai][bj][m][n] = __builtin_amdgcn_mfma_f32_16x16x32_bf16(Bt[n][k], At[m][k], acc[ai][bj][m][n], 0, 0, 0); __builtin_amdgcn_s_setprio(0); } while (0)
; #define PG8_WAIT_V(n) asm volatile("s_waitcnt vmcnt(" #n ")" ::: "memory")
; #define PG8_WAIT_L(n) do { asm volatile("s_waitcnt lgkmcnt(" #n ")" ::: "memory"); __builtin_amdgcn_s_waitcnt(0xC07F); } while (0)
; #define PG8_BAR __builtin_amdgcn_s_barrier()
; #define PG8_SCHED __builtin_amdgcn_sched_barrier(0)
; template <class Epi, class Sched, bool SEG3 = false>
; __device__ __forceinline__ void gemm_phase(PG8_LAS unsigned char* lds, const Gemm g, const Sched& S, const Epi& E) {
;     ...
;             PG8_LDA(At, 1, 1); PG8_STAGE(PG8_SB(1, 0), b3, voffB); PG8_STAGE(PG8_SB(1, 1), b3 + hsB, voffB); PG8_STAGE(PG8_SA(1, 0), a3, voffA);
;             PG8_WAIT_V(8); PG8_WAIT_L(0); PG8_BAR; if (cur.half != 0) { PG8_MMA(1, 0, At, B0); PG8_MMA(1, 1, At, B1); } PG8_BAR; PG8_SCHED;
;         }
	s_mov_b32 m0, s55
	v_lshl_add_u64 v[98:99], v[214:215], 0, s[12:13]
	s_add_u32 s28, s28, 0x40080
	ds_read_b128 v[164:167], v233 offset:49152
	ds_read_b128 v[168:171], v233 offset:50176
	ds_read_b128 v[172:175], v233 offset:51200
	ds_read_b128 v[176:179], v233 offset:52224
	ds_read_b128 v[180:183], v233 offset:53248
	ds_read_b128 v[184:187], v233 offset:54272
	ds_read_b128 v[188:191], v233 offset:55296
	ds_read_b128 v[192:195], v233 offset:56320
	global_load_lds_dwordx4 v[98:99], off
	v_lshl_add_u64 v[98:99], v[216:217], 0, s[12:13]
	s_mov_b32 m0, s56
	s_addc_u32 s29, s29, 0
	global_load_lds_dwordx4 v[98:99], off
	v_lshl_add_u64 v[98:99], s[28:29], 0, v[198:199]
	s_mov_b32 m0, s59
	s_nop 0
	global_load_lds_dwordx4 v[98:99], off
	v_lshl_add_u64 v[98:99], s[28:29], 0, v[202:203]
	s_mov_b32 m0, s60
	s_nop 0
	global_load_lds_dwordx4 v[98:99], off
	v_lshl_add_u64 v[98:99], v[218:219], 0, s[12:13]
	s_mov_b32 m0, s57
	s_nop 0
	global_load_lds_dwordx4 v[98:99], off
	v_lshl_add_u64 v[98:99], v[220:221], 0, s[12:13]
	s_mov_b32 m0, s58
	s_nop 0
	global_load_lds_dwordx4 v[98:99], off
	s_waitcnt vmcnt(8)
	s_waitcnt lgkmcnt(0)
	s_waitcnt lgkmcnt(0)
	s_barrier
	s_setprio 1
	v_mfma_f32_16x16x32_bf16 v[62:65], v[124:127], v[164:167], v[62:65]
	v_mfma_f32_16x16x32_bf16 v[58:61], v[140:143], v[164:167], v[58:61]
	v_mfma_f32_16x16x32_bf16 v[46:49], v[124:127], v[172:175], v[46:49]
	v_mfma_f32_16x16x32_bf16 v[42:45], v[140:143], v[172:175], v[42:45]
	v_mfma_f32_16x16x32_bf16 v[30:33], v[124:127], v[180:183], v[30:33]
	v_mfma_f32_16x16x32_bf16 v[26:29], v[140:143], v[180:183], v[26:29]
	v_mfma_f32_16x16x32_bf16 v[14:17], v[124:127], v[188:191], v[14:17]
	v_mfma_f32_16x16x32_bf16 v[10:13], v[140:143], v[188:191], v[10:13]
	v_mfma_f32_16x16x32_bf16 v[62:65], v[132:135], v[168:171], v[62:65]
	v_mfma_f32_16x16x32_bf16 v[58:61], v[144:147], v[168:171], v[58:61]
	v_mfma_f32_16x16x32_bf16 v[46:49], v[132:135], v[176:179], v[46:49]
	v_mfma_f32_16x16x32_bf16 v[42:45], v[144:147], v[176:179], v[42:45]
	v_mfma_f32_16x16x32_bf16 v[30:33], v[132:135], v[184:187], v[30:33]
	v_mfma_f32_16x16x32_bf16 v[26:29], v[144:147], v[184:187], v[26:29]
	v_mfma_f32_16x16x32_bf16 v[14:17], v[132:135], v[192:195], v[14:17]
	v_mfma_f32_16x16x32_bf16 v[10:13], v[144:147], v[192:195], v[10:13]
	s_setprio 0
	s_setprio 1
	v_mfma_f32_16x16x32_bf16 v[54:57], v[148:151], v[164:167], v[54:57]
	v_mfma_f32_16x16x32_bf16 v[50:53], v[156:159], v[164:167], v[50:53]
	v_mfma_f32_16x16x32_bf16 v[38:41], v[148:151], v[172:175], v[38:41]
	v_mfma_f32_16x16x32_bf16 v[34:37], v[156:159], v[172:175], v[34:37]
	v_mfma_f32_16x16x32_bf16 v[22:25], v[148:151], v[180:183], v[22:25]
	v_mfma_f32_16x16x32_bf16 v[18:21], v[156:159], v[180:183], v[18:21]
	v_mfma_f32_16x16x32_bf16 v[6:9], v[148:151], v[188:191], v[6:9]
	v_mfma_f32_16x16x32_bf16 v[2:5], v[156:159], v[188:191], v[2:5]
	v_mfma_f32_16x16x32_bf16 v[54:57], v[152:155], v[168:171], v[54:57]
	v_mfma_f32_16x16x32_bf16 v[50:53], v[160:163], v[168:171], v[50:53]
	v_mfma_f32_16x16x32_bf16 v[38:41], v[152:155], v[176:179], v[38:41]
	v_mfma_f32_16x16x32_bf16 v[34:37], v[160:163], v[176:179], v[34:37]
	v_mfma_f32_16x16x32_bf16 v[22:25], v[152:155], v[184:187], v[22:25]
	v_mfma_f32_16x16x32_bf16 v[18:21], v[160:163], v[184:187], v[18:21]
	v_mfma_f32_16x16x32_bf16 v[6:9], v[152:155], v[192:195], v[6:9]
	v_mfma_f32_16x16x32_bf16 v[2:5], v[160:163], v[192:195], v[2:5]
	s_setprio 0
	s_barrier
	s_add_u32 s6, s6, 0x100
	s_addc_u32 s7, s7, 0
	s_add_u32 s19, s19, 0x100
	s_addc_u32 s27, s27, 0
	s_cmp_lt_i32 s65, s25
	s_mov_b32 s28, s65
	s_cbranch_scc1 .LBB0_4031
	s_andn2_b64 vcc, exec, s[14:15]
	s_cbranch_vccnz .LBB0_4034

; #define LAS __attribute__((address_space(3)))
; #define PSCALE(k, v) ((kargs()->li == 1 && (k) == lo) ? 0.f : (v))
; template <int K> __device__ __forceinline__ void sample_resid_units(LAS unsigned char* lds, const bf16* Aop, int lda, const bf16* Bt, int ldb, bf16* X, const float* gate, float scale,
;                                                    bf16* XB, float* SSQ, const float* gam, int tid, int vcu, int G) {
;     LAS float* P = (LAS float*)lds;
;     LAS float* R = P + 8 * 1024;
;     const int lane = tid & 63, w = __builtin_amdgcn_readfirstlane(tid >> 6), qq = lane & 15, q4 = lane >> 4;
;     for (int un = vcu; un < 256; un += G) {
;         const int rt = un >> 4, cs = un & 15, pn = cs >> 2, wc = cs & 3; const size_t row0 = (size_t)NPROMPT + 16 * rt;
;         constexpr int kper = K >> 3; const int kbeg = w * kper;
;         f32x4 acc[4];
; #pragma unroll
;         for (int ct = 0; ct < 4; ++ct) acc[ct] = (f32x4){0.f, 0.f, 0.f, 0.f};
;         const bf16* ap = Aop + (row0 + qq) * (size_t)lda + kbeg + 8 * q4;
;         const bf16* bp = Bt + (size_t)(256 * pn + 32 * wc + qq) * ldb + kbeg + 8 * q4;
; #pragma unroll 4
;         for (int k0 = 0; k0 < kper; k0 += 32) {
;             const bf16x8 af = *(const bf16x8*)(ap + k0);
; #pragma unroll
;             for (int ct = 0; ct < 4; ++ct) { const bf16x8 bf = *(const bf16x8*)(bp + (size_t)(128 * (ct >> 1) + 16 * (ct & 1)) * ldb + k0);
;                 acc[ct] = __builtin_amdgcn_mfma_f32_16x16x32_bf16(bf, af, acc[ct], 0, 0, 0); } }
; __global__ void __launch_bounds__(NWAVES * 64, 2) fwd(Args args_unused) {
;     ...
;         if (IN(pb + 7)) {
;             PH_PTRS PH_LAYER
;             sample_resid_units<DM>(lds, MG, DM, (const bf16*)(wl + WL_O), DM, X, modl + 5 * DM, PSCALE(pb + 7, 1.0f), XB, SSQ, GAM + (size_t)(l * 3 + 2) * NSEQ * DM, tid, vcu, G);
.LBB0_4132:
	s_mov_b32 s98, 0
	s_cmp_lt_i32 s84, 21
	s_cselect_b64 s[0:1], -1, 0
	s_cmp_gt_i32 s85, 20
	s_cselect_b64 s[4:5], -1, 0
	s_and_b64 s[0:1], s[0:1], s[4:5]
	s_andn2_b64 vcc, exec, s[0:1]
	s_cbranch_vccnz .LBB0_4238
	s_mov_b64 s[0:1], s[82:83]
	s_load_dwordx2 s[4:5], s[0:1], 0x148
	s_mov_b32 s24, 0
	s_mov_b32 s3, s2
	s_load_dword s33, s[82:83], 0x168
	s_waitcnt lgkmcnt(0)
	s_add_u32 s0, s4, 0xcf00000
	s_addc_u32 s1, s5, 0
	s_add_u32 s8, s4, 0x15000000
	s_addc_u32 s9, s5, 0
	s_add_u32 s44, s4, 0x19100000
	s_addc_u32 s45, s5, 0
	s_add_u32 s10, s4, 0xcc00000
	s_addc_u32 s11, s5, 0
	s_add_u32 s46, s4, 0x7500000
	s_addc_u32 s47, s5, 0
	s_add_u32 s12, s4, 0xb2b5000
	s_addc_u32 s13, s5, 0
	s_add_u32 s14, s4, 0xbcf0000
	v_readlane_b32 s20, v254, 3
	v_mov_b32_e32 v2, v0
	s_addc_u32 s15, s5, 0
	s_mov_b32 s17, 0
	s_cmpk_gt_i32 s20, 0xff
	v_readfirstlane_b32 s4, v2
	s_cbranch_scc1 .LBB0_4140
	s_ashr_i32 s16, s4, 6
	s_lshl_b32 s4, s16, 2
	s_add_i32 s18, s24, s4
	s_lshl_b32 s4, s16, 7
	s_ashr_i32 s5, s4, 31
	s_lshl_b64 s[4:5], s[4:5], 1
	s_add_u32 s6, s44, s4
	s_addc_u32 s7, s45, s5
	s_add_u32 s4, s46, s4
	v_and_b32_e32 v4, 15, v2
	v_and_b32_e32 v3, 63, v2
	v_mov_b32_e32 v7, 0
	v_and_b32_e32 v6, 48, v2
	s_addc_u32 s5, s47, s5
	v_ashrrev_i32_e32 v12, 7, v2
	v_lshlrev_b32_e32 v5, 1, v2
	v_lshl_add_u64 v[8:9], s[6:7], 0, v[6:7]
	v_lshl_add_u64 v[10:11], s[4:5], 0, v[6:7]
	s_lshl_b32 s6, s16, 12
	v_lshl_add_u32 v6, v3, 2, s24
	v_lshrrev_b32_e32 v1, 3, v2
	v_lshl_add_u32 v13, v4, 2, s24
	v_and_b32_e32 v14, 0xc0, v5
	v_ashrrev_i32_e32 v5, 1, v2
	v_lshlrev_b32_e32 v15, 4, v12
	v_lshlrev_b32_e32 v12, 10, v12
	v_and_b32_e32 v5, 0xffffff80, v5
	v_and_b32_e32 v15, 16, v15
	v_and_b32_e32 v1, 14, v1
	v_add3_u32 v12, v13, v14, v12
	v_add_u32_e32 v14, s6, v6
	v_mbcnt_lo_u32_b32 v6, -1, 0
	v_or3_b32 v1, v5, v15, v1
	v_lshlrev_b32_e32 v5, 5, v2
	v_mbcnt_hi_u32_b32 v16, -1, v6
	v_lshlrev_b32_e32 v20, 5, v4
	v_and_b32_e32 v15, 0x200, v5
	v_and_b32_e32 v6, 64, v16
	v_cmp_gt_u32_e32 vcc, 16, v3
	v_cmp_gt_i32_e64 s[4:5], 16, v2
	v_ashrrev_i32_e32 v3, 31, v2
	s_lshl_b32 s21, s20, 5
	s_lshl_b32 s22, s33, 5
	s_mov_b32 s23, 0x8000
	s_mov_b32 s25, 0x40000
	s_mov_b32 s26, 0x48000
	v_add_u32_e32 v15, v12, v15
	s_mov_b32 s27, 0x9000
	v_mov_b64_e32 v[12:13], s[12:13]
	v_xor_b32_e32 v17, 16, v16
	v_add_u32_e32 v18, 64, v6
	v_xor_b32_e32 v19, 32, v16
	v_add_u32_e32 v20, s18, v20
	s_branch .LBB0_4136

; #define PG8_STAGE(bufoff, gbase, voff) do { _Pragma("unroll") for (int _i = 0; _i < 2; ++_i) \
;         __builtin_amdgcn_global_load_lds((const unsigned*)((const char*)(gbase) + (voff)[_i]), (PG8_LAS unsigned*)(lds + (bufoff) + ldsw + _i * 8192), 16, 0, 0); } while (0)
; #define PG8_LDA(dst, b, h) do { _Pragma("unroll") for (int m = 0; m < 4; ++m) _Pragma("unroll") for (int k = 0; k < 2; ++k) dst[m][k] = *(const PG8_LAS bf16x8*)(lds + PG8_SA(b, h) + aoff + m * 2048 + k * 1024); } while (0)
; #define PG8_LDB(dst, b, h) do { _Pragma("unroll") for (int n = 0; n < 2; ++n) _Pragma("unroll") for (int k = 0; k < 2; ++k) dst[n][k] = *(const PG8_LAS bf16x8*)(lds + PG8_SB(b, h) + boff + n * 2048 + k * 1024); } while (0)
; #define PG8_MMA(ai, bj, At, Bt) do { __builtin_amdgcn_s_setprio(1); _Pragma("unroll") for (int m = 0; m < 4; ++m) _Pragma("unroll") for (int n = 0; n < 2; ++n) _Pragma("unroll") for (int k = 0; k < 2; ++k) \
;         acc[ai][bj][m][n] = __builtin_amdgcn_mfma_f32_16x16x32_bf16(Bt[n][k], At[m][k], acc[ai][bj][m][n], 0, 0, 0); __builtin_amdgcn_s_setprio(0); } while (0)
; #define PG8_WAIT_V(n) asm volatile("s_waitcnt vmcnt(" #n ")" ::: "memory")
; #define PG8_WAIT_L(n) do { asm volatile("s_waitcnt lgkmcnt(" #n ")" ::: "memory"); __builtin_amdgcn_s_waitcnt(0xC07F); } while (0)
; #define PG8_BAR __builtin_amdgcn_s_barrier()
; #define PG8_SCHED __builtin_amdgcn_sched_barrier(0)
; template <class Epi, class Sched, bool SEG3 = false>
; __device__ __forceinline__ void gemm_phase(PG8_LAS unsigned char* lds, const Gemm g, const Sched& S, const Epi& E) {
;     ...
;             PG8_WAIT_V(8); PG8_WAIT_L(0); PG8_BAR; if (cur.half != 0) { PG8_MMA(1, 0, At, B0); PG8_MMA(1, 1, At, B1); } PG8_BAR; PG8_SCHED;
;             PG8_LDB(B0, 1, 0); PG8_LDB(B1, 1, 1); PG8_SCHED; PG8_LDA(At, 1, 0); PG8_STAGE(PG8_SA(0, 1), a2 + hsA, voffA);
;             PG8_WAIT_V(8); PG8_WAIT_L(0); PG8_BAR; if (cur.half != 1) { PG8_MMA(0, 0, At, B0); PG8_MMA(0, 1, At, B1); } PG8_BAR; PG8_SCHED;
;             PG8_LDA(At, 1, 1); PG8_STAGE(PG8_SB(1, 0), b3, voffB); PG8_STAGE(PG8_SB(1, 1), b3 + hsB, voffB); PG8_STAGE(PG8_SA(1, 0), a3, voffA);
.Lfi_b_8:
	s_mov_b32 s98, 0
	s_waitcnt lgkmcnt(0)
	s_barrier
	s_setprio 1
	v_mfma_f32_16x16x32_bf16 v[78:81], v[34:37], v[162:165], v[78:81]
	v_mfma_f32_16x16x32_bf16 v[74:77], v[42:45], v[162:165], v[74:77]
	v_mfma_f32_16x16x32_bf16 v[62:65], v[34:37], v[186:189], v[62:65]
	v_mfma_f32_16x16x32_bf16 v[58:61], v[42:45], v[186:189], v[58:61]
	v_mfma_f32_16x16x32_bf16 v[30:33], v[34:37], v[194:197], v[30:33]
	v_mfma_f32_16x16x32_bf16 v[26:29], v[42:45], v[194:197], v[26:29]
	v_mfma_f32_16x16x32_bf16 v[14:17], v[34:37], v[202:205], v[14:17]
	v_mfma_f32_16x16x32_bf16 v[10:13], v[42:45], v[202:205], v[10:13]
	v_mfma_f32_16x16x32_bf16 v[78:81], v[38:41], v[166:169], v[78:81]
	v_mfma_f32_16x16x32_bf16 v[74:77], v[46:49], v[166:169], v[74:77]
	v_mfma_f32_16x16x32_bf16 v[62:65], v[38:41], v[190:193], v[62:65]
	v_mfma_f32_16x16x32_bf16 v[58:61], v[46:49], v[190:193], v[58:61]
	v_mfma_f32_16x16x32_bf16 v[30:33], v[38:41], v[198:201], v[30:33]
	v_mfma_f32_16x16x32_bf16 v[26:29], v[46:49], v[198:201], v[26:29]
	v_mfma_f32_16x16x32_bf16 v[14:17], v[38:41], v[214:217], v[14:17]
	v_mfma_f32_16x16x32_bf16 v[10:13], v[46:49], v[214:217], v[10:13]
	s_setprio 0
	s_setprio 1
	v_mfma_f32_16x16x32_bf16 v[22:25], v[114:117], v[194:197], v[22:25]
	v_mfma_f32_16x16x32_bf16 v[18:21], v[138:141], v[194:197], v[18:21]
	v_mfma_f32_16x16x32_bf16 v[6:9], v[114:117], v[202:205], v[6:9]
	v_mfma_f32_16x16x32_bf16 v[2:5], v[138:141], v[202:205], v[2:5]
	v_mfma_f32_16x16x32_bf16 v[34:37], v[114:117], v[162:165], v[70:73]
	v_mfma_f32_16x16x32_bf16 v[38:41], v[138:141], v[162:165], v[66:69]
	v_mfma_f32_16x16x32_bf16 v[42:45], v[114:117], v[186:189], v[54:57]
	v_mfma_f32_16x16x32_bf16 v[46:49], v[138:141], v[186:189], v[50:53]
	v_mfma_f32_16x16x32_bf16 v[22:25], v[126:129], v[198:201], v[22:25]
	v_mfma_f32_16x16x32_bf16 v[18:21], v[150:153], v[198:201], v[18:21]
	v_mfma_f32_16x16x32_bf16 v[6:9], v[126:129], v[214:217], v[6:9]
	v_mfma_f32_16x16x32_bf16 v[2:5], v[150:153], v[214:217], v[2:5]
	v_mfma_f32_16x16x32_bf16 v[34:37], v[126:129], v[166:169], v[34:37]
	v_mfma_f32_16x16x32_bf16 v[38:41], v[150:153], v[166:169], v[38:41]
	v_mfma_f32_16x16x32_bf16 v[42:45], v[126:129], v[190:193], v[42:45]
	v_mfma_f32_16x16x32_bf16 v[46:49], v[150:153], v[190:193], v[46:49]
	s_setprio 0
	s_barrier
	ds_read_b128 v[50:53], v210
	ds_read_b128 v[54:57], v210 offset:1024
	ds_read_b128 v[66:69], v210 offset:2048
	ds_read_b128 v[70:73], v210 offset:3072
	ds_read_b128 v[114:117], v211
	ds_read_b128 v[126:129], v211 offset:1024
	ds_read_b128 v[138:141], v211 offset:2048
	ds_read_b128 v[150:153], v211 offset:3072
	s_add_u32 s42, s42, 0x40000
	s_addc_u32 s43, s43, 0
	s_mov_b32 m0, s54
	v_lshl_add_u64 v[226:227], s[42:43], 0, v[170:171]
	ds_read_b128 v[162:165], v209 offset:32768
	ds_read_b128 v[166:169], v209 offset:33792
	ds_read_b128 v[186:189], v209 offset:34816
	ds_read_b128 v[190:193], v209 offset:35840
	ds_read_b128 v[194:197], v209 offset:36864
	ds_read_b128 v[198:201], v209 offset:37888
	ds_read_b128 v[202:205], v209 offset:38912
	ds_read_b128 v[214:217], v209 offset:39936
	global_load_lds_dwordx4 v[226:227], off
	v_lshl_add_u64 v[226:227], s[42:43], 0, v[174:175]
	s_mov_b32 m0, s55
	s_nop 0
	global_load_lds_dwordx4 v[226:227], off
	s_waitcnt vmcnt(8)
	s_waitcnt lgkmcnt(0)
	s_waitcnt lgkmcnt(0)
	s_barrier
	s_setprio 1
	v_mfma_f32_16x16x32_bf16 v[158:161], v[50:53], v[162:165], v[158:161]
	v_mfma_f32_16x16x32_bf16 v[154:157], v[66:69], v[162:165], v[154:157]
	v_mfma_f32_16x16x32_bf16 v[134:137], v[50:53], v[186:189], v[134:137]
	v_mfma_f32_16x16x32_bf16 v[130:133], v[66:69], v[186:189], v[130:133]
	v_mfma_f32_16x16x32_bf16 v[110:113], v[50:53], v[194:197], v[110:113]
	v_mfma_f32_16x16x32_bf16 v[106:109], v[66:69], v[194:197], v[106:109]
	v_mfma_f32_16x16x32_bf16 v[94:97], v[50:53], v[202:205], v[94:97]
	v_mfma_f32_16x16x32_bf16 v[90:93], v[66:69], v[202:205], v[90:93]
	v_mfma_f32_16x16x32_bf16 v[158:161], v[54:57], v[166:169], v[158:161]
	v_mfma_f32_16x16x32_bf16 v[154:157], v[70:73], v[166:169], v[154:157]
	v_mfma_f32_16x16x32_bf16 v[134:137], v[54:57], v[190:193], v[134:137]
	v_mfma_f32_16x16x32_bf16 v[130:133], v[70:73], v[190:193], v[130:133]
	v_mfma_f32_16x16x32_bf16 v[110:113], v[54:57], v[198:201], v[110:113]
	v_mfma_f32_16x16x32_bf16 v[106:109], v[70:73], v[198:201], v[106:109]
	v_mfma_f32_16x16x32_bf16 v[94:97], v[54:57], v[214:217], v[94:97]
	v_mfma_f32_16x16x32_bf16 v[90:93], v[70:73], v[214:217], v[90:93]
	s_setprio 0
	s_setprio 1
	v_mfma_f32_16x16x32_bf16 v[146:149], v[114:117], v[162:165], v[146:149]
	v_mfma_f32_16x16x32_bf16 v[142:145], v[138:141], v[162:165], v[142:145]
	v_mfma_f32_16x16x32_bf16 v[122:125], v[114:117], v[186:189], v[122:125]
	v_mfma_f32_16x16x32_bf16 v[118:121], v[138:141], v[186:189], v[118:121]
	v_mfma_f32_16x16x32_bf16 v[102:105], v[114:117], v[194:197], v[102:105]
	v_mfma_f32_16x16x32_bf16 v[98:101], v[138:141], v[194:197], v[98:101]
	v_mfma_f32_16x16x32_bf16 v[86:89], v[114:117], v[202:205], v[86:89]
	v_mfma_f32_16x16x32_bf16 v[82:85], v[138:141], v[202:205], v[82:85]
	v_mfma_f32_16x16x32_bf16 v[146:149], v[126:129], v[166:169], v[146:149]
	v_mfma_f32_16x16x32_bf16 v[142:145], v[150:153], v[166:169], v[142:145]
	v_mfma_f32_16x16x32_bf16 v[122:125], v[126:129], v[190:193], v[122:125]
	v_mfma_f32_16x16x32_bf16 v[118:121], v[150:153], v[190:193], v[118:121]
	v_mfma_f32_16x16x32_bf16 v[102:105], v[126:129], v[198:201], v[102:105]
	v_mfma_f32_16x16x32_bf16 v[98:101], v[150:153], v[198:201], v[98:101]
	v_mfma_f32_16x16x32_bf16 v[86:89], v[126:129], v[214:217], v[86:89]
	v_mfma_f32_16x16x32_bf16 v[82:85], v[150:153], v[214:217], v[82:85]
	s_setprio 0
	s_barrier
; #define PG8_STAGE(bufoff, gbase, voff) do { _Pragma("unroll") for (int _i = 0; _i < 2; ++_i) \
;         __builtin_amdgcn_global_load_lds((const unsigned*)((const char*)(gbase) + (voff)[_i]), (PG8_LAS unsigned*)(lds + (bufoff) + ldsw + _i * 8192), 16, 0, 0); } while (0)
; #define PG8_LDA(dst, b, h) do { _Pragma("unroll") for (int m = 0; m < 4; ++m) _Pragma("unroll") for (int k = 0; k < 2; ++k) dst[m][k] = *(const PG8_LAS bf16x8*)(lds + PG8_SA(b, h) + aoff + m * 2048 + k * 1024); } while (0)
; #define PG8_MMA(ai, bj, At, Bt) do { __builtin_amdgcn_s_setprio(1); _Pragma("unroll") for (int m = 0; m < 4; ++m) _Pragma("unroll") for (int n = 0; n < 2; ++n) _Pragma("unroll") for (int k = 0; k < 2; ++k) \
;         acc[ai][bj][m][n] = __builtin_amdgcn_mfma_f32_16x16x32_bf16(Bt[n][k], At[m][k], acc[ai][bj][m][n], 0, 0, 0); __builtin_amdgcn_s_setprio(0); } while (0)
; #define PG8_WAIT_V(n) asm volatile("s_waitcnt vmcnt(" #n ")" ::: "memory")
; #define PG8_WAIT_L(n) do { asm volatile("s_waitcnt lgkmcnt(" #n ")" ::: "memory"); __builtin_amdgcn_s_waitcnt(0xC07F); } while (0)
; #define PG8_BAR __builtin_amdgcn_s_barrier()
; #define PG8_SCHED __builtin_amdgcn_sched_barrier(0)
; template <class Epi, class Sched, bool SEG3 = false>
; __device__ __forceinline__ void gemm_phase(PG8_LAS unsigned char* lds, const Gemm g, const Sched& S, const Epi& E) {
;     ...
;             PG8_LDA(At, 1, 1); PG8_STAGE(PG8_SB(1, 0), b3, voffB); PG8_STAGE(PG8_SB(1, 1), b3 + hsB, voffB); PG8_STAGE(PG8_SA(1, 0), a3, voffA);
;             PG8_WAIT_V(8); PG8_WAIT_L(0); PG8_BAR; if (cur.half != 0) { PG8_MMA(1, 0, At, B0); PG8_MMA(1, 1, At, B1); } PG8_BAR; PG8_SCHED;
;         }
	s_mov_b32 m0, s58
	v_lshl_add_u64 v[218:219], v[218:219], 0, s[18:19]
	s_add_u32 s40, s40, 0x40080
	ds_read_b128 v[162:165], v209 offset:49152
	ds_read_b128 v[166:169], v209 offset:50176
	ds_read_b128 v[186:189], v209 offset:51200
	ds_read_b128 v[190:193], v209 offset:52224
	ds_read_b128 v[194:197], v209 offset:53248
	ds_read_b128 v[198:201], v209 offset:54272
	ds_read_b128 v[202:205], v209 offset:55296
	ds_read_b128 v[214:217], v209 offset:56320
	global_load_lds_dwordx4 v[218:219], off
	v_lshl_add_u64 v[218:219], v[220:221], 0, s[18:19]
	s_mov_b32 m0, s59
	s_addc_u32 s41, s41, 0
	global_load_lds_dwordx4 v[218:219], off
	v_lshl_add_u64 v[218:219], s[40:41], 0, v[172:173]
	s_mov_b32 m0, s62
	s_nop 0
	global_load_lds_dwordx4 v[218:219], off
	v_lshl_add_u64 v[218:219], s[40:41], 0, v[176:177]
	s_mov_b32 m0, s63
	s_nop 0
	global_load_lds_dwordx4 v[218:219], off
	v_lshl_add_u64 v[218:219], v[222:223], 0, s[18:19]
	s_mov_b32 m0, s60
	s_nop 0
	global_load_lds_dwordx4 v[218:219], off
	v_lshl_add_u64 v[218:219], v[224:225], 0, s[18:19]
	s_mov_b32 m0, s61
	s_nop 0
	global_load_lds_dwordx4 v[218:219], off
	s_waitcnt vmcnt(8)
	s_waitcnt lgkmcnt(0)
	s_waitcnt lgkmcnt(0)
	s_barrier
	s_setprio 1
	v_mfma_f32_16x16x32_bf16 v[78:81], v[50:53], v[162:165], v[78:81]
	v_mfma_f32_16x16x32_bf16 v[74:77], v[66:69], v[162:165], v[74:77]
	v_mfma_f32_16x16x32_bf16 v[62:65], v[50:53], v[186:189], v[62:65]
	v_mfma_f32_16x16x32_bf16 v[58:61], v[66:69], v[186:189], v[58:61]
	v_mfma_f32_16x16x32_bf16 v[30:33], v[50:53], v[194:197], v[30:33]
	v_mfma_f32_16x16x32_bf16 v[26:29], v[66:69], v[194:197], v[26:29]
	v_mfma_f32_16x16x32_bf16 v[14:17], v[50:53], v[202:205], v[14:17]
	v_mfma_f32_16x16x32_bf16 v[10:13], v[66:69], v[202:205], v[10:13]
	v_mfma_f32_16x16x32_bf16 v[78:81], v[54:57], v[166:169], v[78:81]
	v_mfma_f32_16x16x32_bf16 v[74:77], v[70:73], v[166:169], v[74:77]
	v_mfma_f32_16x16x32_bf16 v[62:65], v[54:57], v[190:193], v[62:65]
	v_mfma_f32_16x16x32_bf16 v[58:61], v[70:73], v[190:193], v[58:61]
	v_mfma_f32_16x16x32_bf16 v[30:33], v[54:57], v[198:201], v[30:33]
	v_mfma_f32_16x16x32_bf16 v[26:29], v[70:73], v[198:201], v[26:29]
	v_mfma_f32_16x16x32_bf16 v[14:17], v[54:57], v[214:217], v[14:17]
	v_mfma_f32_16x16x32_bf16 v[10:13], v[70:73], v[214:217], v[10:13]
	s_setprio 0
	s_setprio 1
	v_mfma_f32_16x16x32_bf16 v[34:37], v[114:117], v[162:165], v[34:37]
	v_mfma_f32_16x16x32_bf16 v[70:73], v[126:129], v[166:169], v[34:37]
	v_mfma_f32_16x16x32_bf16 v[34:37], v[138:141], v[162:165], v[38:41]
	v_mfma_f32_16x16x32_bf16 v[66:69], v[150:153], v[166:169], v[34:37]
	v_mfma_f32_16x16x32_bf16 v[34:37], v[114:117], v[186:189], v[42:45]
	v_mfma_f32_16x16x32_bf16 v[54:57], v[126:129], v[190:193], v[34:37]
	v_mfma_f32_16x16x32_bf16 v[34:37], v[138:141], v[186:189], v[46:49]
	v_mfma_f32_16x16x32_bf16 v[22:25], v[114:117], v[194:197], v[22:25]
	v_mfma_f32_16x16x32_bf16 v[18:21], v[138:141], v[194:197], v[18:21]
	v_mfma_f32_16x16x32_bf16 v[6:9], v[114:117], v[202:205], v[6:9]
	v_mfma_f32_16x16x32_bf16 v[2:5], v[138:141], v[202:205], v[2:5]
	v_mfma_f32_16x16x32_bf16 v[50:53], v[150:153], v[190:193], v[34:37]
	v_mfma_f32_16x16x32_bf16 v[22:25], v[126:129], v[198:201], v[22:25]
	v_mfma_f32_16x16x32_bf16 v[18:21], v[150:153], v[198:201], v[18:21]
	v_mfma_f32_16x16x32_bf16 v[6:9], v[126:129], v[214:217], v[6:9]
	v_mfma_f32_16x16x32_bf16 v[2:5], v[150:153], v[214:217], v[2:5]
	s_setprio 0
	s_barrier
	s_add_u32 s38, s38, 0x100
	s_addc_u32 s39, s39, 0
	s_add_u32 s68, s68, 0x100
	s_addc_u32 s69, s69, 0
	s_cmp_lt_i32 s70, s57
	s_mov_b32 s40, s70
	s_cbranch_scc1 .LBB0_4157
	s_andn2_b64 vcc, exec, s[22:23]
	s_cbranch_vccnz .LBB0_4160

;     __host__ __device__ bool next(int i, Unit& u) const { const int q = i / 3; if (!b.next(q, u)) return false; u.seg = i - 3 * q; return true; }
;     __host__ __device__ bool next(int i, Unit& u) const { const long L = (long)i * G + c; if (L >= nN) return false; u.pm = NPROMPT / BM; u.pn = (int)L; u.half = -1; u.seg = 0; return true; }
;     __host__ __device__ void init(int N_, int G_, int c_) { nN = N_ / BM; mn.init(NPROMPT, N_, G_, c_); G = G_; c = c_; }
;     __host__ __device__ bool next(int i, Unit& u) const {
;         const long L = (long)i * G + c;
;         if (L < mn.nwg) return mn.next(i, u);
;         const int j = (int)(L - mn.nwg); if (j >= 2 * nN) return false;
;         u.pm = NPROMPT / BM; u.pn = j % nN; u.half = j / nN; u.seg = 0; return true;
;     }
; __global__ void __launch_bounds__(NWAVES * 64, 2) fwd(Args args_unused) {
;     ...
;         if (IN(pb + 8)) {
;             PH_PTRS PH_LAYER
;             pg8::Gemm g{XB, (const bf16*)(wl + WL_F2I), M, 2 * DFF, DM, DM, DM, 0}; pg8::HalfOrder S; S.init(2 * DFF, G, bx);
;             pg8::EpiSwiGLU E{Gb, SSQ, (const float*)(ws + WS_SHW3) + (size_t)l * NSEQ * 2 * DFF};
;             pg8::gemm_phase<pg8::EpiSwiGLU, pg8::HalfOrder>(lds, g, S, E);
.LBB0_4238:
	s_mov_b32 s98, 0
	s_cmp_lt_i32 s84, 22
	s_cselect_b64 s[0:1], -1, 0
	s_cmp_gt_i32 s85, 21
	s_cselect_b64 s[4:5], -1, 0
	s_and_b64 s[0:1], s[0:1], s[4:5]
	s_andn2_b64 vcc, exec, s[0:1]
	s_cbranch_vccnz .LBB0_4352
	s_mov_b64 s[0:1], s[82:83]
	s_mov_b32 s20, 0
	s_load_dword s3, s[82:83], 0x168
	v_readlane_b32 s4, v254, 3
	s_mov_b32 s33, s2
	v_mov_b32_e32 v1, v0
	v_mov_b32_e32 v10, v0
	s_waitcnt lgkmcnt(0)
	s_movk_i32 s14, 0x400
	v_readfirstlane_b32 s16, v10
	s_cmpk_lt_i32 s33, 0xb00
	s_cbranch_scc1 .LBB0_4245
	s_add_i32 s8, s33, 0xfffff500
	s_mov_b64 s[6:7], 0
	s_cmp_gt_u32 s8, 43
	s_mov_b64 s[4:5], 0
	s_cbranch_scc1 .LBB0_4242
	s_add_i32 s4, s33, 0xfffff4ea
	s_cmp_lt_u32 s8, 22
	s_cselect_b32 s28, s8, s4
	s_cmp_gt_u32 s8, 21
	s_cselect_b64 s[4:5], -1, 0
	v_cndmask_b32_e64 v1, 0, 1, s[4:5]
	s_movk_i32 s30, 0x80
	s_mov_b64 s[4:5], -1
	v_readfirstlane_b32 s74, v1

; #define LAS __attribute__((address_space(3)))
; #define PSCALE(k, v) ((kargs()->li == 1 && (k) == lo) ? 0.f : (v))
; template <int K> __device__ __forceinline__ void sample_resid_units(LAS unsigned char* lds, const bf16* Aop, int lda, const bf16* Bt, int ldb, bf16* X, const float* gate, float scale,
;                                                    bf16* XB, float* SSQ, const float* gam, int tid, int vcu, int G) {
;     LAS float* P = (LAS float*)lds;
;     LAS float* R = P + 8 * 1024;
;     const int lane = tid & 63, w = __builtin_amdgcn_readfirstlane(tid >> 6), qq = lane & 15, q4 = lane >> 4;
;     for (int un = vcu; un < 256; un += G) {
;         const int rt = un >> 4, cs = un & 15, pn = cs >> 2, wc = cs & 3; const size_t row0 = (size_t)NPROMPT + 16 * rt;
;         constexpr int kper = K >> 3; const int kbeg = w * kper;
;         f32x4 acc[4];
; #pragma unroll
;         for (int ct = 0; ct < 4; ++ct) acc[ct] = (f32x4){0.f, 0.f, 0.f, 0.f};
;         const bf16* ap = Aop + (row0 + qq) * (size_t)lda + kbeg + 8 * q4;
;         const bf16* bp = Bt + (size_t)(256 * pn + 32 * wc + qq) * ldb + kbeg + 8 * q4;
; __global__ void __launch_bounds__(NWAVES * 64, 2) fwd(Args args_unused) {
;     ...
;         if (IN(pb + 9)) {
;             PH_PTRS PH_LAYER
;             sample_resid_units<DFF>(lds, Gb, DFF, (const bf16*)(wl + WL_F2O), DFF, X, modl + 8 * DM, PSCALE(pb + 9, 0.5f), XB, SSQ, GAM + (size_t)((l < 1 ? l + 1 : l) * 3 + 0) * NSEQ * DM, tid, vcu, G);
.LBB0_4352:
	s_mov_b32 s98, 0
	s_cmp_lt_i32 s84, 23
	s_cselect_b64 s[0:1], -1, 0
	s_cmp_gt_i32 s85, 22
	s_cselect_b64 s[4:5], -1, 0
	s_and_b64 s[0:1], s[0:1], s[4:5]
	s_andn2_b64 vcc, exec, s[0:1]
	s_cbranch_vccnz .LBB0_4462
	s_mov_b64 s[0:1], s[82:83]
	s_load_dwordx2 s[4:5], s[0:1], 0x148
	s_mov_b32 s26, 0
	s_mov_b32 s3, s2
	s_load_dword s33, s[82:83], 0x168
	s_waitcnt lgkmcnt(0)
	s_add_u32 s0, s4, 0xcf00000
	s_addc_u32 s1, s5, 0
	s_add_u32 s10, s4, 0x15000000
	s_addc_u32 s11, s5, 0
	s_add_u32 s12, s4, 0xcc00000
	s_addc_u32 s13, s5, 0
	s_add_u32 s38, s4, 0x1d200000
	s_addc_u32 s39, s5, 0
	s_add_u32 s40, s4, 0x8200000
	s_addc_u32 s41, s5, 0
	s_add_u32 s14, s4, 0xb2b8000
	s_addc_u32 s15, s5, 0
	s_add_u32 s16, s4, 0xbc90000
	v_readlane_b32 s20, v254, 3
	v_mov_b32_e32 v2, v0
	s_addc_u32 s17, s5, 0
	s_mov_b32 s9, 0
	s_cmpk_gt_i32 s20, 0xff
	v_readfirstlane_b32 s4, v2
	s_cbranch_scc1 .LBB0_4360
	s_ashr_i32 s8, s4, 6
	s_lshl_b32 s4, s8, 2
	s_add_i32 s18, s26, s4
	s_mul_i32 s4, s8, 0x160
	s_ashr_i32 s5, s4, 31
	s_lshl_b64 s[4:5], s[4:5], 1
	s_add_u32 s6, s38, s4
	s_addc_u32 s7, s39, s5
	s_add_u32 s4, s40, s4
	v_and_b32_e32 v3, 63, v2
	v_mov_b32_e32 v7, 0
	v_and_b32_e32 v6, 48, v2
	s_addc_u32 s5, s41, s5
	v_ashrrev_i32_e32 v12, 7, v2
	v_lshlrev_b32_e32 v5, 1, v2
	v_lshl_add_u64 v[8:9], s[6:7], 0, v[6:7]
	v_lshl_add_u64 v[10:11], s[4:5], 0, v[6:7]
	s_lshl_b32 s6, s8, 12
	v_lshl_add_u32 v6, v3, 2, s26
	v_lshrrev_b32_e32 v1, 3, v2
	v_and_b32_e32 v14, 0xc0, v5
	v_ashrrev_i32_e32 v5, 1, v2
	v_lshlrev_b32_e32 v15, 4, v12
	v_and_b32_e32 v4, 15, v2
	v_and_b32_e32 v5, 0xffffff80, v5
	v_and_b32_e32 v15, 16, v15
	v_and_b32_e32 v1, 14, v1
	v_add_u32_e32 v17, s6, v6
	v_mbcnt_lo_u32_b32 v6, -1, 0
	v_lshl_add_u32 v13, v4, 2, s26
	v_or3_b32 v1, v5, v15, v1
	v_lshlrev_b32_e32 v5, 5, v2
	v_lshlrev_b32_e32 v12, 10, v12
	v_mbcnt_hi_u32_b32 v19, -1, v6
	v_lshlrev_b32_e32 v15, 5, v4
	v_and_b32_e32 v18, 0x200, v5
	v_add3_u32 v12, v13, v14, v12
	v_and_b32_e32 v6, 64, v19
	v_cmp_gt_u32_e32 vcc, 16, v3
	v_cmp_gt_i32_e64 s[4:5], 16, v2
	v_ashrrev_i32_e32 v3, 31, v2
	s_lshl_b32 s21, s20, 5
	s_lshl_b32 s22, s33, 5
	s_movk_i32 s23, 0x1600
	v_mov_b32_e32 v16, 0x1600
	s_mov_b32 s24, 0x16000
	s_mov_b32 s25, 0xb0000
	s_mov_b32 s27, 0xc6000
	v_add_u32_e32 v18, v12, v18
	s_mov_b32 s28, 0x9000
	v_mov_b64_e32 v[12:13], s[14:15]
	v_xor_b32_e32 v20, 16, v19
	v_add_u32_e32 v21, 64, v6
	v_xor_b32_e32 v22, 32, v19
	v_add_u32_e32 v23, s18, v15
	s_branch .LBB0_4356
